# gdn_pre inversion regenerated with packed f32 FMAs (same ops/order) and the second half's inverter moved to wave 6 so the two serial inversions sit on different SIMDs
# speedup vs baseline: 1.0174x; 1.0044x over previous
.LBB0_226:
	v_readlane_b32 s8, v242, 9
	s_nop 0
	s_cmp_eq_u32 s8, 0
	s_cbranch_scc1 .LBB0_307
	s_cmp_eq_u32 s8, 6
	s_cbranch_scc1 .LBB0_307

.LBB0_307:
	v_mov_b32_e32 v33, s19
	v_lshl_add_u32 v84, v152, 1, s19
	ds_read_b128 v[74:77], v33 offset:17664
	ds_read_b128 v[78:81], v33 offset:17920
	ds_read_b128 v[86:89], v33 offset:18176
	ds_read_b128 v[90:93], v33 offset:18432
	ds_read_b128 v[154:157], v33 offset:18688
	ds_read_b128 v[180:183], v33 offset:18704
	ds_read_b128 v[184:187], v33 offset:18944
	ds_read_b128 v[188:191], v33 offset:18960
	ds_read_b128 v[198:201], v33 offset:19200
	ds_read_b128 v[202:205], v33 offset:19216
	ds_read_b128 v[206:209], v33 offset:19456
	ds_read_b128 v[210:213], v33 offset:19472
	v_mov_b64_e32 v[98:99], 0
	v_mov_b64_e32 v[100:101], 0
	v_mov_b64_e32 v[102:103], 0
	v_mov_b64_e32 v[104:105], 0
	v_mov_b64_e32 v[106:107], 0
	v_mov_b64_e32 v[108:109], 0
	v_mov_b64_e32 v[110:111], 0
	v_mov_b64_e32 v[112:113], 0
	v_mov_b64_e32 v[114:115], 0
	v_mov_b64_e32 v[116:117], 0
	v_mov_b64_e32 v[118:119], 0
	v_mov_b64_e32 v[120:121], 0
	v_mov_b64_e32 v[122:123], 0
	v_mov_b64_e32 v[124:125], 0
	v_mov_b64_e32 v[126:127], 0
	v_mov_b64_e32 v[128:129], 0
	v_mov_b64_e32 v[130:131], 0
	v_mov_b64_e32 v[132:133], 0
	v_mov_b64_e32 v[134:135], 0
	v_mov_b64_e32 v[136:137], 0
	v_mov_b64_e32 v[138:139], 0
	v_mov_b64_e32 v[140:141], 0
	v_mov_b64_e32 v[142:143], 0
	v_mov_b64_e32 v[162:163], 0
	v_mov_b64_e32 v[164:165], 0
	v_mov_b64_e32 v[166:167], 0
	v_mov_b64_e32 v[168:169], 0
	v_mov_b64_e32 v[170:171], 0
	v_mov_b64_e32 v[172:173], 0
	v_mov_b64_e32 v[174:175], 0
	v_mov_b64_e32 v[176:177], 0
	v_mov_b64_e32 v[178:179], 0
	v_cmp_eq_u32_e32 vcc, 0, v152
	s_nop 1
	v_cndmask_b32_e64 v98, 0, 1.0, vcc
	v_cmp_eq_u32_e32 vcc, 1, v152
	v_cvt_pk_bf16_f32 v25, v98, v98
	ds_write_b16 v84, v25
	v_cndmask_b32_e64 v22, 0, 1.0, vcc
	v_mov_b32_e32 v23, 0
	s_waitcnt lgkmcnt(12)
	v_pk_fma_f32 v[22:23], v[74:75], v[98:99], v[22:23] neg_lo:[1,0,0] neg_hi:[1,0,0]
	v_pk_fma_f32 v[30:31], v[76:77], v[100:101], 0 neg_lo:[1,0,0] neg_hi:[1,0,0]
	v_cmp_eq_u32_e32 vcc, 2, v152
	v_add_f32_e32 v82, v22, v23
	v_add_f32_e32 v83, v30, v31
	v_add_f32_e32 v99, v82, v83
	v_cvt_pk_bf16_f32 v25, v99, v99
	ds_write_b16 v84, v25 offset:144
	v_cndmask_b32_e64 v22, 0, 1.0, vcc
	v_mov_b32_e32 v23, 0
	s_waitcnt lgkmcnt(12)
	v_pk_fma_f32 v[22:23], v[78:79], v[98:99], v[22:23] neg_lo:[1,0,0] neg_hi:[1,0,0]
	v_pk_fma_f32 v[30:31], v[80:81], v[100:101], 0 neg_lo:[1,0,0] neg_hi:[1,0,0]
	v_cmp_eq_u32_e32 vcc, 3, v152
	v_add_f32_e32 v82, v22, v23
	v_add_f32_e32 v83, v30, v31
	v_add_f32_e32 v100, v82, v83
	v_cvt_pk_bf16_f32 v25, v100, v100
	ds_write_b16 v84, v25 offset:288
	v_cndmask_b32_e64 v22, 0, 1.0, vcc
	v_mov_b32_e32 v23, 0
	s_waitcnt lgkmcnt(12)
	v_pk_fma_f32 v[22:23], v[86:87], v[98:99], v[22:23] neg_lo:[1,0,0] neg_hi:[1,0,0]
	v_pk_fma_f32 v[30:31], v[88:89], v[100:101], 0 neg_lo:[1,0,0] neg_hi:[1,0,0]
	v_cmp_eq_u32_e32 vcc, 4, v152
	v_add_f32_e32 v82, v22, v23
	v_add_f32_e32 v83, v30, v31
	v_add_f32_e32 v101, v82, v83
	v_cvt_pk_bf16_f32 v25, v101, v101
	ds_write_b16 v84, v25 offset:432
	v_cndmask_b32_e64 v22, 0, 1.0, vcc
	v_mov_b32_e32 v23, 0
	s_waitcnt lgkmcnt(12)
	v_pk_fma_f32 v[22:23], v[90:91], v[98:99], v[22:23] neg_lo:[1,0,0] neg_hi:[1,0,0]
	v_pk_fma_f32 v[30:31], v[92:93], v[100:101], 0 neg_lo:[1,0,0] neg_hi:[1,0,0]
	v_cmp_eq_u32_e32 vcc, 5, v152
	v_add_f32_e32 v82, v22, v23
	v_add_f32_e32 v83, v30, v31
	v_add_f32_e32 v102, v82, v83
	v_cvt_pk_bf16_f32 v25, v102, v102
	ds_write_b16 v84, v25 offset:576
	v_cndmask_b32_e64 v22, 0, 1.0, vcc
	v_mov_b32_e32 v23, 0
	s_waitcnt lgkmcnt(12)
	v_pk_fma_f32 v[22:23], v[154:155], v[98:99], v[22:23] neg_lo:[1,0,0] neg_hi:[1,0,0]
	v_pk_fma_f32 v[30:31], v[156:157], v[100:101], 0 neg_lo:[1,0,0] neg_hi:[1,0,0]
	s_waitcnt lgkmcnt(11)
	v_pk_fma_f32 v[22:23], v[180:181], v[102:103], v[22:23] neg_lo:[1,0,0] neg_hi:[1,0,0]
	v_pk_fma_f32 v[30:31], v[182:183], v[104:105], v[30:31] neg_lo:[1,0,0] neg_hi:[1,0,0]
	v_cmp_eq_u32_e32 vcc, 6, v152
	v_add_f32_e32 v82, v22, v23
	v_add_f32_e32 v83, v30, v31
	v_add_f32_e32 v103, v82, v83
	v_cvt_pk_bf16_f32 v25, v103, v103
	ds_write_b16 v84, v25 offset:720
	v_cndmask_b32_e64 v22, 0, 1.0, vcc
	v_mov_b32_e32 v23, 0
	s_waitcnt lgkmcnt(11)
	v_pk_fma_f32 v[22:23], v[184:185], v[98:99], v[22:23] neg_lo:[1,0,0] neg_hi:[1,0,0]
	v_pk_fma_f32 v[30:31], v[186:187], v[100:101], 0 neg_lo:[1,0,0] neg_hi:[1,0,0]
	s_waitcnt lgkmcnt(10)
	v_pk_fma_f32 v[22:23], v[188:189], v[102:103], v[22:23] neg_lo:[1,0,0] neg_hi:[1,0,0]
	v_pk_fma_f32 v[30:31], v[190:191], v[104:105], v[30:31] neg_lo:[1,0,0] neg_hi:[1,0,0]
	v_cmp_eq_u32_e32 vcc, 7, v152
	v_add_f32_e32 v82, v22, v23
	v_add_f32_e32 v83, v30, v31
	v_add_f32_e32 v104, v82, v83
	v_cvt_pk_bf16_f32 v25, v104, v104
	ds_write_b16 v84, v25 offset:864
	v_cndmask_b32_e64 v22, 0, 1.0, vcc
	v_mov_b32_e32 v23, 0
	s_waitcnt lgkmcnt(10)
	v_pk_fma_f32 v[22:23], v[198:199], v[98:99], v[22:23] neg_lo:[1,0,0] neg_hi:[1,0,0]
	v_pk_fma_f32 v[30:31], v[200:201], v[100:101], 0 neg_lo:[1,0,0] neg_hi:[1,0,0]
	s_waitcnt lgkmcnt(9)
	v_pk_fma_f32 v[22:23], v[202:203], v[102:103], v[22:23] neg_lo:[1,0,0] neg_hi:[1,0,0]
	v_pk_fma_f32 v[30:31], v[204:205], v[104:105], v[30:31] neg_lo:[1,0,0] neg_hi:[1,0,0]
	v_cmp_eq_u32_e32 vcc, 8, v152
	v_add_f32_e32 v82, v22, v23
	v_add_f32_e32 v83, v30, v31
	v_add_f32_e32 v105, v82, v83
	v_cvt_pk_bf16_f32 v25, v105, v105
	ds_write_b16 v84, v25 offset:1008
	v_cndmask_b32_e64 v22, 0, 1.0, vcc
	v_mov_b32_e32 v23, 0
	ds_read_b128 v[0:3], v33 offset:19712
	ds_read_b128 v[4:7], v33 offset:19728
	ds_read_b128 v[8:11], v33 offset:19744
	s_waitcnt lgkmcnt(12)
	v_pk_fma_f32 v[22:23], v[206:207], v[98:99], v[22:23] neg_lo:[1,0,0] neg_hi:[1,0,0]
	v_pk_fma_f32 v[30:31], v[208:209], v[100:101], 0 neg_lo:[1,0,0] neg_hi:[1,0,0]
	s_waitcnt lgkmcnt(11)
	v_pk_fma_f32 v[22:23], v[210:211], v[102:103], v[22:23] neg_lo:[1,0,0] neg_hi:[1,0,0]
	v_pk_fma_f32 v[30:31], v[212:213], v[104:105], v[30:31] neg_lo:[1,0,0] neg_hi:[1,0,0]
	v_cmp_eq_u32_e32 vcc, 9, v152
	v_add_f32_e32 v82, v22, v23
	v_add_f32_e32 v83, v30, v31
	v_add_f32_e32 v106, v82, v83
	v_cvt_pk_bf16_f32 v25, v106, v106
	ds_write_b16 v84, v25 offset:1152
	v_cndmask_b32_e64 v22, 0, 1.0, vcc
	v_mov_b32_e32 v23, 0
	s_waitcnt lgkmcnt(3)
	v_pk_fma_f32 v[22:23], v[0:1], v[98:99], v[22:23] neg_lo:[1,0,0] neg_hi:[1,0,0]
	v_pk_fma_f32 v[30:31], v[2:3], v[100:101], 0 neg_lo:[1,0,0] neg_hi:[1,0,0]
	ds_read_b128 v[0:3], v33 offset:19968
	s_waitcnt lgkmcnt(3)
	v_pk_fma_f32 v[22:23], v[4:5], v[102:103], v[22:23] neg_lo:[1,0,0] neg_hi:[1,0,0]
	v_pk_fma_f32 v[30:31], v[6:7], v[104:105], v[30:31] neg_lo:[1,0,0] neg_hi:[1,0,0]
	ds_read_b128 v[4:7], v33 offset:19984
	s_waitcnt lgkmcnt(3)
	v_pk_fma_f32 v[22:23], v[8:9], v[106:107], v[22:23] neg_lo:[1,0,0] neg_hi:[1,0,0]
	v_pk_fma_f32 v[30:31], v[10:11], v[108:109], v[30:31] neg_lo:[1,0,0] neg_hi:[1,0,0]
	ds_read_b128 v[8:11], v33 offset:20000
	v_cmp_eq_u32_e32 vcc, 10, v152
	v_add_f32_e32 v82, v22, v23
	v_add_f32_e32 v83, v30, v31
	v_add_f32_e32 v107, v82, v83
	v_cvt_pk_bf16_f32 v25, v107, v107
	ds_write_b16 v84, v25 offset:1296
	v_cndmask_b32_e64 v22, 0, 1.0, vcc
	v_mov_b32_e32 v23, 0
	s_waitcnt lgkmcnt(3)
	v_pk_fma_f32 v[22:23], v[0:1], v[98:99], v[22:23] neg_lo:[1,0,0] neg_hi:[1,0,0]
	v_pk_fma_f32 v[30:31], v[2:3], v[100:101], 0 neg_lo:[1,0,0] neg_hi:[1,0,0]
	ds_read_b128 v[0:3], v33 offset:20224
	s_waitcnt lgkmcnt(3)
	v_pk_fma_f32 v[22:23], v[4:5], v[102:103], v[22:23] neg_lo:[1,0,0] neg_hi:[1,0,0]
	v_pk_fma_f32 v[30:31], v[6:7], v[104:105], v[30:31] neg_lo:[1,0,0] neg_hi:[1,0,0]
	ds_read_b128 v[4:7], v33 offset:20240
	s_waitcnt lgkmcnt(3)
	v_pk_fma_f32 v[22:23], v[8:9], v[106:107], v[22:23] neg_lo:[1,0,0] neg_hi:[1,0,0]
	v_pk_fma_f32 v[30:31], v[10:11], v[108:109], v[30:31] neg_lo:[1,0,0] neg_hi:[1,0,0]
	ds_read_b128 v[8:11], v33 offset:20256
	v_cmp_eq_u32_e32 vcc, 11, v152
	v_add_f32_e32 v82, v22, v23
	v_add_f32_e32 v83, v30, v31
	v_add_f32_e32 v108, v82, v83
	v_cvt_pk_bf16_f32 v25, v108, v108
	ds_write_b16 v84, v25 offset:1440
	v_cndmask_b32_e64 v22, 0, 1.0, vcc
	v_mov_b32_e32 v23, 0
	s_waitcnt lgkmcnt(3)
	v_pk_fma_f32 v[22:23], v[0:1], v[98:99], v[22:23] neg_lo:[1,0,0] neg_hi:[1,0,0]
	v_pk_fma_f32 v[30:31], v[2:3], v[100:101], 0 neg_lo:[1,0,0] neg_hi:[1,0,0]
	ds_read_b128 v[0:3], v33 offset:20480
	s_waitcnt lgkmcnt(3)
	v_pk_fma_f32 v[22:23], v[4:5], v[102:103], v[22:23] neg_lo:[1,0,0] neg_hi:[1,0,0]
	v_pk_fma_f32 v[30:31], v[6:7], v[104:105], v[30:31] neg_lo:[1,0,0] neg_hi:[1,0,0]
	ds_read_b128 v[4:7], v33 offset:20496
	s_waitcnt lgkmcnt(3)
	v_pk_fma_f32 v[22:23], v[8:9], v[106:107], v[22:23] neg_lo:[1,0,0] neg_hi:[1,0,0]
	v_pk_fma_f32 v[30:31], v[10:11], v[108:109], v[30:31] neg_lo:[1,0,0] neg_hi:[1,0,0]
	ds_read_b128 v[8:11], v33 offset:20512
	v_cmp_eq_u32_e32 vcc, 12, v152
	v_add_f32_e32 v82, v22, v23
	v_add_f32_e32 v83, v30, v31
	v_add_f32_e32 v109, v82, v83
	v_cvt_pk_bf16_f32 v25, v109, v109
	ds_write_b16 v84, v25 offset:1584
	v_cndmask_b32_e64 v22, 0, 1.0, vcc
	v_mov_b32_e32 v23, 0
	ds_read_b128 v[12:15], v33 offset:20784
	s_waitcnt lgkmcnt(4)
	v_pk_fma_f32 v[22:23], v[0:1], v[98:99], v[22:23] neg_lo:[1,0,0] neg_hi:[1,0,0]
	v_pk_fma_f32 v[30:31], v[2:3], v[100:101], 0 neg_lo:[1,0,0] neg_hi:[1,0,0]
	ds_read_b128 v[0:3], v33 offset:20736
	s_waitcnt lgkmcnt(4)
	v_pk_fma_f32 v[22:23], v[4:5], v[102:103], v[22:23] neg_lo:[1,0,0] neg_hi:[1,0,0]
	v_pk_fma_f32 v[30:31], v[6:7], v[104:105], v[30:31] neg_lo:[1,0,0] neg_hi:[1,0,0]
	ds_read_b128 v[4:7], v33 offset:20752
	s_waitcnt lgkmcnt(4)
	v_pk_fma_f32 v[22:23], v[8:9], v[106:107], v[22:23] neg_lo:[1,0,0] neg_hi:[1,0,0]
	v_pk_fma_f32 v[30:31], v[10:11], v[108:109], v[30:31] neg_lo:[1,0,0] neg_hi:[1,0,0]
	ds_read_b128 v[8:11], v33 offset:20768
	v_cmp_eq_u32_e32 vcc, 13, v152
	v_add_f32_e32 v82, v22, v23
	v_add_f32_e32 v83, v30, v31
	v_add_f32_e32 v110, v82, v83
	v_cvt_pk_bf16_f32 v25, v110, v110
	ds_write_b16 v84, v25 offset:1728
	v_cndmask_b32_e64 v22, 0, 1.0, vcc
	v_mov_b32_e32 v23, 0
	s_waitcnt lgkmcnt(3)
	v_pk_fma_f32 v[22:23], v[0:1], v[98:99], v[22:23] neg_lo:[1,0,0] neg_hi:[1,0,0]
	v_pk_fma_f32 v[30:31], v[2:3], v[100:101], 0 neg_lo:[1,0,0] neg_hi:[1,0,0]
	ds_read_b128 v[0:3], v33 offset:20992
	s_waitcnt lgkmcnt(3)
	v_pk_fma_f32 v[22:23], v[4:5], v[102:103], v[22:23] neg_lo:[1,0,0] neg_hi:[1,0,0]
	v_pk_fma_f32 v[30:31], v[6:7], v[104:105], v[30:31] neg_lo:[1,0,0] neg_hi:[1,0,0]
	ds_read_b128 v[4:7], v33 offset:21008
	s_waitcnt lgkmcnt(3)
	v_pk_fma_f32 v[22:23], v[8:9], v[106:107], v[22:23] neg_lo:[1,0,0] neg_hi:[1,0,0]
	v_pk_fma_f32 v[30:31], v[10:11], v[108:109], v[30:31] neg_lo:[1,0,0] neg_hi:[1,0,0]
	ds_read_b128 v[8:11], v33 offset:21024
	s_waitcnt lgkmcnt(7)
	v_pk_fma_f32 v[22:23], v[12:13], v[110:111], v[22:23] neg_lo:[1,0,0] neg_hi:[1,0,0]
	v_pk_fma_f32 v[30:31], v[14:15], v[112:113], v[30:31] neg_lo:[1,0,0] neg_hi:[1,0,0]
	ds_read_b128 v[12:15], v33 offset:21040
	v_cmp_eq_u32_e32 vcc, 14, v152
	v_add_f32_e32 v82, v22, v23
	v_add_f32_e32 v83, v30, v31
	v_add_f32_e32 v111, v82, v83
	v_cvt_pk_bf16_f32 v25, v111, v111
	ds_write_b16 v84, v25 offset:1872
	v_cndmask_b32_e64 v22, 0, 1.0, vcc
	v_mov_b32_e32 v23, 0
	s_waitcnt lgkmcnt(4)
	v_pk_fma_f32 v[22:23], v[0:1], v[98:99], v[22:23] neg_lo:[1,0,0] neg_hi:[1,0,0]
	v_pk_fma_f32 v[30:31], v[2:3], v[100:101], 0 neg_lo:[1,0,0] neg_hi:[1,0,0]
	ds_read_b128 v[0:3], v33 offset:21248
	s_waitcnt lgkmcnt(4)
	v_pk_fma_f32 v[22:23], v[4:5], v[102:103], v[22:23] neg_lo:[1,0,0] neg_hi:[1,0,0]
	v_pk_fma_f32 v[30:31], v[6:7], v[104:105], v[30:31] neg_lo:[1,0,0] neg_hi:[1,0,0]
	ds_read_b128 v[4:7], v33 offset:21264
	s_waitcnt lgkmcnt(4)
	v_pk_fma_f32 v[22:23], v[8:9], v[106:107], v[22:23] neg_lo:[1,0,0] neg_hi:[1,0,0]
	v_pk_fma_f32 v[30:31], v[10:11], v[108:109], v[30:31] neg_lo:[1,0,0] neg_hi:[1,0,0]
	ds_read_b128 v[8:11], v33 offset:21280
	s_waitcnt lgkmcnt(4)
	v_pk_fma_f32 v[22:23], v[12:13], v[110:111], v[22:23] neg_lo:[1,0,0] neg_hi:[1,0,0]
	v_pk_fma_f32 v[30:31], v[14:15], v[112:113], v[30:31] neg_lo:[1,0,0] neg_hi:[1,0,0]
	ds_read_b128 v[12:15], v33 offset:21296
	v_cmp_eq_u32_e32 vcc, 15, v152
	v_add_f32_e32 v82, v22, v23
	v_add_f32_e32 v83, v30, v31
	v_add_f32_e32 v112, v82, v83
	v_cvt_pk_bf16_f32 v25, v112, v112
	ds_write_b16 v84, v25 offset:2016
	v_cndmask_b32_e64 v22, 0, 1.0, vcc
	v_mov_b32_e32 v23, 0
	s_waitcnt lgkmcnt(4)
	v_pk_fma_f32 v[22:23], v[0:1], v[98:99], v[22:23] neg_lo:[1,0,0] neg_hi:[1,0,0]
	v_pk_fma_f32 v[30:31], v[2:3], v[100:101], 0 neg_lo:[1,0,0] neg_hi:[1,0,0]
	ds_read_b128 v[0:3], v33 offset:21504
	s_waitcnt lgkmcnt(4)
	v_pk_fma_f32 v[22:23], v[4:5], v[102:103], v[22:23] neg_lo:[1,0,0] neg_hi:[1,0,0]
	v_pk_fma_f32 v[30:31], v[6:7], v[104:105], v[30:31] neg_lo:[1,0,0] neg_hi:[1,0,0]
	ds_read_b128 v[4:7], v33 offset:21520
	s_waitcnt lgkmcnt(4)
	v_pk_fma_f32 v[22:23], v[8:9], v[106:107], v[22:23] neg_lo:[1,0,0] neg_hi:[1,0,0]
	v_pk_fma_f32 v[30:31], v[10:11], v[108:109], v[30:31] neg_lo:[1,0,0] neg_hi:[1,0,0]
	ds_read_b128 v[8:11], v33 offset:21536
	s_waitcnt lgkmcnt(4)
	v_pk_fma_f32 v[22:23], v[12:13], v[110:111], v[22:23] neg_lo:[1,0,0] neg_hi:[1,0,0]
	v_pk_fma_f32 v[30:31], v[14:15], v[112:113], v[30:31] neg_lo:[1,0,0] neg_hi:[1,0,0]
	ds_read_b128 v[12:15], v33 offset:21552
	v_cmp_eq_u32_e32 vcc, 16, v152
	v_add_f32_e32 v82, v22, v23
	v_add_f32_e32 v83, v30, v31
	v_add_f32_e32 v113, v82, v83
	v_cvt_pk_bf16_f32 v25, v113, v113
	ds_write_b16 v84, v25 offset:2160
	v_cndmask_b32_e64 v22, 0, 1.0, vcc
	v_mov_b32_e32 v23, 0
	ds_read_b128 v[16:19], v33 offset:21824
	s_waitcnt lgkmcnt(5)
	v_pk_fma_f32 v[22:23], v[0:1], v[98:99], v[22:23] neg_lo:[1,0,0] neg_hi:[1,0,0]
	v_pk_fma_f32 v[30:31], v[2:3], v[100:101], 0 neg_lo:[1,0,0] neg_hi:[1,0,0]
	ds_read_b128 v[0:3], v33 offset:21760
	s_waitcnt lgkmcnt(5)
	v_pk_fma_f32 v[22:23], v[4:5], v[102:103], v[22:23] neg_lo:[1,0,0] neg_hi:[1,0,0]
	v_pk_fma_f32 v[30:31], v[6:7], v[104:105], v[30:31] neg_lo:[1,0,0] neg_hi:[1,0,0]
	ds_read_b128 v[4:7], v33 offset:21776
	s_waitcnt lgkmcnt(5)
	v_pk_fma_f32 v[22:23], v[8:9], v[106:107], v[22:23] neg_lo:[1,0,0] neg_hi:[1,0,0]
	v_pk_fma_f32 v[30:31], v[10:11], v[108:109], v[30:31] neg_lo:[1,0,0] neg_hi:[1,0,0]
	ds_read_b128 v[8:11], v33 offset:21792
	s_waitcnt lgkmcnt(5)
	v_pk_fma_f32 v[22:23], v[12:13], v[110:111], v[22:23] neg_lo:[1,0,0] neg_hi:[1,0,0]
	v_pk_fma_f32 v[30:31], v[14:15], v[112:113], v[30:31] neg_lo:[1,0,0] neg_hi:[1,0,0]
	ds_read_b128 v[12:15], v33 offset:21808
	v_cmp_eq_u32_e32 vcc, 17, v152
	v_add_f32_e32 v82, v22, v23
	v_add_f32_e32 v83, v30, v31
	v_add_f32_e32 v114, v82, v83
	v_cvt_pk_bf16_f32 v25, v114, v114
	ds_write_b16 v84, v25 offset:2304
	v_cndmask_b32_e64 v22, 0, 1.0, vcc
	v_mov_b32_e32 v23, 0
	s_waitcnt lgkmcnt(4)
	v_pk_fma_f32 v[22:23], v[0:1], v[98:99], v[22:23] neg_lo:[1,0,0] neg_hi:[1,0,0]
	v_pk_fma_f32 v[30:31], v[2:3], v[100:101], 0 neg_lo:[1,0,0] neg_hi:[1,0,0]
	ds_read_b128 v[0:3], v33 offset:22016
	s_waitcnt lgkmcnt(4)
	v_pk_fma_f32 v[22:23], v[4:5], v[102:103], v[22:23] neg_lo:[1,0,0] neg_hi:[1,0,0]
	v_pk_fma_f32 v[30:31], v[6:7], v[104:105], v[30:31] neg_lo:[1,0,0] neg_hi:[1,0,0]
	ds_read_b128 v[4:7], v33 offset:22032
	s_waitcnt lgkmcnt(4)
	v_pk_fma_f32 v[22:23], v[8:9], v[106:107], v[22:23] neg_lo:[1,0,0] neg_hi:[1,0,0]
	v_pk_fma_f32 v[30:31], v[10:11], v[108:109], v[30:31] neg_lo:[1,0,0] neg_hi:[1,0,0]
	ds_read_b128 v[8:11], v33 offset:22048
	s_waitcnt lgkmcnt(4)
	v_pk_fma_f32 v[22:23], v[12:13], v[110:111], v[22:23] neg_lo:[1,0,0] neg_hi:[1,0,0]
	v_pk_fma_f32 v[30:31], v[14:15], v[112:113], v[30:31] neg_lo:[1,0,0] neg_hi:[1,0,0]
	ds_read_b128 v[12:15], v33 offset:22064
	s_waitcnt lgkmcnt(9)
	v_pk_fma_f32 v[22:23], v[16:17], v[114:115], v[22:23] neg_lo:[1,0,0] neg_hi:[1,0,0]
	v_pk_fma_f32 v[30:31], v[18:19], v[116:117], v[30:31] neg_lo:[1,0,0] neg_hi:[1,0,0]
	ds_read_b128 v[16:19], v33 offset:22080
	v_cmp_eq_u32_e32 vcc, 18, v152
	v_add_f32_e32 v82, v22, v23
	v_add_f32_e32 v83, v30, v31
	v_add_f32_e32 v115, v82, v83
	v_cvt_pk_bf16_f32 v25, v115, v115
	ds_write_b16 v84, v25 offset:2448
	v_cndmask_b32_e64 v22, 0, 1.0, vcc
	v_mov_b32_e32 v23, 0
	s_waitcnt lgkmcnt(5)
	v_pk_fma_f32 v[22:23], v[0:1], v[98:99], v[22:23] neg_lo:[1,0,0] neg_hi:[1,0,0]
	v_pk_fma_f32 v[30:31], v[2:3], v[100:101], 0 neg_lo:[1,0,0] neg_hi:[1,0,0]
	ds_read_b128 v[0:3], v33 offset:22272
	s_waitcnt lgkmcnt(5)
	v_pk_fma_f32 v[22:23], v[4:5], v[102:103], v[22:23] neg_lo:[1,0,0] neg_hi:[1,0,0]
	v_pk_fma_f32 v[30:31], v[6:7], v[104:105], v[30:31] neg_lo:[1,0,0] neg_hi:[1,0,0]
	ds_read_b128 v[4:7], v33 offset:22288
	s_waitcnt lgkmcnt(5)
	v_pk_fma_f32 v[22:23], v[8:9], v[106:107], v[22:23] neg_lo:[1,0,0] neg_hi:[1,0,0]
	v_pk_fma_f32 v[30:31], v[10:11], v[108:109], v[30:31] neg_lo:[1,0,0] neg_hi:[1,0,0]
	ds_read_b128 v[8:11], v33 offset:22304
	s_waitcnt lgkmcnt(5)
	v_pk_fma_f32 v[22:23], v[12:13], v[110:111], v[22:23] neg_lo:[1,0,0] neg_hi:[1,0,0]
	v_pk_fma_f32 v[30:31], v[14:15], v[112:113], v[30:31] neg_lo:[1,0,0] neg_hi:[1,0,0]
	ds_read_b128 v[12:15], v33 offset:22320
	s_waitcnt lgkmcnt(5)
	v_pk_fma_f32 v[22:23], v[16:17], v[114:115], v[22:23] neg_lo:[1,0,0] neg_hi:[1,0,0]
	v_pk_fma_f32 v[30:31], v[18:19], v[116:117], v[30:31] neg_lo:[1,0,0] neg_hi:[1,0,0]
	ds_read_b128 v[16:19], v33 offset:22336
	v_cmp_eq_u32_e32 vcc, 19, v152
	v_add_f32_e32 v82, v22, v23
	v_add_f32_e32 v83, v30, v31
	v_add_f32_e32 v116, v82, v83
	v_cvt_pk_bf16_f32 v25, v116, v116
	ds_write_b16 v84, v25 offset:2592
	v_cndmask_b32_e64 v22, 0, 1.0, vcc
	v_mov_b32_e32 v23, 0
	s_waitcnt lgkmcnt(5)
	v_pk_fma_f32 v[22:23], v[0:1], v[98:99], v[22:23] neg_lo:[1,0,0] neg_hi:[1,0,0]
	v_pk_fma_f32 v[30:31], v[2:3], v[100:101], 0 neg_lo:[1,0,0] neg_hi:[1,0,0]
	ds_read_b128 v[0:3], v33 offset:22528
	s_waitcnt lgkmcnt(5)
	v_pk_fma_f32 v[22:23], v[4:5], v[102:103], v[22:23] neg_lo:[1,0,0] neg_hi:[1,0,0]
	v_pk_fma_f32 v[30:31], v[6:7], v[104:105], v[30:31] neg_lo:[1,0,0] neg_hi:[1,0,0]
	ds_read_b128 v[4:7], v33 offset:22544
	s_waitcnt lgkmcnt(5)
	v_pk_fma_f32 v[22:23], v[8:9], v[106:107], v[22:23] neg_lo:[1,0,0] neg_hi:[1,0,0]
	v_pk_fma_f32 v[30:31], v[10:11], v[108:109], v[30:31] neg_lo:[1,0,0] neg_hi:[1,0,0]
	ds_read_b128 v[8:11], v33 offset:22560
	s_waitcnt lgkmcnt(5)
	v_pk_fma_f32 v[22:23], v[12:13], v[110:111], v[22:23] neg_lo:[1,0,0] neg_hi:[1,0,0]
	v_pk_fma_f32 v[30:31], v[14:15], v[112:113], v[30:31] neg_lo:[1,0,0] neg_hi:[1,0,0]
	ds_read_b128 v[12:15], v33 offset:22576
	s_waitcnt lgkmcnt(5)
	v_pk_fma_f32 v[22:23], v[16:17], v[114:115], v[22:23] neg_lo:[1,0,0] neg_hi:[1,0,0]
	v_pk_fma_f32 v[30:31], v[18:19], v[116:117], v[30:31] neg_lo:[1,0,0] neg_hi:[1,0,0]
	ds_read_b128 v[16:19], v33 offset:22592
	v_cmp_eq_u32_e32 vcc, 20, v152
	v_add_f32_e32 v82, v22, v23
	v_add_f32_e32 v83, v30, v31
	v_add_f32_e32 v117, v82, v83
	v_cvt_pk_bf16_f32 v25, v117, v117
	ds_write_b16 v84, v25 offset:2736
	v_cndmask_b32_e64 v22, 0, 1.0, vcc
	v_mov_b32_e32 v23, 0
	ds_read_b128 v[26:29], v33 offset:22864
	s_waitcnt lgkmcnt(6)
	v_pk_fma_f32 v[22:23], v[0:1], v[98:99], v[22:23] neg_lo:[1,0,0] neg_hi:[1,0,0]
	v_pk_fma_f32 v[30:31], v[2:3], v[100:101], 0 neg_lo:[1,0,0] neg_hi:[1,0,0]
	ds_read_b128 v[0:3], v33 offset:22784
	s_waitcnt lgkmcnt(6)
	v_pk_fma_f32 v[22:23], v[4:5], v[102:103], v[22:23] neg_lo:[1,0,0] neg_hi:[1,0,0]
	v_pk_fma_f32 v[30:31], v[6:7], v[104:105], v[30:31] neg_lo:[1,0,0] neg_hi:[1,0,0]
	ds_read_b128 v[4:7], v33 offset:22800
	s_waitcnt lgkmcnt(6)
	v_pk_fma_f32 v[22:23], v[8:9], v[106:107], v[22:23] neg_lo:[1,0,0] neg_hi:[1,0,0]
	v_pk_fma_f32 v[30:31], v[10:11], v[108:109], v[30:31] neg_lo:[1,0,0] neg_hi:[1,0,0]
	ds_read_b128 v[8:11], v33 offset:22816
	s_waitcnt lgkmcnt(6)
	v_pk_fma_f32 v[22:23], v[12:13], v[110:111], v[22:23] neg_lo:[1,0,0] neg_hi:[1,0,0]
	v_pk_fma_f32 v[30:31], v[14:15], v[112:113], v[30:31] neg_lo:[1,0,0] neg_hi:[1,0,0]
	ds_read_b128 v[12:15], v33 offset:22832
	s_waitcnt lgkmcnt(6)
	v_pk_fma_f32 v[22:23], v[16:17], v[114:115], v[22:23] neg_lo:[1,0,0] neg_hi:[1,0,0]
	v_pk_fma_f32 v[30:31], v[18:19], v[116:117], v[30:31] neg_lo:[1,0,0] neg_hi:[1,0,0]
	ds_read_b128 v[16:19], v33 offset:22848
	v_cmp_eq_u32_e32 vcc, 21, v152
	v_add_f32_e32 v82, v22, v23
	v_add_f32_e32 v83, v30, v31
	v_add_f32_e32 v118, v82, v83
	v_cvt_pk_bf16_f32 v25, v118, v118
	ds_write_b16 v84, v25 offset:2880
	v_cndmask_b32_e64 v22, 0, 1.0, vcc
	v_mov_b32_e32 v23, 0
	s_waitcnt lgkmcnt(5)
	v_pk_fma_f32 v[22:23], v[0:1], v[98:99], v[22:23] neg_lo:[1,0,0] neg_hi:[1,0,0]
	v_pk_fma_f32 v[30:31], v[2:3], v[100:101], 0 neg_lo:[1,0,0] neg_hi:[1,0,0]
	ds_read_b128 v[0:3], v33 offset:23040
	s_waitcnt lgkmcnt(5)
	v_pk_fma_f32 v[22:23], v[4:5], v[102:103], v[22:23] neg_lo:[1,0,0] neg_hi:[1,0,0]
	v_pk_fma_f32 v[30:31], v[6:7], v[104:105], v[30:31] neg_lo:[1,0,0] neg_hi:[1,0,0]
	ds_read_b128 v[4:7], v33 offset:23056
	s_waitcnt lgkmcnt(5)
	v_pk_fma_f32 v[22:23], v[8:9], v[106:107], v[22:23] neg_lo:[1,0,0] neg_hi:[1,0,0]
	v_pk_fma_f32 v[30:31], v[10:11], v[108:109], v[30:31] neg_lo:[1,0,0] neg_hi:[1,0,0]
	ds_read_b128 v[8:11], v33 offset:23072
	s_waitcnt lgkmcnt(5)
	v_pk_fma_f32 v[22:23], v[12:13], v[110:111], v[22:23] neg_lo:[1,0,0] neg_hi:[1,0,0]
	v_pk_fma_f32 v[30:31], v[14:15], v[112:113], v[30:31] neg_lo:[1,0,0] neg_hi:[1,0,0]
	ds_read_b128 v[12:15], v33 offset:23088
	s_waitcnt lgkmcnt(5)
	v_pk_fma_f32 v[22:23], v[16:17], v[114:115], v[22:23] neg_lo:[1,0,0] neg_hi:[1,0,0]
	v_pk_fma_f32 v[30:31], v[18:19], v[116:117], v[30:31] neg_lo:[1,0,0] neg_hi:[1,0,0]
	ds_read_b128 v[16:19], v33 offset:23104
	s_waitcnt lgkmcnt(11)
	v_pk_fma_f32 v[22:23], v[26:27], v[118:119], v[22:23] neg_lo:[1,0,0] neg_hi:[1,0,0]
	v_pk_fma_f32 v[30:31], v[28:29], v[120:121], v[30:31] neg_lo:[1,0,0] neg_hi:[1,0,0]
	ds_read_b128 v[26:29], v33 offset:23120
	v_cmp_eq_u32_e32 vcc, 22, v152
	v_add_f32_e32 v82, v22, v23
	v_add_f32_e32 v83, v30, v31
	v_add_f32_e32 v119, v82, v83
	v_cvt_pk_bf16_f32 v25, v119, v119
	ds_write_b16 v84, v25 offset:3024
	v_cndmask_b32_e64 v22, 0, 1.0, vcc
	v_mov_b32_e32 v23, 0
	s_waitcnt lgkmcnt(6)
	v_pk_fma_f32 v[22:23], v[0:1], v[98:99], v[22:23] neg_lo:[1,0,0] neg_hi:[1,0,0]
	v_pk_fma_f32 v[30:31], v[2:3], v[100:101], 0 neg_lo:[1,0,0] neg_hi:[1,0,0]
	ds_read_b128 v[0:3], v33 offset:23296
	s_waitcnt lgkmcnt(6)
	v_pk_fma_f32 v[22:23], v[4:5], v[102:103], v[22:23] neg_lo:[1,0,0] neg_hi:[1,0,0]
	v_pk_fma_f32 v[30:31], v[6:7], v[104:105], v[30:31] neg_lo:[1,0,0] neg_hi:[1,0,0]
	ds_read_b128 v[4:7], v33 offset:23312
	s_waitcnt lgkmcnt(6)
	v_pk_fma_f32 v[22:23], v[8:9], v[106:107], v[22:23] neg_lo:[1,0,0] neg_hi:[1,0,0]
	v_pk_fma_f32 v[30:31], v[10:11], v[108:109], v[30:31] neg_lo:[1,0,0] neg_hi:[1,0,0]
	ds_read_b128 v[8:11], v33 offset:23328
	s_waitcnt lgkmcnt(6)
	v_pk_fma_f32 v[22:23], v[12:13], v[110:111], v[22:23] neg_lo:[1,0,0] neg_hi:[1,0,0]
	v_pk_fma_f32 v[30:31], v[14:15], v[112:113], v[30:31] neg_lo:[1,0,0] neg_hi:[1,0,0]
	ds_read_b128 v[12:15], v33 offset:23344
	s_waitcnt lgkmcnt(6)
	v_pk_fma_f32 v[22:23], v[16:17], v[114:115], v[22:23] neg_lo:[1,0,0] neg_hi:[1,0,0]
	v_pk_fma_f32 v[30:31], v[18:19], v[116:117], v[30:31] neg_lo:[1,0,0] neg_hi:[1,0,0]
	ds_read_b128 v[16:19], v33 offset:23360
	s_waitcnt lgkmcnt(6)
	v_pk_fma_f32 v[22:23], v[26:27], v[118:119], v[22:23] neg_lo:[1,0,0] neg_hi:[1,0,0]
	v_pk_fma_f32 v[30:31], v[28:29], v[120:121], v[30:31] neg_lo:[1,0,0] neg_hi:[1,0,0]
	ds_read_b128 v[26:29], v33 offset:23376
	v_cmp_eq_u32_e32 vcc, 23, v152
	v_add_f32_e32 v82, v22, v23
	v_add_f32_e32 v83, v30, v31
	v_add_f32_e32 v120, v82, v83
	v_cvt_pk_bf16_f32 v25, v120, v120
	ds_write_b16 v84, v25 offset:3168
	v_cndmask_b32_e64 v22, 0, 1.0, vcc
	v_mov_b32_e32 v23, 0
	s_waitcnt lgkmcnt(6)
	v_pk_fma_f32 v[22:23], v[0:1], v[98:99], v[22:23] neg_lo:[1,0,0] neg_hi:[1,0,0]
	v_pk_fma_f32 v[30:31], v[2:3], v[100:101], 0 neg_lo:[1,0,0] neg_hi:[1,0,0]
	ds_read_b128 v[0:3], v33 offset:23552
	s_waitcnt lgkmcnt(6)
	v_pk_fma_f32 v[22:23], v[4:5], v[102:103], v[22:23] neg_lo:[1,0,0] neg_hi:[1,0,0]
	v_pk_fma_f32 v[30:31], v[6:7], v[104:105], v[30:31] neg_lo:[1,0,0] neg_hi:[1,0,0]
	ds_read_b128 v[4:7], v33 offset:23568
	s_waitcnt lgkmcnt(6)
	v_pk_fma_f32 v[22:23], v[8:9], v[106:107], v[22:23] neg_lo:[1,0,0] neg_hi:[1,0,0]
	v_pk_fma_f32 v[30:31], v[10:11], v[108:109], v[30:31] neg_lo:[1,0,0] neg_hi:[1,0,0]
	ds_read_b128 v[8:11], v33 offset:23584
	s_waitcnt lgkmcnt(6)
	v_pk_fma_f32 v[22:23], v[12:13], v[110:111], v[22:23] neg_lo:[1,0,0] neg_hi:[1,0,0]
	v_pk_fma_f32 v[30:31], v[14:15], v[112:113], v[30:31] neg_lo:[1,0,0] neg_hi:[1,0,0]
	ds_read_b128 v[12:15], v33 offset:23600
	s_waitcnt lgkmcnt(6)
	v_pk_fma_f32 v[22:23], v[16:17], v[114:115], v[22:23] neg_lo:[1,0,0] neg_hi:[1,0,0]
	v_pk_fma_f32 v[30:31], v[18:19], v[116:117], v[30:31] neg_lo:[1,0,0] neg_hi:[1,0,0]
	ds_read_b128 v[16:19], v33 offset:23616
	s_waitcnt lgkmcnt(6)
	v_pk_fma_f32 v[22:23], v[26:27], v[118:119], v[22:23] neg_lo:[1,0,0] neg_hi:[1,0,0]
	v_pk_fma_f32 v[30:31], v[28:29], v[120:121], v[30:31] neg_lo:[1,0,0] neg_hi:[1,0,0]
	ds_read_b128 v[26:29], v33 offset:23632
	v_cmp_eq_u32_e32 vcc, 24, v152
	v_add_f32_e32 v82, v22, v23
	v_add_f32_e32 v83, v30, v31
	v_add_f32_e32 v121, v82, v83
	v_cvt_pk_bf16_f32 v25, v121, v121
	ds_write_b16 v84, v25 offset:3312
	v_cndmask_b32_e64 v22, 0, 1.0, vcc
	v_mov_b32_e32 v23, 0
	ds_read_b128 v[34:37], v33 offset:23904
	s_waitcnt lgkmcnt(7)
	v_pk_fma_f32 v[22:23], v[0:1], v[98:99], v[22:23] neg_lo:[1,0,0] neg_hi:[1,0,0]
	v_pk_fma_f32 v[30:31], v[2:3], v[100:101], 0 neg_lo:[1,0,0] neg_hi:[1,0,0]
	ds_read_b128 v[0:3], v33 offset:23808
	s_waitcnt lgkmcnt(7)
	v_pk_fma_f32 v[22:23], v[4:5], v[102:103], v[22:23] neg_lo:[1,0,0] neg_hi:[1,0,0]
	v_pk_fma_f32 v[30:31], v[6:7], v[104:105], v[30:31] neg_lo:[1,0,0] neg_hi:[1,0,0]
	ds_read_b128 v[4:7], v33 offset:23824
	s_waitcnt lgkmcnt(7)
	v_pk_fma_f32 v[22:23], v[8:9], v[106:107], v[22:23] neg_lo:[1,0,0] neg_hi:[1,0,0]
	v_pk_fma_f32 v[30:31], v[10:11], v[108:109], v[30:31] neg_lo:[1,0,0] neg_hi:[1,0,0]
	ds_read_b128 v[8:11], v33 offset:23840
	s_waitcnt lgkmcnt(7)
	v_pk_fma_f32 v[22:23], v[12:13], v[110:111], v[22:23] neg_lo:[1,0,0] neg_hi:[1,0,0]
	v_pk_fma_f32 v[30:31], v[14:15], v[112:113], v[30:31] neg_lo:[1,0,0] neg_hi:[1,0,0]
	ds_read_b128 v[12:15], v33 offset:23856
	s_waitcnt lgkmcnt(7)
	v_pk_fma_f32 v[22:23], v[16:17], v[114:115], v[22:23] neg_lo:[1,0,0] neg_hi:[1,0,0]
	v_pk_fma_f32 v[30:31], v[18:19], v[116:117], v[30:31] neg_lo:[1,0,0] neg_hi:[1,0,0]
	ds_read_b128 v[16:19], v33 offset:23872
	s_waitcnt lgkmcnt(7)
	v_pk_fma_f32 v[22:23], v[26:27], v[118:119], v[22:23] neg_lo:[1,0,0] neg_hi:[1,0,0]
	v_pk_fma_f32 v[30:31], v[28:29], v[120:121], v[30:31] neg_lo:[1,0,0] neg_hi:[1,0,0]
	ds_read_b128 v[26:29], v33 offset:23888
	v_cmp_eq_u32_e32 vcc, 25, v152
	v_add_f32_e32 v82, v22, v23
	v_add_f32_e32 v83, v30, v31
	v_add_f32_e32 v122, v82, v83
	v_cvt_pk_bf16_f32 v25, v122, v122
	ds_write_b16 v84, v25 offset:3456
	v_cndmask_b32_e64 v22, 0, 1.0, vcc
	v_mov_b32_e32 v23, 0
	s_waitcnt lgkmcnt(6)
	v_pk_fma_f32 v[22:23], v[0:1], v[98:99], v[22:23] neg_lo:[1,0,0] neg_hi:[1,0,0]
	v_pk_fma_f32 v[30:31], v[2:3], v[100:101], 0 neg_lo:[1,0,0] neg_hi:[1,0,0]
	ds_read_b128 v[0:3], v33 offset:24064
	s_waitcnt lgkmcnt(6)
	v_pk_fma_f32 v[22:23], v[4:5], v[102:103], v[22:23] neg_lo:[1,0,0] neg_hi:[1,0,0]
	v_pk_fma_f32 v[30:31], v[6:7], v[104:105], v[30:31] neg_lo:[1,0,0] neg_hi:[1,0,0]
	ds_read_b128 v[4:7], v33 offset:24080
	s_waitcnt lgkmcnt(6)
	v_pk_fma_f32 v[22:23], v[8:9], v[106:107], v[22:23] neg_lo:[1,0,0] neg_hi:[1,0,0]
	v_pk_fma_f32 v[30:31], v[10:11], v[108:109], v[30:31] neg_lo:[1,0,0] neg_hi:[1,0,0]
	ds_read_b128 v[8:11], v33 offset:24096
	s_waitcnt lgkmcnt(6)
	v_pk_fma_f32 v[22:23], v[12:13], v[110:111], v[22:23] neg_lo:[1,0,0] neg_hi:[1,0,0]
	v_pk_fma_f32 v[30:31], v[14:15], v[112:113], v[30:31] neg_lo:[1,0,0] neg_hi:[1,0,0]
	ds_read_b128 v[12:15], v33 offset:24112
	s_waitcnt lgkmcnt(6)
	v_pk_fma_f32 v[22:23], v[16:17], v[114:115], v[22:23] neg_lo:[1,0,0] neg_hi:[1,0,0]
	v_pk_fma_f32 v[30:31], v[18:19], v[116:117], v[30:31] neg_lo:[1,0,0] neg_hi:[1,0,0]
	ds_read_b128 v[16:19], v33 offset:24128
	s_waitcnt lgkmcnt(6)
	v_pk_fma_f32 v[22:23], v[26:27], v[118:119], v[22:23] neg_lo:[1,0,0] neg_hi:[1,0,0]
	v_pk_fma_f32 v[30:31], v[28:29], v[120:121], v[30:31] neg_lo:[1,0,0] neg_hi:[1,0,0]
	ds_read_b128 v[26:29], v33 offset:24144
	s_waitcnt lgkmcnt(13)
	v_pk_fma_f32 v[22:23], v[34:35], v[122:123], v[22:23] neg_lo:[1,0,0] neg_hi:[1,0,0]
	v_pk_fma_f32 v[30:31], v[36:37], v[124:125], v[30:31] neg_lo:[1,0,0] neg_hi:[1,0,0]
	ds_read_b128 v[34:37], v33 offset:24160
	v_cmp_eq_u32_e32 vcc, 26, v152
	v_add_f32_e32 v82, v22, v23
	v_add_f32_e32 v83, v30, v31
	v_add_f32_e32 v123, v82, v83
	v_cvt_pk_bf16_f32 v25, v123, v123
	ds_write_b16 v84, v25 offset:3600
	v_cndmask_b32_e64 v22, 0, 1.0, vcc
	v_mov_b32_e32 v23, 0
	s_waitcnt lgkmcnt(7)
	v_pk_fma_f32 v[22:23], v[0:1], v[98:99], v[22:23] neg_lo:[1,0,0] neg_hi:[1,0,0]
	v_pk_fma_f32 v[30:31], v[2:3], v[100:101], 0 neg_lo:[1,0,0] neg_hi:[1,0,0]
	ds_read_b128 v[0:3], v33 offset:24320
	s_waitcnt lgkmcnt(7)
	v_pk_fma_f32 v[22:23], v[4:5], v[102:103], v[22:23] neg_lo:[1,0,0] neg_hi:[1,0,0]
	v_pk_fma_f32 v[30:31], v[6:7], v[104:105], v[30:31] neg_lo:[1,0,0] neg_hi:[1,0,0]
	ds_read_b128 v[4:7], v33 offset:24336
	s_waitcnt lgkmcnt(7)
	v_pk_fma_f32 v[22:23], v[8:9], v[106:107], v[22:23] neg_lo:[1,0,0] neg_hi:[1,0,0]
	v_pk_fma_f32 v[30:31], v[10:11], v[108:109], v[30:31] neg_lo:[1,0,0] neg_hi:[1,0,0]
	ds_read_b128 v[8:11], v33 offset:24352
	s_waitcnt lgkmcnt(7)
	v_pk_fma_f32 v[22:23], v[12:13], v[110:111], v[22:23] neg_lo:[1,0,0] neg_hi:[1,0,0]
	v_pk_fma_f32 v[30:31], v[14:15], v[112:113], v[30:31] neg_lo:[1,0,0] neg_hi:[1,0,0]
	ds_read_b128 v[12:15], v33 offset:24368
	s_waitcnt lgkmcnt(7)
	v_pk_fma_f32 v[22:23], v[16:17], v[114:115], v[22:23] neg_lo:[1,0,0] neg_hi:[1,0,0]
	v_pk_fma_f32 v[30:31], v[18:19], v[116:117], v[30:31] neg_lo:[1,0,0] neg_hi:[1,0,0]
	ds_read_b128 v[16:19], v33 offset:24384
	s_waitcnt lgkmcnt(7)
	v_pk_fma_f32 v[22:23], v[26:27], v[118:119], v[22:23] neg_lo:[1,0,0] neg_hi:[1,0,0]
	v_pk_fma_f32 v[30:31], v[28:29], v[120:121], v[30:31] neg_lo:[1,0,0] neg_hi:[1,0,0]
	ds_read_b128 v[26:29], v33 offset:24400
	s_waitcnt lgkmcnt(7)
	v_pk_fma_f32 v[22:23], v[34:35], v[122:123], v[22:23] neg_lo:[1,0,0] neg_hi:[1,0,0]
	v_pk_fma_f32 v[30:31], v[36:37], v[124:125], v[30:31] neg_lo:[1,0,0] neg_hi:[1,0,0]
	ds_read_b128 v[34:37], v33 offset:24416
	v_cmp_eq_u32_e32 vcc, 27, v152
	v_add_f32_e32 v82, v22, v23
	v_add_f32_e32 v83, v30, v31
	v_add_f32_e32 v124, v82, v83
	v_cvt_pk_bf16_f32 v25, v124, v124
	ds_write_b16 v84, v25 offset:3744
	v_cndmask_b32_e64 v22, 0, 1.0, vcc
	v_mov_b32_e32 v23, 0
	s_waitcnt lgkmcnt(7)
	v_pk_fma_f32 v[22:23], v[0:1], v[98:99], v[22:23] neg_lo:[1,0,0] neg_hi:[1,0,0]
	v_pk_fma_f32 v[30:31], v[2:3], v[100:101], 0 neg_lo:[1,0,0] neg_hi:[1,0,0]
	ds_read_b128 v[0:3], v33 offset:24576
	s_waitcnt lgkmcnt(7)
	v_pk_fma_f32 v[22:23], v[4:5], v[102:103], v[22:23] neg_lo:[1,0,0] neg_hi:[1,0,0]
	v_pk_fma_f32 v[30:31], v[6:7], v[104:105], v[30:31] neg_lo:[1,0,0] neg_hi:[1,0,0]
	ds_read_b128 v[4:7], v33 offset:24592
	s_waitcnt lgkmcnt(7)
	v_pk_fma_f32 v[22:23], v[8:9], v[106:107], v[22:23] neg_lo:[1,0,0] neg_hi:[1,0,0]
	v_pk_fma_f32 v[30:31], v[10:11], v[108:109], v[30:31] neg_lo:[1,0,0] neg_hi:[1,0,0]
	ds_read_b128 v[8:11], v33 offset:24608
	s_waitcnt lgkmcnt(7)
	v_pk_fma_f32 v[22:23], v[12:13], v[110:111], v[22:23] neg_lo:[1,0,0] neg_hi:[1,0,0]
	v_pk_fma_f32 v[30:31], v[14:15], v[112:113], v[30:31] neg_lo:[1,0,0] neg_hi:[1,0,0]
	ds_read_b128 v[12:15], v33 offset:24624
	s_waitcnt lgkmcnt(7)
	v_pk_fma_f32 v[22:23], v[16:17], v[114:115], v[22:23] neg_lo:[1,0,0] neg_hi:[1,0,0]
	v_pk_fma_f32 v[30:31], v[18:19], v[116:117], v[30:31] neg_lo:[1,0,0] neg_hi:[1,0,0]
	ds_read_b128 v[16:19], v33 offset:24640
	s_waitcnt lgkmcnt(7)
	v_pk_fma_f32 v[22:23], v[26:27], v[118:119], v[22:23] neg_lo:[1,0,0] neg_hi:[1,0,0]
	v_pk_fma_f32 v[30:31], v[28:29], v[120:121], v[30:31] neg_lo:[1,0,0] neg_hi:[1,0,0]
	ds_read_b128 v[26:29], v33 offset:24656
	s_waitcnt lgkmcnt(7)
	v_pk_fma_f32 v[22:23], v[34:35], v[122:123], v[22:23] neg_lo:[1,0,0] neg_hi:[1,0,0]
	v_pk_fma_f32 v[30:31], v[36:37], v[124:125], v[30:31] neg_lo:[1,0,0] neg_hi:[1,0,0]
	ds_read_b128 v[34:37], v33 offset:24672
	v_cmp_eq_u32_e32 vcc, 28, v152
	v_add_f32_e32 v82, v22, v23
	v_add_f32_e32 v83, v30, v31
	v_add_f32_e32 v125, v82, v83
	v_cvt_pk_bf16_f32 v25, v125, v125
	ds_write_b16 v84, v25 offset:3888
	v_cndmask_b32_e64 v22, 0, 1.0, vcc
	v_mov_b32_e32 v23, 0
	ds_read_b128 v[38:41], v33 offset:24944
	s_waitcnt lgkmcnt(8)
	v_pk_fma_f32 v[22:23], v[0:1], v[98:99], v[22:23] neg_lo:[1,0,0] neg_hi:[1,0,0]
	v_pk_fma_f32 v[30:31], v[2:3], v[100:101], 0 neg_lo:[1,0,0] neg_hi:[1,0,0]
	ds_read_b128 v[0:3], v33 offset:24832
	s_waitcnt lgkmcnt(8)
	v_pk_fma_f32 v[22:23], v[4:5], v[102:103], v[22:23] neg_lo:[1,0,0] neg_hi:[1,0,0]
	v_pk_fma_f32 v[30:31], v[6:7], v[104:105], v[30:31] neg_lo:[1,0,0] neg_hi:[1,0,0]
	ds_read_b128 v[4:7], v33 offset:24848
	s_waitcnt lgkmcnt(8)
	v_pk_fma_f32 v[22:23], v[8:9], v[106:107], v[22:23] neg_lo:[1,0,0] neg_hi:[1,0,0]
	v_pk_fma_f32 v[30:31], v[10:11], v[108:109], v[30:31] neg_lo:[1,0,0] neg_hi:[1,0,0]
	ds_read_b128 v[8:11], v33 offset:24864
	s_waitcnt lgkmcnt(8)
	v_pk_fma_f32 v[22:23], v[12:13], v[110:111], v[22:23] neg_lo:[1,0,0] neg_hi:[1,0,0]
	v_pk_fma_f32 v[30:31], v[14:15], v[112:113], v[30:31] neg_lo:[1,0,0] neg_hi:[1,0,0]
	ds_read_b128 v[12:15], v33 offset:24880
	s_waitcnt lgkmcnt(8)
	v_pk_fma_f32 v[22:23], v[16:17], v[114:115], v[22:23] neg_lo:[1,0,0] neg_hi:[1,0,0]
	v_pk_fma_f32 v[30:31], v[18:19], v[116:117], v[30:31] neg_lo:[1,0,0] neg_hi:[1,0,0]
	ds_read_b128 v[16:19], v33 offset:24896
	s_waitcnt lgkmcnt(8)
	v_pk_fma_f32 v[22:23], v[26:27], v[118:119], v[22:23] neg_lo:[1,0,0] neg_hi:[1,0,0]
	v_pk_fma_f32 v[30:31], v[28:29], v[120:121], v[30:31] neg_lo:[1,0,0] neg_hi:[1,0,0]
	ds_read_b128 v[26:29], v33 offset:24912
	s_waitcnt lgkmcnt(8)
	v_pk_fma_f32 v[22:23], v[34:35], v[122:123], v[22:23] neg_lo:[1,0,0] neg_hi:[1,0,0]
	v_pk_fma_f32 v[30:31], v[36:37], v[124:125], v[30:31] neg_lo:[1,0,0] neg_hi:[1,0,0]
	ds_read_b128 v[34:37], v33 offset:24928
	v_cmp_eq_u32_e32 vcc, 29, v152
	v_add_f32_e32 v82, v22, v23
	v_add_f32_e32 v83, v30, v31
	v_add_f32_e32 v126, v82, v83
	v_cvt_pk_bf16_f32 v25, v126, v126
	ds_write_b16 v84, v25 offset:4032
	v_cndmask_b32_e64 v22, 0, 1.0, vcc
	v_mov_b32_e32 v23, 0
	s_waitcnt lgkmcnt(7)
	v_pk_fma_f32 v[22:23], v[0:1], v[98:99], v[22:23] neg_lo:[1,0,0] neg_hi:[1,0,0]
	v_pk_fma_f32 v[30:31], v[2:3], v[100:101], 0 neg_lo:[1,0,0] neg_hi:[1,0,0]
	ds_read_b128 v[0:3], v33 offset:25088
	s_waitcnt lgkmcnt(7)
	v_pk_fma_f32 v[22:23], v[4:5], v[102:103], v[22:23] neg_lo:[1,0,0] neg_hi:[1,0,0]
	v_pk_fma_f32 v[30:31], v[6:7], v[104:105], v[30:31] neg_lo:[1,0,0] neg_hi:[1,0,0]
	ds_read_b128 v[4:7], v33 offset:25104
	s_waitcnt lgkmcnt(7)
	v_pk_fma_f32 v[22:23], v[8:9], v[106:107], v[22:23] neg_lo:[1,0,0] neg_hi:[1,0,0]
	v_pk_fma_f32 v[30:31], v[10:11], v[108:109], v[30:31] neg_lo:[1,0,0] neg_hi:[1,0,0]
	ds_read_b128 v[8:11], v33 offset:25120
	s_waitcnt lgkmcnt(7)
	v_pk_fma_f32 v[22:23], v[12:13], v[110:111], v[22:23] neg_lo:[1,0,0] neg_hi:[1,0,0]
	v_pk_fma_f32 v[30:31], v[14:15], v[112:113], v[30:31] neg_lo:[1,0,0] neg_hi:[1,0,0]
	ds_read_b128 v[12:15], v33 offset:25136
	s_waitcnt lgkmcnt(7)
	v_pk_fma_f32 v[22:23], v[16:17], v[114:115], v[22:23] neg_lo:[1,0,0] neg_hi:[1,0,0]
	v_pk_fma_f32 v[30:31], v[18:19], v[116:117], v[30:31] neg_lo:[1,0,0] neg_hi:[1,0,0]
	ds_read_b128 v[16:19], v33 offset:25152
	s_waitcnt lgkmcnt(7)
	v_pk_fma_f32 v[22:23], v[26:27], v[118:119], v[22:23] neg_lo:[1,0,0] neg_hi:[1,0,0]
	v_pk_fma_f32 v[30:31], v[28:29], v[120:121], v[30:31] neg_lo:[1,0,0] neg_hi:[1,0,0]
	ds_read_b128 v[26:29], v33 offset:25168
	s_waitcnt lgkmcnt(7)
	v_pk_fma_f32 v[22:23], v[34:35], v[122:123], v[22:23] neg_lo:[1,0,0] neg_hi:[1,0,0]
	v_pk_fma_f32 v[30:31], v[36:37], v[124:125], v[30:31] neg_lo:[1,0,0] neg_hi:[1,0,0]
	ds_read_b128 v[34:37], v33 offset:25184
	s_waitcnt lgkmcnt(15)
	v_pk_fma_f32 v[22:23], v[38:39], v[126:127], v[22:23] neg_lo:[1,0,0] neg_hi:[1,0,0]
	v_pk_fma_f32 v[30:31], v[40:41], v[128:129], v[30:31] neg_lo:[1,0,0] neg_hi:[1,0,0]
	ds_read_b128 v[38:41], v33 offset:25200
	v_cmp_eq_u32_e32 vcc, 30, v152
	v_add_f32_e32 v82, v22, v23
	v_add_f32_e32 v83, v30, v31
	v_add_f32_e32 v127, v82, v83
	v_cvt_pk_bf16_f32 v25, v127, v127
	ds_write_b16 v84, v25 offset:4176
	v_cndmask_b32_e64 v22, 0, 1.0, vcc
	v_mov_b32_e32 v23, 0
	s_waitcnt lgkmcnt(8)
	v_pk_fma_f32 v[22:23], v[0:1], v[98:99], v[22:23] neg_lo:[1,0,0] neg_hi:[1,0,0]
	v_pk_fma_f32 v[30:31], v[2:3], v[100:101], 0 neg_lo:[1,0,0] neg_hi:[1,0,0]
	ds_read_b128 v[0:3], v33 offset:25344
	s_waitcnt lgkmcnt(8)
	v_pk_fma_f32 v[22:23], v[4:5], v[102:103], v[22:23] neg_lo:[1,0,0] neg_hi:[1,0,0]
	v_pk_fma_f32 v[30:31], v[6:7], v[104:105], v[30:31] neg_lo:[1,0,0] neg_hi:[1,0,0]
	ds_read_b128 v[4:7], v33 offset:25360
	s_waitcnt lgkmcnt(8)
	v_pk_fma_f32 v[22:23], v[8:9], v[106:107], v[22:23] neg_lo:[1,0,0] neg_hi:[1,0,0]
	v_pk_fma_f32 v[30:31], v[10:11], v[108:109], v[30:31] neg_lo:[1,0,0] neg_hi:[1,0,0]
	ds_read_b128 v[8:11], v33 offset:25376
	s_waitcnt lgkmcnt(8)
	v_pk_fma_f32 v[22:23], v[12:13], v[110:111], v[22:23] neg_lo:[1,0,0] neg_hi:[1,0,0]
	v_pk_fma_f32 v[30:31], v[14:15], v[112:113], v[30:31] neg_lo:[1,0,0] neg_hi:[1,0,0]
	ds_read_b128 v[12:15], v33 offset:25392
	s_waitcnt lgkmcnt(8)
	v_pk_fma_f32 v[22:23], v[16:17], v[114:115], v[22:23] neg_lo:[1,0,0] neg_hi:[1,0,0]
	v_pk_fma_f32 v[30:31], v[18:19], v[116:117], v[30:31] neg_lo:[1,0,0] neg_hi:[1,0,0]
	ds_read_b128 v[16:19], v33 offset:25408
	s_waitcnt lgkmcnt(8)
	v_pk_fma_f32 v[22:23], v[26:27], v[118:119], v[22:23] neg_lo:[1,0,0] neg_hi:[1,0,0]
	v_pk_fma_f32 v[30:31], v[28:29], v[120:121], v[30:31] neg_lo:[1,0,0] neg_hi:[1,0,0]
	ds_read_b128 v[26:29], v33 offset:25424
	s_waitcnt lgkmcnt(8)
	v_pk_fma_f32 v[22:23], v[34:35], v[122:123], v[22:23] neg_lo:[1,0,0] neg_hi:[1,0,0]
	v_pk_fma_f32 v[30:31], v[36:37], v[124:125], v[30:31] neg_lo:[1,0,0] neg_hi:[1,0,0]
	ds_read_b128 v[34:37], v33 offset:25440
	s_waitcnt lgkmcnt(8)
	v_pk_fma_f32 v[22:23], v[38:39], v[126:127], v[22:23] neg_lo:[1,0,0] neg_hi:[1,0,0]
	v_pk_fma_f32 v[30:31], v[40:41], v[128:129], v[30:31] neg_lo:[1,0,0] neg_hi:[1,0,0]
	ds_read_b128 v[38:41], v33 offset:25456
	v_cmp_eq_u32_e32 vcc, 31, v152
	v_add_f32_e32 v82, v22, v23
	v_add_f32_e32 v83, v30, v31
	v_add_f32_e32 v128, v82, v83
	v_cvt_pk_bf16_f32 v25, v128, v128
	ds_write_b16 v84, v25 offset:4320
	v_cndmask_b32_e64 v22, 0, 1.0, vcc
	v_mov_b32_e32 v23, 0
	s_waitcnt lgkmcnt(8)
	v_pk_fma_f32 v[22:23], v[0:1], v[98:99], v[22:23] neg_lo:[1,0,0] neg_hi:[1,0,0]
	v_pk_fma_f32 v[30:31], v[2:3], v[100:101], 0 neg_lo:[1,0,0] neg_hi:[1,0,0]
	ds_read_b128 v[0:3], v33 offset:25600
	s_waitcnt lgkmcnt(8)
	v_pk_fma_f32 v[22:23], v[4:5], v[102:103], v[22:23] neg_lo:[1,0,0] neg_hi:[1,0,0]
	v_pk_fma_f32 v[30:31], v[6:7], v[104:105], v[30:31] neg_lo:[1,0,0] neg_hi:[1,0,0]
	ds_read_b128 v[4:7], v33 offset:25616
	s_waitcnt lgkmcnt(8)
	v_pk_fma_f32 v[22:23], v[8:9], v[106:107], v[22:23] neg_lo:[1,0,0] neg_hi:[1,0,0]
	v_pk_fma_f32 v[30:31], v[10:11], v[108:109], v[30:31] neg_lo:[1,0,0] neg_hi:[1,0,0]
	ds_read_b128 v[8:11], v33 offset:25632
	s_waitcnt lgkmcnt(8)
	v_pk_fma_f32 v[22:23], v[12:13], v[110:111], v[22:23] neg_lo:[1,0,0] neg_hi:[1,0,0]
	v_pk_fma_f32 v[30:31], v[14:15], v[112:113], v[30:31] neg_lo:[1,0,0] neg_hi:[1,0,0]
	ds_read_b128 v[12:15], v33 offset:25648
	s_waitcnt lgkmcnt(8)
	v_pk_fma_f32 v[22:23], v[16:17], v[114:115], v[22:23] neg_lo:[1,0,0] neg_hi:[1,0,0]
	v_pk_fma_f32 v[30:31], v[18:19], v[116:117], v[30:31] neg_lo:[1,0,0] neg_hi:[1,0,0]
	ds_read_b128 v[16:19], v33 offset:25664
	s_waitcnt lgkmcnt(8)
	v_pk_fma_f32 v[22:23], v[26:27], v[118:119], v[22:23] neg_lo:[1,0,0] neg_hi:[1,0,0]
	v_pk_fma_f32 v[30:31], v[28:29], v[120:121], v[30:31] neg_lo:[1,0,0] neg_hi:[1,0,0]
	ds_read_b128 v[26:29], v33 offset:25680
	s_waitcnt lgkmcnt(8)
	v_pk_fma_f32 v[22:23], v[34:35], v[122:123], v[22:23] neg_lo:[1,0,0] neg_hi:[1,0,0]
	v_pk_fma_f32 v[30:31], v[36:37], v[124:125], v[30:31] neg_lo:[1,0,0] neg_hi:[1,0,0]
	ds_read_b128 v[34:37], v33 offset:25696
	s_waitcnt lgkmcnt(8)
	v_pk_fma_f32 v[22:23], v[38:39], v[126:127], v[22:23] neg_lo:[1,0,0] neg_hi:[1,0,0]
	v_pk_fma_f32 v[30:31], v[40:41], v[128:129], v[30:31] neg_lo:[1,0,0] neg_hi:[1,0,0]
	ds_read_b128 v[38:41], v33 offset:25712
	v_cmp_eq_u32_e32 vcc, 32, v152
	v_add_f32_e32 v82, v22, v23
	v_add_f32_e32 v83, v30, v31
	v_add_f32_e32 v129, v82, v83
	v_cvt_pk_bf16_f32 v25, v129, v129
	ds_write_b16 v84, v25 offset:4464
	v_cndmask_b32_e64 v22, 0, 1.0, vcc
	v_mov_b32_e32 v23, 0
	ds_read_b128 v[42:45], v33 offset:25984
	s_waitcnt lgkmcnt(9)
	v_pk_fma_f32 v[22:23], v[0:1], v[98:99], v[22:23] neg_lo:[1,0,0] neg_hi:[1,0,0]
	v_pk_fma_f32 v[30:31], v[2:3], v[100:101], 0 neg_lo:[1,0,0] neg_hi:[1,0,0]
	ds_read_b128 v[0:3], v33 offset:25856
	s_waitcnt lgkmcnt(9)
	v_pk_fma_f32 v[22:23], v[4:5], v[102:103], v[22:23] neg_lo:[1,0,0] neg_hi:[1,0,0]
	v_pk_fma_f32 v[30:31], v[6:7], v[104:105], v[30:31] neg_lo:[1,0,0] neg_hi:[1,0,0]
	ds_read_b128 v[4:7], v33 offset:25872
	s_waitcnt lgkmcnt(9)
	v_pk_fma_f32 v[22:23], v[8:9], v[106:107], v[22:23] neg_lo:[1,0,0] neg_hi:[1,0,0]
	v_pk_fma_f32 v[30:31], v[10:11], v[108:109], v[30:31] neg_lo:[1,0,0] neg_hi:[1,0,0]
	ds_read_b128 v[8:11], v33 offset:25888
	s_waitcnt lgkmcnt(9)
	v_pk_fma_f32 v[22:23], v[12:13], v[110:111], v[22:23] neg_lo:[1,0,0] neg_hi:[1,0,0]
	v_pk_fma_f32 v[30:31], v[14:15], v[112:113], v[30:31] neg_lo:[1,0,0] neg_hi:[1,0,0]
	ds_read_b128 v[12:15], v33 offset:25904
	s_waitcnt lgkmcnt(9)
	v_pk_fma_f32 v[22:23], v[16:17], v[114:115], v[22:23] neg_lo:[1,0,0] neg_hi:[1,0,0]
	v_pk_fma_f32 v[30:31], v[18:19], v[116:117], v[30:31] neg_lo:[1,0,0] neg_hi:[1,0,0]
	ds_read_b128 v[16:19], v33 offset:25920
	s_waitcnt lgkmcnt(9)
	v_pk_fma_f32 v[22:23], v[26:27], v[118:119], v[22:23] neg_lo:[1,0,0] neg_hi:[1,0,0]
	v_pk_fma_f32 v[30:31], v[28:29], v[120:121], v[30:31] neg_lo:[1,0,0] neg_hi:[1,0,0]
	ds_read_b128 v[26:29], v33 offset:25936
	s_waitcnt lgkmcnt(9)
	v_pk_fma_f32 v[22:23], v[34:35], v[122:123], v[22:23] neg_lo:[1,0,0] neg_hi:[1,0,0]
	v_pk_fma_f32 v[30:31], v[36:37], v[124:125], v[30:31] neg_lo:[1,0,0] neg_hi:[1,0,0]
	ds_read_b128 v[34:37], v33 offset:25952
	s_waitcnt lgkmcnt(9)
	v_pk_fma_f32 v[22:23], v[38:39], v[126:127], v[22:23] neg_lo:[1,0,0] neg_hi:[1,0,0]
	v_pk_fma_f32 v[30:31], v[40:41], v[128:129], v[30:31] neg_lo:[1,0,0] neg_hi:[1,0,0]
	ds_read_b128 v[38:41], v33 offset:25968
	v_cmp_eq_u32_e32 vcc, 33, v152
	v_add_f32_e32 v82, v22, v23
	v_add_f32_e32 v83, v30, v31
	v_add_f32_e32 v130, v82, v83
	v_cvt_pk_bf16_f32 v25, v130, v130
	ds_write_b16 v84, v25 offset:4608
	v_cndmask_b32_e64 v22, 0, 1.0, vcc
	v_mov_b32_e32 v23, 0
	s_waitcnt lgkmcnt(8)
	v_pk_fma_f32 v[22:23], v[0:1], v[98:99], v[22:23] neg_lo:[1,0,0] neg_hi:[1,0,0]
	v_pk_fma_f32 v[30:31], v[2:3], v[100:101], 0 neg_lo:[1,0,0] neg_hi:[1,0,0]
	ds_read_b128 v[0:3], v33 offset:26112
	s_waitcnt lgkmcnt(8)
	v_pk_fma_f32 v[22:23], v[4:5], v[102:103], v[22:23] neg_lo:[1,0,0] neg_hi:[1,0,0]
	v_pk_fma_f32 v[30:31], v[6:7], v[104:105], v[30:31] neg_lo:[1,0,0] neg_hi:[1,0,0]
	ds_read_b128 v[4:7], v33 offset:26128
	s_waitcnt lgkmcnt(8)
	v_pk_fma_f32 v[22:23], v[8:9], v[106:107], v[22:23] neg_lo:[1,0,0] neg_hi:[1,0,0]
	v_pk_fma_f32 v[30:31], v[10:11], v[108:109], v[30:31] neg_lo:[1,0,0] neg_hi:[1,0,0]
	ds_read_b128 v[8:11], v33 offset:26144
	s_waitcnt lgkmcnt(8)
	v_pk_fma_f32 v[22:23], v[12:13], v[110:111], v[22:23] neg_lo:[1,0,0] neg_hi:[1,0,0]
	v_pk_fma_f32 v[30:31], v[14:15], v[112:113], v[30:31] neg_lo:[1,0,0] neg_hi:[1,0,0]
	ds_read_b128 v[12:15], v33 offset:26160
	s_waitcnt lgkmcnt(8)
	v_pk_fma_f32 v[22:23], v[16:17], v[114:115], v[22:23] neg_lo:[1,0,0] neg_hi:[1,0,0]
	v_pk_fma_f32 v[30:31], v[18:19], v[116:117], v[30:31] neg_lo:[1,0,0] neg_hi:[1,0,0]
	ds_read_b128 v[16:19], v33 offset:26176
	s_waitcnt lgkmcnt(8)
	v_pk_fma_f32 v[22:23], v[26:27], v[118:119], v[22:23] neg_lo:[1,0,0] neg_hi:[1,0,0]
	v_pk_fma_f32 v[30:31], v[28:29], v[120:121], v[30:31] neg_lo:[1,0,0] neg_hi:[1,0,0]
	ds_read_b128 v[26:29], v33 offset:26192
	s_waitcnt lgkmcnt(8)
	v_pk_fma_f32 v[22:23], v[34:35], v[122:123], v[22:23] neg_lo:[1,0,0] neg_hi:[1,0,0]
	v_pk_fma_f32 v[30:31], v[36:37], v[124:125], v[30:31] neg_lo:[1,0,0] neg_hi:[1,0,0]
	ds_read_b128 v[34:37], v33 offset:26208
	s_waitcnt lgkmcnt(8)
	v_pk_fma_f32 v[22:23], v[38:39], v[126:127], v[22:23] neg_lo:[1,0,0] neg_hi:[1,0,0]
	v_pk_fma_f32 v[30:31], v[40:41], v[128:129], v[30:31] neg_lo:[1,0,0] neg_hi:[1,0,0]
	ds_read_b128 v[38:41], v33 offset:26224
	s_waitcnt lgkmcnt(15)
	v_pk_fma_f32 v[22:23], v[42:43], v[130:131], v[22:23] neg_lo:[1,0,0] neg_hi:[1,0,0]
	v_pk_fma_f32 v[30:31], v[44:45], v[132:133], v[30:31] neg_lo:[1,0,0] neg_hi:[1,0,0]
	ds_read_b128 v[42:45], v33 offset:26240
	v_cmp_eq_u32_e32 vcc, 34, v152
	v_add_f32_e32 v82, v22, v23
	v_add_f32_e32 v83, v30, v31
	v_add_f32_e32 v131, v82, v83
	v_cvt_pk_bf16_f32 v25, v131, v131
	ds_write_b16 v84, v25 offset:4752
	v_cndmask_b32_e64 v22, 0, 1.0, vcc
	v_mov_b32_e32 v23, 0
	s_waitcnt lgkmcnt(9)
	v_pk_fma_f32 v[22:23], v[0:1], v[98:99], v[22:23] neg_lo:[1,0,0] neg_hi:[1,0,0]
	v_pk_fma_f32 v[30:31], v[2:3], v[100:101], 0 neg_lo:[1,0,0] neg_hi:[1,0,0]
	ds_read_b128 v[0:3], v33 offset:26368
	s_waitcnt lgkmcnt(9)
	v_pk_fma_f32 v[22:23], v[4:5], v[102:103], v[22:23] neg_lo:[1,0,0] neg_hi:[1,0,0]
	v_pk_fma_f32 v[30:31], v[6:7], v[104:105], v[30:31] neg_lo:[1,0,0] neg_hi:[1,0,0]
	ds_read_b128 v[4:7], v33 offset:26384
	s_waitcnt lgkmcnt(9)
	v_pk_fma_f32 v[22:23], v[8:9], v[106:107], v[22:23] neg_lo:[1,0,0] neg_hi:[1,0,0]
	v_pk_fma_f32 v[30:31], v[10:11], v[108:109], v[30:31] neg_lo:[1,0,0] neg_hi:[1,0,0]
	ds_read_b128 v[8:11], v33 offset:26400
	s_waitcnt lgkmcnt(9)
	v_pk_fma_f32 v[22:23], v[12:13], v[110:111], v[22:23] neg_lo:[1,0,0] neg_hi:[1,0,0]
	v_pk_fma_f32 v[30:31], v[14:15], v[112:113], v[30:31] neg_lo:[1,0,0] neg_hi:[1,0,0]
	ds_read_b128 v[12:15], v33 offset:26416
	s_waitcnt lgkmcnt(9)
	v_pk_fma_f32 v[22:23], v[16:17], v[114:115], v[22:23] neg_lo:[1,0,0] neg_hi:[1,0,0]
	v_pk_fma_f32 v[30:31], v[18:19], v[116:117], v[30:31] neg_lo:[1,0,0] neg_hi:[1,0,0]
	ds_read_b128 v[16:19], v33 offset:26432
	s_waitcnt lgkmcnt(9)
	v_pk_fma_f32 v[22:23], v[26:27], v[118:119], v[22:23] neg_lo:[1,0,0] neg_hi:[1,0,0]
	v_pk_fma_f32 v[30:31], v[28:29], v[120:121], v[30:31] neg_lo:[1,0,0] neg_hi:[1,0,0]
	ds_read_b128 v[26:29], v33 offset:26448
	s_waitcnt lgkmcnt(9)
	v_pk_fma_f32 v[22:23], v[34:35], v[122:123], v[22:23] neg_lo:[1,0,0] neg_hi:[1,0,0]
	v_pk_fma_f32 v[30:31], v[36:37], v[124:125], v[30:31] neg_lo:[1,0,0] neg_hi:[1,0,0]
	ds_read_b128 v[34:37], v33 offset:26464
	s_waitcnt lgkmcnt(9)
	v_pk_fma_f32 v[22:23], v[38:39], v[126:127], v[22:23] neg_lo:[1,0,0] neg_hi:[1,0,0]
	v_pk_fma_f32 v[30:31], v[40:41], v[128:129], v[30:31] neg_lo:[1,0,0] neg_hi:[1,0,0]
	ds_read_b128 v[38:41], v33 offset:26480
	s_waitcnt lgkmcnt(9)
	v_pk_fma_f32 v[22:23], v[42:43], v[130:131], v[22:23] neg_lo:[1,0,0] neg_hi:[1,0,0]
	v_pk_fma_f32 v[30:31], v[44:45], v[132:133], v[30:31] neg_lo:[1,0,0] neg_hi:[1,0,0]
	ds_read_b128 v[42:45], v33 offset:26496
	v_cmp_eq_u32_e32 vcc, 35, v152
	v_add_f32_e32 v82, v22, v23
	v_add_f32_e32 v83, v30, v31
	v_add_f32_e32 v132, v82, v83
	v_cvt_pk_bf16_f32 v25, v132, v132
	ds_write_b16 v84, v25 offset:4896
	v_cndmask_b32_e64 v22, 0, 1.0, vcc
	v_mov_b32_e32 v23, 0
	s_waitcnt lgkmcnt(9)
	v_pk_fma_f32 v[22:23], v[0:1], v[98:99], v[22:23] neg_lo:[1,0,0] neg_hi:[1,0,0]
	v_pk_fma_f32 v[30:31], v[2:3], v[100:101], 0 neg_lo:[1,0,0] neg_hi:[1,0,0]
	ds_read_b128 v[0:3], v33 offset:26624
	s_waitcnt lgkmcnt(9)
	v_pk_fma_f32 v[22:23], v[4:5], v[102:103], v[22:23] neg_lo:[1,0,0] neg_hi:[1,0,0]
	v_pk_fma_f32 v[30:31], v[6:7], v[104:105], v[30:31] neg_lo:[1,0,0] neg_hi:[1,0,0]
	ds_read_b128 v[4:7], v33 offset:26640
	s_waitcnt lgkmcnt(9)
	v_pk_fma_f32 v[22:23], v[8:9], v[106:107], v[22:23] neg_lo:[1,0,0] neg_hi:[1,0,0]
	v_pk_fma_f32 v[30:31], v[10:11], v[108:109], v[30:31] neg_lo:[1,0,0] neg_hi:[1,0,0]
	ds_read_b128 v[8:11], v33 offset:26656
	s_waitcnt lgkmcnt(9)
	v_pk_fma_f32 v[22:23], v[12:13], v[110:111], v[22:23] neg_lo:[1,0,0] neg_hi:[1,0,0]
	v_pk_fma_f32 v[30:31], v[14:15], v[112:113], v[30:31] neg_lo:[1,0,0] neg_hi:[1,0,0]
	ds_read_b128 v[12:15], v33 offset:26672
	s_waitcnt lgkmcnt(9)
	v_pk_fma_f32 v[22:23], v[16:17], v[114:115], v[22:23] neg_lo:[1,0,0] neg_hi:[1,0,0]
	v_pk_fma_f32 v[30:31], v[18:19], v[116:117], v[30:31] neg_lo:[1,0,0] neg_hi:[1,0,0]
	ds_read_b128 v[16:19], v33 offset:26688
	s_waitcnt lgkmcnt(9)
	v_pk_fma_f32 v[22:23], v[26:27], v[118:119], v[22:23] neg_lo:[1,0,0] neg_hi:[1,0,0]
	v_pk_fma_f32 v[30:31], v[28:29], v[120:121], v[30:31] neg_lo:[1,0,0] neg_hi:[1,0,0]
	ds_read_b128 v[26:29], v33 offset:26704
	s_waitcnt lgkmcnt(9)
	v_pk_fma_f32 v[22:23], v[34:35], v[122:123], v[22:23] neg_lo:[1,0,0] neg_hi:[1,0,0]
	v_pk_fma_f32 v[30:31], v[36:37], v[124:125], v[30:31] neg_lo:[1,0,0] neg_hi:[1,0,0]
	ds_read_b128 v[34:37], v33 offset:26720
	s_waitcnt lgkmcnt(9)
	v_pk_fma_f32 v[22:23], v[38:39], v[126:127], v[22:23] neg_lo:[1,0,0] neg_hi:[1,0,0]
	v_pk_fma_f32 v[30:31], v[40:41], v[128:129], v[30:31] neg_lo:[1,0,0] neg_hi:[1,0,0]
	ds_read_b128 v[38:41], v33 offset:26736
	s_waitcnt lgkmcnt(9)
	v_pk_fma_f32 v[22:23], v[42:43], v[130:131], v[22:23] neg_lo:[1,0,0] neg_hi:[1,0,0]
	v_pk_fma_f32 v[30:31], v[44:45], v[132:133], v[30:31] neg_lo:[1,0,0] neg_hi:[1,0,0]
	ds_read_b128 v[42:45], v33 offset:26752
	v_cmp_eq_u32_e32 vcc, 36, v152
	v_add_f32_e32 v82, v22, v23
	v_add_f32_e32 v83, v30, v31
	v_add_f32_e32 v133, v82, v83
	v_cvt_pk_bf16_f32 v25, v133, v133
	ds_write_b16 v84, v25 offset:5040
	v_cndmask_b32_e64 v22, 0, 1.0, vcc
	v_mov_b32_e32 v23, 0
	ds_read_b128 v[46:49], v33 offset:27024
	s_waitcnt lgkmcnt(10)
	v_pk_fma_f32 v[22:23], v[0:1], v[98:99], v[22:23] neg_lo:[1,0,0] neg_hi:[1,0,0]
	v_pk_fma_f32 v[30:31], v[2:3], v[100:101], 0 neg_lo:[1,0,0] neg_hi:[1,0,0]
	ds_read_b128 v[0:3], v33 offset:26880
	s_waitcnt lgkmcnt(10)
	v_pk_fma_f32 v[22:23], v[4:5], v[102:103], v[22:23] neg_lo:[1,0,0] neg_hi:[1,0,0]
	v_pk_fma_f32 v[30:31], v[6:7], v[104:105], v[30:31] neg_lo:[1,0,0] neg_hi:[1,0,0]
	ds_read_b128 v[4:7], v33 offset:26896
	s_waitcnt lgkmcnt(10)
	v_pk_fma_f32 v[22:23], v[8:9], v[106:107], v[22:23] neg_lo:[1,0,0] neg_hi:[1,0,0]
	v_pk_fma_f32 v[30:31], v[10:11], v[108:109], v[30:31] neg_lo:[1,0,0] neg_hi:[1,0,0]
	ds_read_b128 v[8:11], v33 offset:26912
	s_waitcnt lgkmcnt(10)
	v_pk_fma_f32 v[22:23], v[12:13], v[110:111], v[22:23] neg_lo:[1,0,0] neg_hi:[1,0,0]
	v_pk_fma_f32 v[30:31], v[14:15], v[112:113], v[30:31] neg_lo:[1,0,0] neg_hi:[1,0,0]
	ds_read_b128 v[12:15], v33 offset:26928
	s_waitcnt lgkmcnt(10)
	v_pk_fma_f32 v[22:23], v[16:17], v[114:115], v[22:23] neg_lo:[1,0,0] neg_hi:[1,0,0]
	v_pk_fma_f32 v[30:31], v[18:19], v[116:117], v[30:31] neg_lo:[1,0,0] neg_hi:[1,0,0]
	ds_read_b128 v[16:19], v33 offset:26944
	s_waitcnt lgkmcnt(10)
	v_pk_fma_f32 v[22:23], v[26:27], v[118:119], v[22:23] neg_lo:[1,0,0] neg_hi:[1,0,0]
	v_pk_fma_f32 v[30:31], v[28:29], v[120:121], v[30:31] neg_lo:[1,0,0] neg_hi:[1,0,0]
	ds_read_b128 v[26:29], v33 offset:26960
	s_waitcnt lgkmcnt(10)
	v_pk_fma_f32 v[22:23], v[34:35], v[122:123], v[22:23] neg_lo:[1,0,0] neg_hi:[1,0,0]
	v_pk_fma_f32 v[30:31], v[36:37], v[124:125], v[30:31] neg_lo:[1,0,0] neg_hi:[1,0,0]
	ds_read_b128 v[34:37], v33 offset:26976
	s_waitcnt lgkmcnt(10)
	v_pk_fma_f32 v[22:23], v[38:39], v[126:127], v[22:23] neg_lo:[1,0,0] neg_hi:[1,0,0]
	v_pk_fma_f32 v[30:31], v[40:41], v[128:129], v[30:31] neg_lo:[1,0,0] neg_hi:[1,0,0]
	ds_read_b128 v[38:41], v33 offset:26992
	s_waitcnt lgkmcnt(10)
	v_pk_fma_f32 v[22:23], v[42:43], v[130:131], v[22:23] neg_lo:[1,0,0] neg_hi:[1,0,0]
	v_pk_fma_f32 v[30:31], v[44:45], v[132:133], v[30:31] neg_lo:[1,0,0] neg_hi:[1,0,0]
	ds_read_b128 v[42:45], v33 offset:27008
	v_cmp_eq_u32_e32 vcc, 37, v152
	v_add_f32_e32 v82, v22, v23
	v_add_f32_e32 v83, v30, v31
	v_add_f32_e32 v134, v82, v83
	v_cvt_pk_bf16_f32 v25, v134, v134
	ds_write_b16 v84, v25 offset:5184
	v_cndmask_b32_e64 v22, 0, 1.0, vcc
	v_mov_b32_e32 v23, 0
	s_waitcnt lgkmcnt(9)
	v_pk_fma_f32 v[22:23], v[0:1], v[98:99], v[22:23] neg_lo:[1,0,0] neg_hi:[1,0,0]
	v_pk_fma_f32 v[30:31], v[2:3], v[100:101], 0 neg_lo:[1,0,0] neg_hi:[1,0,0]
	ds_read_b128 v[0:3], v33 offset:27136
	s_waitcnt lgkmcnt(9)
	v_pk_fma_f32 v[22:23], v[4:5], v[102:103], v[22:23] neg_lo:[1,0,0] neg_hi:[1,0,0]
	v_pk_fma_f32 v[30:31], v[6:7], v[104:105], v[30:31] neg_lo:[1,0,0] neg_hi:[1,0,0]
	ds_read_b128 v[4:7], v33 offset:27152
	s_waitcnt lgkmcnt(9)
	v_pk_fma_f32 v[22:23], v[8:9], v[106:107], v[22:23] neg_lo:[1,0,0] neg_hi:[1,0,0]
	v_pk_fma_f32 v[30:31], v[10:11], v[108:109], v[30:31] neg_lo:[1,0,0] neg_hi:[1,0,0]
	ds_read_b128 v[8:11], v33 offset:27168
	s_waitcnt lgkmcnt(9)
	v_pk_fma_f32 v[22:23], v[12:13], v[110:111], v[22:23] neg_lo:[1,0,0] neg_hi:[1,0,0]
	v_pk_fma_f32 v[30:31], v[14:15], v[112:113], v[30:31] neg_lo:[1,0,0] neg_hi:[1,0,0]
	ds_read_b128 v[12:15], v33 offset:27184
	s_waitcnt lgkmcnt(9)
	v_pk_fma_f32 v[22:23], v[16:17], v[114:115], v[22:23] neg_lo:[1,0,0] neg_hi:[1,0,0]
	v_pk_fma_f32 v[30:31], v[18:19], v[116:117], v[30:31] neg_lo:[1,0,0] neg_hi:[1,0,0]
	ds_read_b128 v[16:19], v33 offset:27200
	s_waitcnt lgkmcnt(9)
	v_pk_fma_f32 v[22:23], v[26:27], v[118:119], v[22:23] neg_lo:[1,0,0] neg_hi:[1,0,0]
	v_pk_fma_f32 v[30:31], v[28:29], v[120:121], v[30:31] neg_lo:[1,0,0] neg_hi:[1,0,0]
	ds_read_b128 v[26:29], v33 offset:27216
	s_waitcnt lgkmcnt(9)
	v_pk_fma_f32 v[22:23], v[34:35], v[122:123], v[22:23] neg_lo:[1,0,0] neg_hi:[1,0,0]
	v_pk_fma_f32 v[30:31], v[36:37], v[124:125], v[30:31] neg_lo:[1,0,0] neg_hi:[1,0,0]
	ds_read_b128 v[34:37], v33 offset:27232
	s_waitcnt lgkmcnt(9)
	v_pk_fma_f32 v[22:23], v[38:39], v[126:127], v[22:23] neg_lo:[1,0,0] neg_hi:[1,0,0]
	v_pk_fma_f32 v[30:31], v[40:41], v[128:129], v[30:31] neg_lo:[1,0,0] neg_hi:[1,0,0]
	ds_read_b128 v[38:41], v33 offset:27248
	s_waitcnt lgkmcnt(9)
	v_pk_fma_f32 v[22:23], v[42:43], v[130:131], v[22:23] neg_lo:[1,0,0] neg_hi:[1,0,0]
	v_pk_fma_f32 v[30:31], v[44:45], v[132:133], v[30:31] neg_lo:[1,0,0] neg_hi:[1,0,0]
	ds_read_b128 v[42:45], v33 offset:27264
	s_waitcnt lgkmcnt(15)
	v_pk_fma_f32 v[22:23], v[46:47], v[134:135], v[22:23] neg_lo:[1,0,0] neg_hi:[1,0,0]
	v_pk_fma_f32 v[30:31], v[48:49], v[136:137], v[30:31] neg_lo:[1,0,0] neg_hi:[1,0,0]
	ds_read_b128 v[46:49], v33 offset:27280
	v_cmp_eq_u32_e32 vcc, 38, v152
	v_add_f32_e32 v82, v22, v23
	v_add_f32_e32 v83, v30, v31
	v_add_f32_e32 v135, v82, v83
	v_cvt_pk_bf16_f32 v25, v135, v135
	ds_write_b16 v84, v25 offset:5328
	v_cndmask_b32_e64 v22, 0, 1.0, vcc
	v_mov_b32_e32 v23, 0
	s_waitcnt lgkmcnt(10)
	v_pk_fma_f32 v[22:23], v[0:1], v[98:99], v[22:23] neg_lo:[1,0,0] neg_hi:[1,0,0]
	v_pk_fma_f32 v[30:31], v[2:3], v[100:101], 0 neg_lo:[1,0,0] neg_hi:[1,0,0]
	ds_read_b128 v[0:3], v33 offset:27392
	s_waitcnt lgkmcnt(10)
	v_pk_fma_f32 v[22:23], v[4:5], v[102:103], v[22:23] neg_lo:[1,0,0] neg_hi:[1,0,0]
	v_pk_fma_f32 v[30:31], v[6:7], v[104:105], v[30:31] neg_lo:[1,0,0] neg_hi:[1,0,0]
	ds_read_b128 v[4:7], v33 offset:27408
	s_waitcnt lgkmcnt(10)
	v_pk_fma_f32 v[22:23], v[8:9], v[106:107], v[22:23] neg_lo:[1,0,0] neg_hi:[1,0,0]
	v_pk_fma_f32 v[30:31], v[10:11], v[108:109], v[30:31] neg_lo:[1,0,0] neg_hi:[1,0,0]
	ds_read_b128 v[8:11], v33 offset:27424
	s_waitcnt lgkmcnt(10)
	v_pk_fma_f32 v[22:23], v[12:13], v[110:111], v[22:23] neg_lo:[1,0,0] neg_hi:[1,0,0]
	v_pk_fma_f32 v[30:31], v[14:15], v[112:113], v[30:31] neg_lo:[1,0,0] neg_hi:[1,0,0]
	ds_read_b128 v[12:15], v33 offset:27440
	s_waitcnt lgkmcnt(10)
	v_pk_fma_f32 v[22:23], v[16:17], v[114:115], v[22:23] neg_lo:[1,0,0] neg_hi:[1,0,0]
	v_pk_fma_f32 v[30:31], v[18:19], v[116:117], v[30:31] neg_lo:[1,0,0] neg_hi:[1,0,0]
	ds_read_b128 v[16:19], v33 offset:27456
	s_waitcnt lgkmcnt(10)
	v_pk_fma_f32 v[22:23], v[26:27], v[118:119], v[22:23] neg_lo:[1,0,0] neg_hi:[1,0,0]
	v_pk_fma_f32 v[30:31], v[28:29], v[120:121], v[30:31] neg_lo:[1,0,0] neg_hi:[1,0,0]
	ds_read_b128 v[26:29], v33 offset:27472
	s_waitcnt lgkmcnt(10)
	v_pk_fma_f32 v[22:23], v[34:35], v[122:123], v[22:23] neg_lo:[1,0,0] neg_hi:[1,0,0]
	v_pk_fma_f32 v[30:31], v[36:37], v[124:125], v[30:31] neg_lo:[1,0,0] neg_hi:[1,0,0]
	ds_read_b128 v[34:37], v33 offset:27488
	s_waitcnt lgkmcnt(10)
	v_pk_fma_f32 v[22:23], v[38:39], v[126:127], v[22:23] neg_lo:[1,0,0] neg_hi:[1,0,0]
	v_pk_fma_f32 v[30:31], v[40:41], v[128:129], v[30:31] neg_lo:[1,0,0] neg_hi:[1,0,0]
	ds_read_b128 v[38:41], v33 offset:27504
	s_waitcnt lgkmcnt(10)
	v_pk_fma_f32 v[22:23], v[42:43], v[130:131], v[22:23] neg_lo:[1,0,0] neg_hi:[1,0,0]
	v_pk_fma_f32 v[30:31], v[44:45], v[132:133], v[30:31] neg_lo:[1,0,0] neg_hi:[1,0,0]
	ds_read_b128 v[42:45], v33 offset:27520
	s_waitcnt lgkmcnt(10)
	v_pk_fma_f32 v[22:23], v[46:47], v[134:135], v[22:23] neg_lo:[1,0,0] neg_hi:[1,0,0]
	v_pk_fma_f32 v[30:31], v[48:49], v[136:137], v[30:31] neg_lo:[1,0,0] neg_hi:[1,0,0]
	ds_read_b128 v[46:49], v33 offset:27536
	v_cmp_eq_u32_e32 vcc, 39, v152
	v_add_f32_e32 v82, v22, v23
	v_add_f32_e32 v83, v30, v31
	v_add_f32_e32 v136, v82, v83
	v_cvt_pk_bf16_f32 v25, v136, v136
	ds_write_b16 v84, v25 offset:5472
	v_cndmask_b32_e64 v22, 0, 1.0, vcc
	v_mov_b32_e32 v23, 0
	s_waitcnt lgkmcnt(10)
	v_pk_fma_f32 v[22:23], v[0:1], v[98:99], v[22:23] neg_lo:[1,0,0] neg_hi:[1,0,0]
	v_pk_fma_f32 v[30:31], v[2:3], v[100:101], 0 neg_lo:[1,0,0] neg_hi:[1,0,0]
	ds_read_b128 v[0:3], v33 offset:27648
	s_waitcnt lgkmcnt(10)
	v_pk_fma_f32 v[22:23], v[4:5], v[102:103], v[22:23] neg_lo:[1,0,0] neg_hi:[1,0,0]
	v_pk_fma_f32 v[30:31], v[6:7], v[104:105], v[30:31] neg_lo:[1,0,0] neg_hi:[1,0,0]
	ds_read_b128 v[4:7], v33 offset:27664
	s_waitcnt lgkmcnt(10)
	v_pk_fma_f32 v[22:23], v[8:9], v[106:107], v[22:23] neg_lo:[1,0,0] neg_hi:[1,0,0]
	v_pk_fma_f32 v[30:31], v[10:11], v[108:109], v[30:31] neg_lo:[1,0,0] neg_hi:[1,0,0]
	ds_read_b128 v[8:11], v33 offset:27680
	s_waitcnt lgkmcnt(10)
	v_pk_fma_f32 v[22:23], v[12:13], v[110:111], v[22:23] neg_lo:[1,0,0] neg_hi:[1,0,0]
	v_pk_fma_f32 v[30:31], v[14:15], v[112:113], v[30:31] neg_lo:[1,0,0] neg_hi:[1,0,0]
	ds_read_b128 v[12:15], v33 offset:27696
	s_waitcnt lgkmcnt(10)
	v_pk_fma_f32 v[22:23], v[16:17], v[114:115], v[22:23] neg_lo:[1,0,0] neg_hi:[1,0,0]
	v_pk_fma_f32 v[30:31], v[18:19], v[116:117], v[30:31] neg_lo:[1,0,0] neg_hi:[1,0,0]
	ds_read_b128 v[16:19], v33 offset:27712
	s_waitcnt lgkmcnt(10)
	v_pk_fma_f32 v[22:23], v[26:27], v[118:119], v[22:23] neg_lo:[1,0,0] neg_hi:[1,0,0]
	v_pk_fma_f32 v[30:31], v[28:29], v[120:121], v[30:31] neg_lo:[1,0,0] neg_hi:[1,0,0]
	ds_read_b128 v[26:29], v33 offset:27728
	s_waitcnt lgkmcnt(10)
	v_pk_fma_f32 v[22:23], v[34:35], v[122:123], v[22:23] neg_lo:[1,0,0] neg_hi:[1,0,0]
	v_pk_fma_f32 v[30:31], v[36:37], v[124:125], v[30:31] neg_lo:[1,0,0] neg_hi:[1,0,0]
	ds_read_b128 v[34:37], v33 offset:27744
	s_waitcnt lgkmcnt(10)
	v_pk_fma_f32 v[22:23], v[38:39], v[126:127], v[22:23] neg_lo:[1,0,0] neg_hi:[1,0,0]
	v_pk_fma_f32 v[30:31], v[40:41], v[128:129], v[30:31] neg_lo:[1,0,0] neg_hi:[1,0,0]
	ds_read_b128 v[38:41], v33 offset:27760
	s_waitcnt lgkmcnt(10)
	v_pk_fma_f32 v[22:23], v[42:43], v[130:131], v[22:23] neg_lo:[1,0,0] neg_hi:[1,0,0]
	v_pk_fma_f32 v[30:31], v[44:45], v[132:133], v[30:31] neg_lo:[1,0,0] neg_hi:[1,0,0]
	ds_read_b128 v[42:45], v33 offset:27776
	s_waitcnt lgkmcnt(10)
	v_pk_fma_f32 v[22:23], v[46:47], v[134:135], v[22:23] neg_lo:[1,0,0] neg_hi:[1,0,0]
	v_pk_fma_f32 v[30:31], v[48:49], v[136:137], v[30:31] neg_lo:[1,0,0] neg_hi:[1,0,0]
	ds_read_b128 v[46:49], v33 offset:27792
	v_cmp_eq_u32_e32 vcc, 40, v152
	v_add_f32_e32 v82, v22, v23
	v_add_f32_e32 v83, v30, v31
	v_add_f32_e32 v137, v82, v83
	v_cvt_pk_bf16_f32 v25, v137, v137
	ds_write_b16 v84, v25 offset:5616
	v_cndmask_b32_e64 v22, 0, 1.0, vcc
	v_mov_b32_e32 v23, 0
	ds_read_b128 v[50:53], v33 offset:28064
	s_waitcnt lgkmcnt(11)
	v_pk_fma_f32 v[22:23], v[0:1], v[98:99], v[22:23] neg_lo:[1,0,0] neg_hi:[1,0,0]
	v_pk_fma_f32 v[30:31], v[2:3], v[100:101], 0 neg_lo:[1,0,0] neg_hi:[1,0,0]
	ds_read_b128 v[0:3], v33 offset:27904
	s_waitcnt lgkmcnt(11)
	v_pk_fma_f32 v[22:23], v[4:5], v[102:103], v[22:23] neg_lo:[1,0,0] neg_hi:[1,0,0]
	v_pk_fma_f32 v[30:31], v[6:7], v[104:105], v[30:31] neg_lo:[1,0,0] neg_hi:[1,0,0]
	ds_read_b128 v[4:7], v33 offset:27920
	s_waitcnt lgkmcnt(11)
	v_pk_fma_f32 v[22:23], v[8:9], v[106:107], v[22:23] neg_lo:[1,0,0] neg_hi:[1,0,0]
	v_pk_fma_f32 v[30:31], v[10:11], v[108:109], v[30:31] neg_lo:[1,0,0] neg_hi:[1,0,0]
	ds_read_b128 v[8:11], v33 offset:27936
	s_waitcnt lgkmcnt(11)
	v_pk_fma_f32 v[22:23], v[12:13], v[110:111], v[22:23] neg_lo:[1,0,0] neg_hi:[1,0,0]
	v_pk_fma_f32 v[30:31], v[14:15], v[112:113], v[30:31] neg_lo:[1,0,0] neg_hi:[1,0,0]
	ds_read_b128 v[12:15], v33 offset:27952
	s_waitcnt lgkmcnt(11)
	v_pk_fma_f32 v[22:23], v[16:17], v[114:115], v[22:23] neg_lo:[1,0,0] neg_hi:[1,0,0]
	v_pk_fma_f32 v[30:31], v[18:19], v[116:117], v[30:31] neg_lo:[1,0,0] neg_hi:[1,0,0]
	ds_read_b128 v[16:19], v33 offset:27968
	s_waitcnt lgkmcnt(11)
	v_pk_fma_f32 v[22:23], v[26:27], v[118:119], v[22:23] neg_lo:[1,0,0] neg_hi:[1,0,0]
	v_pk_fma_f32 v[30:31], v[28:29], v[120:121], v[30:31] neg_lo:[1,0,0] neg_hi:[1,0,0]
	ds_read_b128 v[26:29], v33 offset:27984
	s_waitcnt lgkmcnt(11)
	v_pk_fma_f32 v[22:23], v[34:35], v[122:123], v[22:23] neg_lo:[1,0,0] neg_hi:[1,0,0]
	v_pk_fma_f32 v[30:31], v[36:37], v[124:125], v[30:31] neg_lo:[1,0,0] neg_hi:[1,0,0]
	ds_read_b128 v[34:37], v33 offset:28000
	s_waitcnt lgkmcnt(11)
	v_pk_fma_f32 v[22:23], v[38:39], v[126:127], v[22:23] neg_lo:[1,0,0] neg_hi:[1,0,0]
	v_pk_fma_f32 v[30:31], v[40:41], v[128:129], v[30:31] neg_lo:[1,0,0] neg_hi:[1,0,0]
	ds_read_b128 v[38:41], v33 offset:28016
	s_waitcnt lgkmcnt(11)
	v_pk_fma_f32 v[22:23], v[42:43], v[130:131], v[22:23] neg_lo:[1,0,0] neg_hi:[1,0,0]
	v_pk_fma_f32 v[30:31], v[44:45], v[132:133], v[30:31] neg_lo:[1,0,0] neg_hi:[1,0,0]
	ds_read_b128 v[42:45], v33 offset:28032
	s_waitcnt lgkmcnt(11)
	v_pk_fma_f32 v[22:23], v[46:47], v[134:135], v[22:23] neg_lo:[1,0,0] neg_hi:[1,0,0]
	v_pk_fma_f32 v[30:31], v[48:49], v[136:137], v[30:31] neg_lo:[1,0,0] neg_hi:[1,0,0]
	ds_read_b128 v[46:49], v33 offset:28048
	v_cmp_eq_u32_e32 vcc, 41, v152
	v_add_f32_e32 v82, v22, v23
	v_add_f32_e32 v83, v30, v31
	v_add_f32_e32 v138, v82, v83
	v_cvt_pk_bf16_f32 v25, v138, v138
	ds_write_b16 v84, v25 offset:5760
	v_cndmask_b32_e64 v22, 0, 1.0, vcc
	v_mov_b32_e32 v23, 0
	s_waitcnt lgkmcnt(10)
	v_pk_fma_f32 v[22:23], v[0:1], v[98:99], v[22:23] neg_lo:[1,0,0] neg_hi:[1,0,0]
	v_pk_fma_f32 v[30:31], v[2:3], v[100:101], 0 neg_lo:[1,0,0] neg_hi:[1,0,0]
	ds_read_b128 v[0:3], v33 offset:28160
	s_waitcnt lgkmcnt(10)
	v_pk_fma_f32 v[22:23], v[4:5], v[102:103], v[22:23] neg_lo:[1,0,0] neg_hi:[1,0,0]
	v_pk_fma_f32 v[30:31], v[6:7], v[104:105], v[30:31] neg_lo:[1,0,0] neg_hi:[1,0,0]
	ds_read_b128 v[4:7], v33 offset:28176
	s_waitcnt lgkmcnt(10)
	v_pk_fma_f32 v[22:23], v[8:9], v[106:107], v[22:23] neg_lo:[1,0,0] neg_hi:[1,0,0]
	v_pk_fma_f32 v[30:31], v[10:11], v[108:109], v[30:31] neg_lo:[1,0,0] neg_hi:[1,0,0]
	ds_read_b128 v[8:11], v33 offset:28192
	s_waitcnt lgkmcnt(10)
	v_pk_fma_f32 v[22:23], v[12:13], v[110:111], v[22:23] neg_lo:[1,0,0] neg_hi:[1,0,0]
	v_pk_fma_f32 v[30:31], v[14:15], v[112:113], v[30:31] neg_lo:[1,0,0] neg_hi:[1,0,0]
	ds_read_b128 v[12:15], v33 offset:28208
	s_waitcnt lgkmcnt(10)
	v_pk_fma_f32 v[22:23], v[16:17], v[114:115], v[22:23] neg_lo:[1,0,0] neg_hi:[1,0,0]
	v_pk_fma_f32 v[30:31], v[18:19], v[116:117], v[30:31] neg_lo:[1,0,0] neg_hi:[1,0,0]
	ds_read_b128 v[16:19], v33 offset:28224
	s_waitcnt lgkmcnt(10)
	v_pk_fma_f32 v[22:23], v[26:27], v[118:119], v[22:23] neg_lo:[1,0,0] neg_hi:[1,0,0]
	v_pk_fma_f32 v[30:31], v[28:29], v[120:121], v[30:31] neg_lo:[1,0,0] neg_hi:[1,0,0]
	ds_read_b128 v[26:29], v33 offset:28240
	s_waitcnt lgkmcnt(10)
	v_pk_fma_f32 v[22:23], v[34:35], v[122:123], v[22:23] neg_lo:[1,0,0] neg_hi:[1,0,0]
	v_pk_fma_f32 v[30:31], v[36:37], v[124:125], v[30:31] neg_lo:[1,0,0] neg_hi:[1,0,0]
	ds_read_b128 v[34:37], v33 offset:28256
	s_waitcnt lgkmcnt(10)
	v_pk_fma_f32 v[22:23], v[38:39], v[126:127], v[22:23] neg_lo:[1,0,0] neg_hi:[1,0,0]
	v_pk_fma_f32 v[30:31], v[40:41], v[128:129], v[30:31] neg_lo:[1,0,0] neg_hi:[1,0,0]
	ds_read_b128 v[38:41], v33 offset:28272
	s_waitcnt lgkmcnt(10)
	v_pk_fma_f32 v[22:23], v[42:43], v[130:131], v[22:23] neg_lo:[1,0,0] neg_hi:[1,0,0]
	v_pk_fma_f32 v[30:31], v[44:45], v[132:133], v[30:31] neg_lo:[1,0,0] neg_hi:[1,0,0]
	ds_read_b128 v[42:45], v33 offset:28288
	s_waitcnt lgkmcnt(10)
	v_pk_fma_f32 v[22:23], v[46:47], v[134:135], v[22:23] neg_lo:[1,0,0] neg_hi:[1,0,0]
	v_pk_fma_f32 v[30:31], v[48:49], v[136:137], v[30:31] neg_lo:[1,0,0] neg_hi:[1,0,0]
	ds_read_b128 v[46:49], v33 offset:28304
	s_waitcnt lgkmcnt(15)
	v_pk_fma_f32 v[22:23], v[50:51], v[138:139], v[22:23] neg_lo:[1,0,0] neg_hi:[1,0,0]
	v_pk_fma_f32 v[30:31], v[52:53], v[140:141], v[30:31] neg_lo:[1,0,0] neg_hi:[1,0,0]
	ds_read_b128 v[50:53], v33 offset:28320
	v_cmp_eq_u32_e32 vcc, 42, v152
	v_add_f32_e32 v82, v22, v23
	v_add_f32_e32 v83, v30, v31
	v_add_f32_e32 v139, v82, v83
	v_cvt_pk_bf16_f32 v25, v139, v139
	ds_write_b16 v84, v25 offset:5904
	v_cndmask_b32_e64 v22, 0, 1.0, vcc
	v_mov_b32_e32 v23, 0
	s_waitcnt lgkmcnt(11)
	v_pk_fma_f32 v[22:23], v[0:1], v[98:99], v[22:23] neg_lo:[1,0,0] neg_hi:[1,0,0]
	v_pk_fma_f32 v[30:31], v[2:3], v[100:101], 0 neg_lo:[1,0,0] neg_hi:[1,0,0]
	ds_read_b128 v[0:3], v33 offset:28416
	s_waitcnt lgkmcnt(11)
	v_pk_fma_f32 v[22:23], v[4:5], v[102:103], v[22:23] neg_lo:[1,0,0] neg_hi:[1,0,0]
	v_pk_fma_f32 v[30:31], v[6:7], v[104:105], v[30:31] neg_lo:[1,0,0] neg_hi:[1,0,0]
	ds_read_b128 v[4:7], v33 offset:28432
	s_waitcnt lgkmcnt(11)
	v_pk_fma_f32 v[22:23], v[8:9], v[106:107], v[22:23] neg_lo:[1,0,0] neg_hi:[1,0,0]
	v_pk_fma_f32 v[30:31], v[10:11], v[108:109], v[30:31] neg_lo:[1,0,0] neg_hi:[1,0,0]
	ds_read_b128 v[8:11], v33 offset:28448
	s_waitcnt lgkmcnt(11)
	v_pk_fma_f32 v[22:23], v[12:13], v[110:111], v[22:23] neg_lo:[1,0,0] neg_hi:[1,0,0]
	v_pk_fma_f32 v[30:31], v[14:15], v[112:113], v[30:31] neg_lo:[1,0,0] neg_hi:[1,0,0]
	ds_read_b128 v[12:15], v33 offset:28464
	s_waitcnt lgkmcnt(11)
	v_pk_fma_f32 v[22:23], v[16:17], v[114:115], v[22:23] neg_lo:[1,0,0] neg_hi:[1,0,0]
	v_pk_fma_f32 v[30:31], v[18:19], v[116:117], v[30:31] neg_lo:[1,0,0] neg_hi:[1,0,0]
	ds_read_b128 v[16:19], v33 offset:28480
	s_waitcnt lgkmcnt(11)
	v_pk_fma_f32 v[22:23], v[26:27], v[118:119], v[22:23] neg_lo:[1,0,0] neg_hi:[1,0,0]
	v_pk_fma_f32 v[30:31], v[28:29], v[120:121], v[30:31] neg_lo:[1,0,0] neg_hi:[1,0,0]
	ds_read_b128 v[26:29], v33 offset:28496
	s_waitcnt lgkmcnt(11)
	v_pk_fma_f32 v[22:23], v[34:35], v[122:123], v[22:23] neg_lo:[1,0,0] neg_hi:[1,0,0]
	v_pk_fma_f32 v[30:31], v[36:37], v[124:125], v[30:31] neg_lo:[1,0,0] neg_hi:[1,0,0]
	ds_read_b128 v[34:37], v33 offset:28512
	s_waitcnt lgkmcnt(11)
	v_pk_fma_f32 v[22:23], v[38:39], v[126:127], v[22:23] neg_lo:[1,0,0] neg_hi:[1,0,0]
	v_pk_fma_f32 v[30:31], v[40:41], v[128:129], v[30:31] neg_lo:[1,0,0] neg_hi:[1,0,0]
	ds_read_b128 v[38:41], v33 offset:28528
	s_waitcnt lgkmcnt(11)
	v_pk_fma_f32 v[22:23], v[42:43], v[130:131], v[22:23] neg_lo:[1,0,0] neg_hi:[1,0,0]
	v_pk_fma_f32 v[30:31], v[44:45], v[132:133], v[30:31] neg_lo:[1,0,0] neg_hi:[1,0,0]
	ds_read_b128 v[42:45], v33 offset:28544
	s_waitcnt lgkmcnt(11)
	v_pk_fma_f32 v[22:23], v[46:47], v[134:135], v[22:23] neg_lo:[1,0,0] neg_hi:[1,0,0]
	v_pk_fma_f32 v[30:31], v[48:49], v[136:137], v[30:31] neg_lo:[1,0,0] neg_hi:[1,0,0]
	ds_read_b128 v[46:49], v33 offset:28560
	s_waitcnt lgkmcnt(11)
	v_pk_fma_f32 v[22:23], v[50:51], v[138:139], v[22:23] neg_lo:[1,0,0] neg_hi:[1,0,0]
	v_pk_fma_f32 v[30:31], v[52:53], v[140:141], v[30:31] neg_lo:[1,0,0] neg_hi:[1,0,0]
	ds_read_b128 v[50:53], v33 offset:28576
	v_cmp_eq_u32_e32 vcc, 43, v152
	v_add_f32_e32 v82, v22, v23
	v_add_f32_e32 v83, v30, v31
	v_add_f32_e32 v140, v82, v83
	v_cvt_pk_bf16_f32 v25, v140, v140
	ds_write_b16 v84, v25 offset:6048
	v_cndmask_b32_e64 v22, 0, 1.0, vcc
	v_mov_b32_e32 v23, 0
	s_waitcnt lgkmcnt(11)
	v_pk_fma_f32 v[22:23], v[0:1], v[98:99], v[22:23] neg_lo:[1,0,0] neg_hi:[1,0,0]
	v_pk_fma_f32 v[30:31], v[2:3], v[100:101], 0 neg_lo:[1,0,0] neg_hi:[1,0,0]
	ds_read_b128 v[0:3], v33 offset:28672
	s_waitcnt lgkmcnt(11)
	v_pk_fma_f32 v[22:23], v[4:5], v[102:103], v[22:23] neg_lo:[1,0,0] neg_hi:[1,0,0]
	v_pk_fma_f32 v[30:31], v[6:7], v[104:105], v[30:31] neg_lo:[1,0,0] neg_hi:[1,0,0]
	ds_read_b128 v[4:7], v33 offset:28688
	s_waitcnt lgkmcnt(11)
	v_pk_fma_f32 v[22:23], v[8:9], v[106:107], v[22:23] neg_lo:[1,0,0] neg_hi:[1,0,0]
	v_pk_fma_f32 v[30:31], v[10:11], v[108:109], v[30:31] neg_lo:[1,0,0] neg_hi:[1,0,0]
	ds_read_b128 v[8:11], v33 offset:28704
	s_waitcnt lgkmcnt(11)
	v_pk_fma_f32 v[22:23], v[12:13], v[110:111], v[22:23] neg_lo:[1,0,0] neg_hi:[1,0,0]
	v_pk_fma_f32 v[30:31], v[14:15], v[112:113], v[30:31] neg_lo:[1,0,0] neg_hi:[1,0,0]
	ds_read_b128 v[12:15], v33 offset:28720
	s_waitcnt lgkmcnt(11)
	v_pk_fma_f32 v[22:23], v[16:17], v[114:115], v[22:23] neg_lo:[1,0,0] neg_hi:[1,0,0]
	v_pk_fma_f32 v[30:31], v[18:19], v[116:117], v[30:31] neg_lo:[1,0,0] neg_hi:[1,0,0]
	ds_read_b128 v[16:19], v33 offset:28736
	s_waitcnt lgkmcnt(11)
	v_pk_fma_f32 v[22:23], v[26:27], v[118:119], v[22:23] neg_lo:[1,0,0] neg_hi:[1,0,0]
	v_pk_fma_f32 v[30:31], v[28:29], v[120:121], v[30:31] neg_lo:[1,0,0] neg_hi:[1,0,0]
	ds_read_b128 v[26:29], v33 offset:28752
	s_waitcnt lgkmcnt(11)
	v_pk_fma_f32 v[22:23], v[34:35], v[122:123], v[22:23] neg_lo:[1,0,0] neg_hi:[1,0,0]
	v_pk_fma_f32 v[30:31], v[36:37], v[124:125], v[30:31] neg_lo:[1,0,0] neg_hi:[1,0,0]
	ds_read_b128 v[34:37], v33 offset:28768
	s_waitcnt lgkmcnt(11)
	v_pk_fma_f32 v[22:23], v[38:39], v[126:127], v[22:23] neg_lo:[1,0,0] neg_hi:[1,0,0]
	v_pk_fma_f32 v[30:31], v[40:41], v[128:129], v[30:31] neg_lo:[1,0,0] neg_hi:[1,0,0]
	ds_read_b128 v[38:41], v33 offset:28784
	s_waitcnt lgkmcnt(11)
	v_pk_fma_f32 v[22:23], v[42:43], v[130:131], v[22:23] neg_lo:[1,0,0] neg_hi:[1,0,0]
	v_pk_fma_f32 v[30:31], v[44:45], v[132:133], v[30:31] neg_lo:[1,0,0] neg_hi:[1,0,0]
	ds_read_b128 v[42:45], v33 offset:28800
	s_waitcnt lgkmcnt(11)
	v_pk_fma_f32 v[22:23], v[46:47], v[134:135], v[22:23] neg_lo:[1,0,0] neg_hi:[1,0,0]
	v_pk_fma_f32 v[30:31], v[48:49], v[136:137], v[30:31] neg_lo:[1,0,0] neg_hi:[1,0,0]
	ds_read_b128 v[46:49], v33 offset:28816
	s_waitcnt lgkmcnt(11)
	v_pk_fma_f32 v[22:23], v[50:51], v[138:139], v[22:23] neg_lo:[1,0,0] neg_hi:[1,0,0]
	v_pk_fma_f32 v[30:31], v[52:53], v[140:141], v[30:31] neg_lo:[1,0,0] neg_hi:[1,0,0]
	ds_read_b128 v[50:53], v33 offset:28832
	v_cmp_eq_u32_e32 vcc, 44, v152
	v_add_f32_e32 v82, v22, v23
	v_add_f32_e32 v83, v30, v31
	v_add_f32_e32 v141, v82, v83
	v_cvt_pk_bf16_f32 v25, v141, v141
	ds_write_b16 v84, v25 offset:6192
	v_cndmask_b32_e64 v22, 0, 1.0, vcc
	v_mov_b32_e32 v23, 0
	ds_read_b128 v[54:57], v33 offset:29104
	s_waitcnt lgkmcnt(12)
	v_pk_fma_f32 v[22:23], v[0:1], v[98:99], v[22:23] neg_lo:[1,0,0] neg_hi:[1,0,0]
	v_pk_fma_f32 v[30:31], v[2:3], v[100:101], 0 neg_lo:[1,0,0] neg_hi:[1,0,0]
	ds_read_b128 v[0:3], v33 offset:28928
	s_waitcnt lgkmcnt(12)
	v_pk_fma_f32 v[22:23], v[4:5], v[102:103], v[22:23] neg_lo:[1,0,0] neg_hi:[1,0,0]
	v_pk_fma_f32 v[30:31], v[6:7], v[104:105], v[30:31] neg_lo:[1,0,0] neg_hi:[1,0,0]
	ds_read_b128 v[4:7], v33 offset:28944
	s_waitcnt lgkmcnt(12)
	v_pk_fma_f32 v[22:23], v[8:9], v[106:107], v[22:23] neg_lo:[1,0,0] neg_hi:[1,0,0]
	v_pk_fma_f32 v[30:31], v[10:11], v[108:109], v[30:31] neg_lo:[1,0,0] neg_hi:[1,0,0]
	ds_read_b128 v[8:11], v33 offset:28960
	s_waitcnt lgkmcnt(12)
	v_pk_fma_f32 v[22:23], v[12:13], v[110:111], v[22:23] neg_lo:[1,0,0] neg_hi:[1,0,0]
	v_pk_fma_f32 v[30:31], v[14:15], v[112:113], v[30:31] neg_lo:[1,0,0] neg_hi:[1,0,0]
	ds_read_b128 v[12:15], v33 offset:28976
	s_waitcnt lgkmcnt(12)
	v_pk_fma_f32 v[22:23], v[16:17], v[114:115], v[22:23] neg_lo:[1,0,0] neg_hi:[1,0,0]
	v_pk_fma_f32 v[30:31], v[18:19], v[116:117], v[30:31] neg_lo:[1,0,0] neg_hi:[1,0,0]
	ds_read_b128 v[16:19], v33 offset:28992
	s_waitcnt lgkmcnt(12)
	v_pk_fma_f32 v[22:23], v[26:27], v[118:119], v[22:23] neg_lo:[1,0,0] neg_hi:[1,0,0]
	v_pk_fma_f32 v[30:31], v[28:29], v[120:121], v[30:31] neg_lo:[1,0,0] neg_hi:[1,0,0]
	ds_read_b128 v[26:29], v33 offset:29008
	s_waitcnt lgkmcnt(12)
	v_pk_fma_f32 v[22:23], v[34:35], v[122:123], v[22:23] neg_lo:[1,0,0] neg_hi:[1,0,0]
	v_pk_fma_f32 v[30:31], v[36:37], v[124:125], v[30:31] neg_lo:[1,0,0] neg_hi:[1,0,0]
	ds_read_b128 v[34:37], v33 offset:29024
	s_waitcnt lgkmcnt(12)
	v_pk_fma_f32 v[22:23], v[38:39], v[126:127], v[22:23] neg_lo:[1,0,0] neg_hi:[1,0,0]
	v_pk_fma_f32 v[30:31], v[40:41], v[128:129], v[30:31] neg_lo:[1,0,0] neg_hi:[1,0,0]
	ds_read_b128 v[38:41], v33 offset:29040
	s_waitcnt lgkmcnt(12)
	v_pk_fma_f32 v[22:23], v[42:43], v[130:131], v[22:23] neg_lo:[1,0,0] neg_hi:[1,0,0]
	v_pk_fma_f32 v[30:31], v[44:45], v[132:133], v[30:31] neg_lo:[1,0,0] neg_hi:[1,0,0]
	ds_read_b128 v[42:45], v33 offset:29056
	s_waitcnt lgkmcnt(12)
	v_pk_fma_f32 v[22:23], v[46:47], v[134:135], v[22:23] neg_lo:[1,0,0] neg_hi:[1,0,0]
	v_pk_fma_f32 v[30:31], v[48:49], v[136:137], v[30:31] neg_lo:[1,0,0] neg_hi:[1,0,0]
	ds_read_b128 v[46:49], v33 offset:29072
	s_waitcnt lgkmcnt(12)
	v_pk_fma_f32 v[22:23], v[50:51], v[138:139], v[22:23] neg_lo:[1,0,0] neg_hi:[1,0,0]
	v_pk_fma_f32 v[30:31], v[52:53], v[140:141], v[30:31] neg_lo:[1,0,0] neg_hi:[1,0,0]
	ds_read_b128 v[50:53], v33 offset:29088
	v_cmp_eq_u32_e32 vcc, 45, v152
	v_add_f32_e32 v82, v22, v23
	v_add_f32_e32 v83, v30, v31
	v_add_f32_e32 v142, v82, v83
	v_cvt_pk_bf16_f32 v25, v142, v142
	ds_write_b16 v84, v25 offset:6336
	v_cndmask_b32_e64 v22, 0, 1.0, vcc
	v_mov_b32_e32 v23, 0
	s_waitcnt lgkmcnt(11)
	v_pk_fma_f32 v[22:23], v[0:1], v[98:99], v[22:23] neg_lo:[1,0,0] neg_hi:[1,0,0]
	v_pk_fma_f32 v[30:31], v[2:3], v[100:101], 0 neg_lo:[1,0,0] neg_hi:[1,0,0]
	ds_read_b128 v[0:3], v33 offset:29184
	s_waitcnt lgkmcnt(11)
	v_pk_fma_f32 v[22:23], v[4:5], v[102:103], v[22:23] neg_lo:[1,0,0] neg_hi:[1,0,0]
	v_pk_fma_f32 v[30:31], v[6:7], v[104:105], v[30:31] neg_lo:[1,0,0] neg_hi:[1,0,0]
	ds_read_b128 v[4:7], v33 offset:29200
	s_waitcnt lgkmcnt(11)
	v_pk_fma_f32 v[22:23], v[8:9], v[106:107], v[22:23] neg_lo:[1,0,0] neg_hi:[1,0,0]
	v_pk_fma_f32 v[30:31], v[10:11], v[108:109], v[30:31] neg_lo:[1,0,0] neg_hi:[1,0,0]
	ds_read_b128 v[8:11], v33 offset:29216
	s_waitcnt lgkmcnt(11)
	v_pk_fma_f32 v[22:23], v[12:13], v[110:111], v[22:23] neg_lo:[1,0,0] neg_hi:[1,0,0]
	v_pk_fma_f32 v[30:31], v[14:15], v[112:113], v[30:31] neg_lo:[1,0,0] neg_hi:[1,0,0]
	ds_read_b128 v[12:15], v33 offset:29232
	s_waitcnt lgkmcnt(11)
	v_pk_fma_f32 v[22:23], v[16:17], v[114:115], v[22:23] neg_lo:[1,0,0] neg_hi:[1,0,0]
	v_pk_fma_f32 v[30:31], v[18:19], v[116:117], v[30:31] neg_lo:[1,0,0] neg_hi:[1,0,0]
	ds_read_b128 v[16:19], v33 offset:29248
	s_waitcnt lgkmcnt(11)
	v_pk_fma_f32 v[22:23], v[26:27], v[118:119], v[22:23] neg_lo:[1,0,0] neg_hi:[1,0,0]
	v_pk_fma_f32 v[30:31], v[28:29], v[120:121], v[30:31] neg_lo:[1,0,0] neg_hi:[1,0,0]
	ds_read_b128 v[26:29], v33 offset:29264
	s_waitcnt lgkmcnt(11)
	v_pk_fma_f32 v[22:23], v[34:35], v[122:123], v[22:23] neg_lo:[1,0,0] neg_hi:[1,0,0]
	v_pk_fma_f32 v[30:31], v[36:37], v[124:125], v[30:31] neg_lo:[1,0,0] neg_hi:[1,0,0]
	ds_read_b128 v[34:37], v33 offset:29280
	s_waitcnt lgkmcnt(11)
	v_pk_fma_f32 v[22:23], v[38:39], v[126:127], v[22:23] neg_lo:[1,0,0] neg_hi:[1,0,0]
	v_pk_fma_f32 v[30:31], v[40:41], v[128:129], v[30:31] neg_lo:[1,0,0] neg_hi:[1,0,0]
	ds_read_b128 v[38:41], v33 offset:29296
	s_waitcnt lgkmcnt(11)
	v_pk_fma_f32 v[22:23], v[42:43], v[130:131], v[22:23] neg_lo:[1,0,0] neg_hi:[1,0,0]
	v_pk_fma_f32 v[30:31], v[44:45], v[132:133], v[30:31] neg_lo:[1,0,0] neg_hi:[1,0,0]
	ds_read_b128 v[42:45], v33 offset:29312
	s_waitcnt lgkmcnt(11)
	v_pk_fma_f32 v[22:23], v[46:47], v[134:135], v[22:23] neg_lo:[1,0,0] neg_hi:[1,0,0]
	v_pk_fma_f32 v[30:31], v[48:49], v[136:137], v[30:31] neg_lo:[1,0,0] neg_hi:[1,0,0]
	ds_read_b128 v[46:49], v33 offset:29328
	s_waitcnt lgkmcnt(11)
	v_pk_fma_f32 v[22:23], v[50:51], v[138:139], v[22:23] neg_lo:[1,0,0] neg_hi:[1,0,0]
	v_pk_fma_f32 v[30:31], v[52:53], v[140:141], v[30:31] neg_lo:[1,0,0] neg_hi:[1,0,0]
	ds_read_b128 v[50:53], v33 offset:29344
	s_waitcnt lgkmcnt(15)
	v_pk_fma_f32 v[22:23], v[54:55], v[142:143], v[22:23] neg_lo:[1,0,0] neg_hi:[1,0,0]
	v_pk_fma_f32 v[30:31], v[56:57], v[162:163], v[30:31] neg_lo:[1,0,0] neg_hi:[1,0,0]
	ds_read_b128 v[54:57], v33 offset:29360
	v_cmp_eq_u32_e32 vcc, 46, v152
	v_add_f32_e32 v82, v22, v23
	v_add_f32_e32 v83, v30, v31
	v_add_f32_e32 v143, v82, v83
	v_cvt_pk_bf16_f32 v25, v143, v143
	ds_write_b16 v84, v25 offset:6480
	v_cndmask_b32_e64 v22, 0, 1.0, vcc
	v_mov_b32_e32 v23, 0
	s_waitcnt lgkmcnt(12)
	v_pk_fma_f32 v[22:23], v[0:1], v[98:99], v[22:23] neg_lo:[1,0,0] neg_hi:[1,0,0]
	v_pk_fma_f32 v[30:31], v[2:3], v[100:101], 0 neg_lo:[1,0,0] neg_hi:[1,0,0]
	ds_read_b128 v[0:3], v33 offset:29440
	s_waitcnt lgkmcnt(12)
	v_pk_fma_f32 v[22:23], v[4:5], v[102:103], v[22:23] neg_lo:[1,0,0] neg_hi:[1,0,0]
	v_pk_fma_f32 v[30:31], v[6:7], v[104:105], v[30:31] neg_lo:[1,0,0] neg_hi:[1,0,0]
	ds_read_b128 v[4:7], v33 offset:29456
	s_waitcnt lgkmcnt(12)
	v_pk_fma_f32 v[22:23], v[8:9], v[106:107], v[22:23] neg_lo:[1,0,0] neg_hi:[1,0,0]
	v_pk_fma_f32 v[30:31], v[10:11], v[108:109], v[30:31] neg_lo:[1,0,0] neg_hi:[1,0,0]
	ds_read_b128 v[8:11], v33 offset:29472
	s_waitcnt lgkmcnt(12)
	v_pk_fma_f32 v[22:23], v[12:13], v[110:111], v[22:23] neg_lo:[1,0,0] neg_hi:[1,0,0]
	v_pk_fma_f32 v[30:31], v[14:15], v[112:113], v[30:31] neg_lo:[1,0,0] neg_hi:[1,0,0]
	ds_read_b128 v[12:15], v33 offset:29488
	s_waitcnt lgkmcnt(12)
	v_pk_fma_f32 v[22:23], v[16:17], v[114:115], v[22:23] neg_lo:[1,0,0] neg_hi:[1,0,0]
	v_pk_fma_f32 v[30:31], v[18:19], v[116:117], v[30:31] neg_lo:[1,0,0] neg_hi:[1,0,0]
	ds_read_b128 v[16:19], v33 offset:29504
	s_waitcnt lgkmcnt(12)
	v_pk_fma_f32 v[22:23], v[26:27], v[118:119], v[22:23] neg_lo:[1,0,0] neg_hi:[1,0,0]
	v_pk_fma_f32 v[30:31], v[28:29], v[120:121], v[30:31] neg_lo:[1,0,0] neg_hi:[1,0,0]
	ds_read_b128 v[26:29], v33 offset:29520
	s_waitcnt lgkmcnt(12)
	v_pk_fma_f32 v[22:23], v[34:35], v[122:123], v[22:23] neg_lo:[1,0,0] neg_hi:[1,0,0]
	v_pk_fma_f32 v[30:31], v[36:37], v[124:125], v[30:31] neg_lo:[1,0,0] neg_hi:[1,0,0]
	ds_read_b128 v[34:37], v33 offset:29536
	s_waitcnt lgkmcnt(12)
	v_pk_fma_f32 v[22:23], v[38:39], v[126:127], v[22:23] neg_lo:[1,0,0] neg_hi:[1,0,0]
	v_pk_fma_f32 v[30:31], v[40:41], v[128:129], v[30:31] neg_lo:[1,0,0] neg_hi:[1,0,0]
	ds_read_b128 v[38:41], v33 offset:29552
	s_waitcnt lgkmcnt(12)
	v_pk_fma_f32 v[22:23], v[42:43], v[130:131], v[22:23] neg_lo:[1,0,0] neg_hi:[1,0,0]
	v_pk_fma_f32 v[30:31], v[44:45], v[132:133], v[30:31] neg_lo:[1,0,0] neg_hi:[1,0,0]
	ds_read_b128 v[42:45], v33 offset:29568
	s_waitcnt lgkmcnt(12)
	v_pk_fma_f32 v[22:23], v[46:47], v[134:135], v[22:23] neg_lo:[1,0,0] neg_hi:[1,0,0]
	v_pk_fma_f32 v[30:31], v[48:49], v[136:137], v[30:31] neg_lo:[1,0,0] neg_hi:[1,0,0]
	ds_read_b128 v[46:49], v33 offset:29584
	s_waitcnt lgkmcnt(12)
	v_pk_fma_f32 v[22:23], v[50:51], v[138:139], v[22:23] neg_lo:[1,0,0] neg_hi:[1,0,0]
	v_pk_fma_f32 v[30:31], v[52:53], v[140:141], v[30:31] neg_lo:[1,0,0] neg_hi:[1,0,0]
	ds_read_b128 v[50:53], v33 offset:29600
	s_waitcnt lgkmcnt(12)
	v_pk_fma_f32 v[22:23], v[54:55], v[142:143], v[22:23] neg_lo:[1,0,0] neg_hi:[1,0,0]
	v_pk_fma_f32 v[30:31], v[56:57], v[162:163], v[30:31] neg_lo:[1,0,0] neg_hi:[1,0,0]
	ds_read_b128 v[54:57], v33 offset:29616
	v_cmp_eq_u32_e32 vcc, 47, v152
	v_add_f32_e32 v82, v22, v23
	v_add_f32_e32 v83, v30, v31
	v_add_f32_e32 v162, v82, v83
	v_cvt_pk_bf16_f32 v25, v162, v162
	ds_write_b16 v84, v25 offset:6624
	v_cndmask_b32_e64 v22, 0, 1.0, vcc
	v_mov_b32_e32 v23, 0
	s_waitcnt lgkmcnt(12)
	v_pk_fma_f32 v[22:23], v[0:1], v[98:99], v[22:23] neg_lo:[1,0,0] neg_hi:[1,0,0]
	v_pk_fma_f32 v[30:31], v[2:3], v[100:101], 0 neg_lo:[1,0,0] neg_hi:[1,0,0]
	ds_read_b128 v[0:3], v33 offset:29696
	s_waitcnt lgkmcnt(12)
	v_pk_fma_f32 v[22:23], v[4:5], v[102:103], v[22:23] neg_lo:[1,0,0] neg_hi:[1,0,0]
	v_pk_fma_f32 v[30:31], v[6:7], v[104:105], v[30:31] neg_lo:[1,0,0] neg_hi:[1,0,0]
	ds_read_b128 v[4:7], v33 offset:29712
	s_waitcnt lgkmcnt(12)
	v_pk_fma_f32 v[22:23], v[8:9], v[106:107], v[22:23] neg_lo:[1,0,0] neg_hi:[1,0,0]
	v_pk_fma_f32 v[30:31], v[10:11], v[108:109], v[30:31] neg_lo:[1,0,0] neg_hi:[1,0,0]
	ds_read_b128 v[8:11], v33 offset:29728
	s_waitcnt lgkmcnt(12)
	v_pk_fma_f32 v[22:23], v[12:13], v[110:111], v[22:23] neg_lo:[1,0,0] neg_hi:[1,0,0]
	v_pk_fma_f32 v[30:31], v[14:15], v[112:113], v[30:31] neg_lo:[1,0,0] neg_hi:[1,0,0]
	ds_read_b128 v[12:15], v33 offset:29744
	s_waitcnt lgkmcnt(12)
	v_pk_fma_f32 v[22:23], v[16:17], v[114:115], v[22:23] neg_lo:[1,0,0] neg_hi:[1,0,0]
	v_pk_fma_f32 v[30:31], v[18:19], v[116:117], v[30:31] neg_lo:[1,0,0] neg_hi:[1,0,0]
	ds_read_b128 v[16:19], v33 offset:29760
	s_waitcnt lgkmcnt(12)
	v_pk_fma_f32 v[22:23], v[26:27], v[118:119], v[22:23] neg_lo:[1,0,0] neg_hi:[1,0,0]
	v_pk_fma_f32 v[30:31], v[28:29], v[120:121], v[30:31] neg_lo:[1,0,0] neg_hi:[1,0,0]
	ds_read_b128 v[26:29], v33 offset:29776
	s_waitcnt lgkmcnt(12)
	v_pk_fma_f32 v[22:23], v[34:35], v[122:123], v[22:23] neg_lo:[1,0,0] neg_hi:[1,0,0]
	v_pk_fma_f32 v[30:31], v[36:37], v[124:125], v[30:31] neg_lo:[1,0,0] neg_hi:[1,0,0]
	ds_read_b128 v[34:37], v33 offset:29792
	s_waitcnt lgkmcnt(12)
	v_pk_fma_f32 v[22:23], v[38:39], v[126:127], v[22:23] neg_lo:[1,0,0] neg_hi:[1,0,0]
	v_pk_fma_f32 v[30:31], v[40:41], v[128:129], v[30:31] neg_lo:[1,0,0] neg_hi:[1,0,0]
	ds_read_b128 v[38:41], v33 offset:29808
	s_waitcnt lgkmcnt(12)
	v_pk_fma_f32 v[22:23], v[42:43], v[130:131], v[22:23] neg_lo:[1,0,0] neg_hi:[1,0,0]
	v_pk_fma_f32 v[30:31], v[44:45], v[132:133], v[30:31] neg_lo:[1,0,0] neg_hi:[1,0,0]
	ds_read_b128 v[42:45], v33 offset:29824
	s_waitcnt lgkmcnt(12)
	v_pk_fma_f32 v[22:23], v[46:47], v[134:135], v[22:23] neg_lo:[1,0,0] neg_hi:[1,0,0]
	v_pk_fma_f32 v[30:31], v[48:49], v[136:137], v[30:31] neg_lo:[1,0,0] neg_hi:[1,0,0]
	ds_read_b128 v[46:49], v33 offset:29840
	s_waitcnt lgkmcnt(12)
	v_pk_fma_f32 v[22:23], v[50:51], v[138:139], v[22:23] neg_lo:[1,0,0] neg_hi:[1,0,0]
	v_pk_fma_f32 v[30:31], v[52:53], v[140:141], v[30:31] neg_lo:[1,0,0] neg_hi:[1,0,0]
	ds_read_b128 v[50:53], v33 offset:29856
	s_waitcnt lgkmcnt(12)
	v_pk_fma_f32 v[22:23], v[54:55], v[142:143], v[22:23] neg_lo:[1,0,0] neg_hi:[1,0,0]
	v_pk_fma_f32 v[30:31], v[56:57], v[162:163], v[30:31] neg_lo:[1,0,0] neg_hi:[1,0,0]
	ds_read_b128 v[54:57], v33 offset:29872
	v_cmp_eq_u32_e32 vcc, 48, v152
	v_add_f32_e32 v82, v22, v23
	v_add_f32_e32 v83, v30, v31
	v_add_f32_e32 v163, v82, v83
	v_cvt_pk_bf16_f32 v25, v163, v163
	ds_write_b16 v84, v25 offset:6768
	v_cndmask_b32_e64 v22, 0, 1.0, vcc
	v_mov_b32_e32 v23, 0
	ds_read_b128 v[58:61], v33 offset:30144
	s_waitcnt lgkmcnt(13)
	v_pk_fma_f32 v[22:23], v[0:1], v[98:99], v[22:23] neg_lo:[1,0,0] neg_hi:[1,0,0]
	v_pk_fma_f32 v[30:31], v[2:3], v[100:101], 0 neg_lo:[1,0,0] neg_hi:[1,0,0]
	ds_read_b128 v[0:3], v33 offset:29952
	s_waitcnt lgkmcnt(13)
	v_pk_fma_f32 v[22:23], v[4:5], v[102:103], v[22:23] neg_lo:[1,0,0] neg_hi:[1,0,0]
	v_pk_fma_f32 v[30:31], v[6:7], v[104:105], v[30:31] neg_lo:[1,0,0] neg_hi:[1,0,0]
	ds_read_b128 v[4:7], v33 offset:29968
	s_waitcnt lgkmcnt(13)
	v_pk_fma_f32 v[22:23], v[8:9], v[106:107], v[22:23] neg_lo:[1,0,0] neg_hi:[1,0,0]
	v_pk_fma_f32 v[30:31], v[10:11], v[108:109], v[30:31] neg_lo:[1,0,0] neg_hi:[1,0,0]
	ds_read_b128 v[8:11], v33 offset:29984
	s_waitcnt lgkmcnt(13)
	v_pk_fma_f32 v[22:23], v[12:13], v[110:111], v[22:23] neg_lo:[1,0,0] neg_hi:[1,0,0]
	v_pk_fma_f32 v[30:31], v[14:15], v[112:113], v[30:31] neg_lo:[1,0,0] neg_hi:[1,0,0]
	ds_read_b128 v[12:15], v33 offset:30000
	s_waitcnt lgkmcnt(13)
	v_pk_fma_f32 v[22:23], v[16:17], v[114:115], v[22:23] neg_lo:[1,0,0] neg_hi:[1,0,0]
	v_pk_fma_f32 v[30:31], v[18:19], v[116:117], v[30:31] neg_lo:[1,0,0] neg_hi:[1,0,0]
	ds_read_b128 v[16:19], v33 offset:30016
	s_waitcnt lgkmcnt(13)
	v_pk_fma_f32 v[22:23], v[26:27], v[118:119], v[22:23] neg_lo:[1,0,0] neg_hi:[1,0,0]
	v_pk_fma_f32 v[30:31], v[28:29], v[120:121], v[30:31] neg_lo:[1,0,0] neg_hi:[1,0,0]
	ds_read_b128 v[26:29], v33 offset:30032
	s_waitcnt lgkmcnt(13)
	v_pk_fma_f32 v[22:23], v[34:35], v[122:123], v[22:23] neg_lo:[1,0,0] neg_hi:[1,0,0]
	v_pk_fma_f32 v[30:31], v[36:37], v[124:125], v[30:31] neg_lo:[1,0,0] neg_hi:[1,0,0]
	ds_read_b128 v[34:37], v33 offset:30048
	s_waitcnt lgkmcnt(13)
	v_pk_fma_f32 v[22:23], v[38:39], v[126:127], v[22:23] neg_lo:[1,0,0] neg_hi:[1,0,0]
	v_pk_fma_f32 v[30:31], v[40:41], v[128:129], v[30:31] neg_lo:[1,0,0] neg_hi:[1,0,0]
	ds_read_b128 v[38:41], v33 offset:30064
	s_waitcnt lgkmcnt(13)
	v_pk_fma_f32 v[22:23], v[42:43], v[130:131], v[22:23] neg_lo:[1,0,0] neg_hi:[1,0,0]
	v_pk_fma_f32 v[30:31], v[44:45], v[132:133], v[30:31] neg_lo:[1,0,0] neg_hi:[1,0,0]
	ds_read_b128 v[42:45], v33 offset:30080
	s_waitcnt lgkmcnt(13)
	v_pk_fma_f32 v[22:23], v[46:47], v[134:135], v[22:23] neg_lo:[1,0,0] neg_hi:[1,0,0]
	v_pk_fma_f32 v[30:31], v[48:49], v[136:137], v[30:31] neg_lo:[1,0,0] neg_hi:[1,0,0]
	ds_read_b128 v[46:49], v33 offset:30096
	s_waitcnt lgkmcnt(13)
	v_pk_fma_f32 v[22:23], v[50:51], v[138:139], v[22:23] neg_lo:[1,0,0] neg_hi:[1,0,0]
	v_pk_fma_f32 v[30:31], v[52:53], v[140:141], v[30:31] neg_lo:[1,0,0] neg_hi:[1,0,0]
	ds_read_b128 v[50:53], v33 offset:30112
	s_waitcnt lgkmcnt(13)
	v_pk_fma_f32 v[22:23], v[54:55], v[142:143], v[22:23] neg_lo:[1,0,0] neg_hi:[1,0,0]
	v_pk_fma_f32 v[30:31], v[56:57], v[162:163], v[30:31] neg_lo:[1,0,0] neg_hi:[1,0,0]
	ds_read_b128 v[54:57], v33 offset:30128
	v_cmp_eq_u32_e32 vcc, 49, v152
	v_add_f32_e32 v82, v22, v23
	v_add_f32_e32 v83, v30, v31
	v_add_f32_e32 v164, v82, v83
	v_cvt_pk_bf16_f32 v25, v164, v164
	ds_write_b16 v84, v25 offset:6912
	v_cndmask_b32_e64 v22, 0, 1.0, vcc
	v_mov_b32_e32 v23, 0
	s_waitcnt lgkmcnt(12)
	v_pk_fma_f32 v[22:23], v[0:1], v[98:99], v[22:23] neg_lo:[1,0,0] neg_hi:[1,0,0]
	v_pk_fma_f32 v[30:31], v[2:3], v[100:101], 0 neg_lo:[1,0,0] neg_hi:[1,0,0]
	ds_read_b128 v[0:3], v33 offset:30208
	s_waitcnt lgkmcnt(12)
	v_pk_fma_f32 v[22:23], v[4:5], v[102:103], v[22:23] neg_lo:[1,0,0] neg_hi:[1,0,0]
	v_pk_fma_f32 v[30:31], v[6:7], v[104:105], v[30:31] neg_lo:[1,0,0] neg_hi:[1,0,0]
	ds_read_b128 v[4:7], v33 offset:30224
	s_waitcnt lgkmcnt(12)
	v_pk_fma_f32 v[22:23], v[8:9], v[106:107], v[22:23] neg_lo:[1,0,0] neg_hi:[1,0,0]
	v_pk_fma_f32 v[30:31], v[10:11], v[108:109], v[30:31] neg_lo:[1,0,0] neg_hi:[1,0,0]
	ds_read_b128 v[8:11], v33 offset:30240
	s_waitcnt lgkmcnt(12)
	v_pk_fma_f32 v[22:23], v[12:13], v[110:111], v[22:23] neg_lo:[1,0,0] neg_hi:[1,0,0]
	v_pk_fma_f32 v[30:31], v[14:15], v[112:113], v[30:31] neg_lo:[1,0,0] neg_hi:[1,0,0]
	ds_read_b128 v[12:15], v33 offset:30256
	s_waitcnt lgkmcnt(12)
	v_pk_fma_f32 v[22:23], v[16:17], v[114:115], v[22:23] neg_lo:[1,0,0] neg_hi:[1,0,0]
	v_pk_fma_f32 v[30:31], v[18:19], v[116:117], v[30:31] neg_lo:[1,0,0] neg_hi:[1,0,0]
	ds_read_b128 v[16:19], v33 offset:30272
	s_waitcnt lgkmcnt(12)
	v_pk_fma_f32 v[22:23], v[26:27], v[118:119], v[22:23] neg_lo:[1,0,0] neg_hi:[1,0,0]
	v_pk_fma_f32 v[30:31], v[28:29], v[120:121], v[30:31] neg_lo:[1,0,0] neg_hi:[1,0,0]
	ds_read_b128 v[26:29], v33 offset:30288
	s_waitcnt lgkmcnt(12)
	v_pk_fma_f32 v[22:23], v[34:35], v[122:123], v[22:23] neg_lo:[1,0,0] neg_hi:[1,0,0]
	v_pk_fma_f32 v[30:31], v[36:37], v[124:125], v[30:31] neg_lo:[1,0,0] neg_hi:[1,0,0]
	ds_read_b128 v[34:37], v33 offset:30304
	s_waitcnt lgkmcnt(12)
	v_pk_fma_f32 v[22:23], v[38:39], v[126:127], v[22:23] neg_lo:[1,0,0] neg_hi:[1,0,0]
	v_pk_fma_f32 v[30:31], v[40:41], v[128:129], v[30:31] neg_lo:[1,0,0] neg_hi:[1,0,0]
	ds_read_b128 v[38:41], v33 offset:30320
	s_waitcnt lgkmcnt(12)
	v_pk_fma_f32 v[22:23], v[42:43], v[130:131], v[22:23] neg_lo:[1,0,0] neg_hi:[1,0,0]
	v_pk_fma_f32 v[30:31], v[44:45], v[132:133], v[30:31] neg_lo:[1,0,0] neg_hi:[1,0,0]
	ds_read_b128 v[42:45], v33 offset:30336
	s_waitcnt lgkmcnt(12)
	v_pk_fma_f32 v[22:23], v[46:47], v[134:135], v[22:23] neg_lo:[1,0,0] neg_hi:[1,0,0]
	v_pk_fma_f32 v[30:31], v[48:49], v[136:137], v[30:31] neg_lo:[1,0,0] neg_hi:[1,0,0]
	ds_read_b128 v[46:49], v33 offset:30352
	s_waitcnt lgkmcnt(12)
	v_pk_fma_f32 v[22:23], v[50:51], v[138:139], v[22:23] neg_lo:[1,0,0] neg_hi:[1,0,0]
	v_pk_fma_f32 v[30:31], v[52:53], v[140:141], v[30:31] neg_lo:[1,0,0] neg_hi:[1,0,0]
	ds_read_b128 v[50:53], v33 offset:30368
	s_waitcnt lgkmcnt(12)
	v_pk_fma_f32 v[22:23], v[54:55], v[142:143], v[22:23] neg_lo:[1,0,0] neg_hi:[1,0,0]
	v_pk_fma_f32 v[30:31], v[56:57], v[162:163], v[30:31] neg_lo:[1,0,0] neg_hi:[1,0,0]
	ds_read_b128 v[54:57], v33 offset:30384
	s_waitcnt lgkmcnt(15)
	v_pk_fma_f32 v[22:23], v[58:59], v[164:165], v[22:23] neg_lo:[1,0,0] neg_hi:[1,0,0]
	v_pk_fma_f32 v[30:31], v[60:61], v[166:167], v[30:31] neg_lo:[1,0,0] neg_hi:[1,0,0]
	ds_read_b128 v[58:61], v33 offset:30400
	v_cmp_eq_u32_e32 vcc, 50, v152
	v_add_f32_e32 v82, v22, v23
	v_add_f32_e32 v83, v30, v31
	v_add_f32_e32 v165, v82, v83
	v_cvt_pk_bf16_f32 v25, v165, v165
	ds_write_b16 v84, v25 offset:7056
	v_cndmask_b32_e64 v22, 0, 1.0, vcc
	v_mov_b32_e32 v23, 0
	s_waitcnt lgkmcnt(13)
	v_pk_fma_f32 v[22:23], v[0:1], v[98:99], v[22:23] neg_lo:[1,0,0] neg_hi:[1,0,0]
	v_pk_fma_f32 v[30:31], v[2:3], v[100:101], 0 neg_lo:[1,0,0] neg_hi:[1,0,0]
	ds_read_b128 v[0:3], v33 offset:30464
	s_waitcnt lgkmcnt(13)
	v_pk_fma_f32 v[22:23], v[4:5], v[102:103], v[22:23] neg_lo:[1,0,0] neg_hi:[1,0,0]
	v_pk_fma_f32 v[30:31], v[6:7], v[104:105], v[30:31] neg_lo:[1,0,0] neg_hi:[1,0,0]
	ds_read_b128 v[4:7], v33 offset:30480
	s_waitcnt lgkmcnt(13)
	v_pk_fma_f32 v[22:23], v[8:9], v[106:107], v[22:23] neg_lo:[1,0,0] neg_hi:[1,0,0]
	v_pk_fma_f32 v[30:31], v[10:11], v[108:109], v[30:31] neg_lo:[1,0,0] neg_hi:[1,0,0]
	ds_read_b128 v[8:11], v33 offset:30496
	s_waitcnt lgkmcnt(13)
	v_pk_fma_f32 v[22:23], v[12:13], v[110:111], v[22:23] neg_lo:[1,0,0] neg_hi:[1,0,0]
	v_pk_fma_f32 v[30:31], v[14:15], v[112:113], v[30:31] neg_lo:[1,0,0] neg_hi:[1,0,0]
	ds_read_b128 v[12:15], v33 offset:30512
	s_waitcnt lgkmcnt(13)
	v_pk_fma_f32 v[22:23], v[16:17], v[114:115], v[22:23] neg_lo:[1,0,0] neg_hi:[1,0,0]
	v_pk_fma_f32 v[30:31], v[18:19], v[116:117], v[30:31] neg_lo:[1,0,0] neg_hi:[1,0,0]
	ds_read_b128 v[16:19], v33 offset:30528
	s_waitcnt lgkmcnt(13)
	v_pk_fma_f32 v[22:23], v[26:27], v[118:119], v[22:23] neg_lo:[1,0,0] neg_hi:[1,0,0]
	v_pk_fma_f32 v[30:31], v[28:29], v[120:121], v[30:31] neg_lo:[1,0,0] neg_hi:[1,0,0]
	ds_read_b128 v[26:29], v33 offset:30544
	s_waitcnt lgkmcnt(13)
	v_pk_fma_f32 v[22:23], v[34:35], v[122:123], v[22:23] neg_lo:[1,0,0] neg_hi:[1,0,0]
	v_pk_fma_f32 v[30:31], v[36:37], v[124:125], v[30:31] neg_lo:[1,0,0] neg_hi:[1,0,0]
	ds_read_b128 v[34:37], v33 offset:30560
	s_waitcnt lgkmcnt(13)
	v_pk_fma_f32 v[22:23], v[38:39], v[126:127], v[22:23] neg_lo:[1,0,0] neg_hi:[1,0,0]
	v_pk_fma_f32 v[30:31], v[40:41], v[128:129], v[30:31] neg_lo:[1,0,0] neg_hi:[1,0,0]
	ds_read_b128 v[38:41], v33 offset:30576
	s_waitcnt lgkmcnt(13)
	v_pk_fma_f32 v[22:23], v[42:43], v[130:131], v[22:23] neg_lo:[1,0,0] neg_hi:[1,0,0]
	v_pk_fma_f32 v[30:31], v[44:45], v[132:133], v[30:31] neg_lo:[1,0,0] neg_hi:[1,0,0]
	ds_read_b128 v[42:45], v33 offset:30592
	s_waitcnt lgkmcnt(13)
	v_pk_fma_f32 v[22:23], v[46:47], v[134:135], v[22:23] neg_lo:[1,0,0] neg_hi:[1,0,0]
	v_pk_fma_f32 v[30:31], v[48:49], v[136:137], v[30:31] neg_lo:[1,0,0] neg_hi:[1,0,0]
	ds_read_b128 v[46:49], v33 offset:30608
	s_waitcnt lgkmcnt(13)
	v_pk_fma_f32 v[22:23], v[50:51], v[138:139], v[22:23] neg_lo:[1,0,0] neg_hi:[1,0,0]
	v_pk_fma_f32 v[30:31], v[52:53], v[140:141], v[30:31] neg_lo:[1,0,0] neg_hi:[1,0,0]
	ds_read_b128 v[50:53], v33 offset:30624
	s_waitcnt lgkmcnt(13)
	v_pk_fma_f32 v[22:23], v[54:55], v[142:143], v[22:23] neg_lo:[1,0,0] neg_hi:[1,0,0]
	v_pk_fma_f32 v[30:31], v[56:57], v[162:163], v[30:31] neg_lo:[1,0,0] neg_hi:[1,0,0]
	ds_read_b128 v[54:57], v33 offset:30640
	s_waitcnt lgkmcnt(13)
	v_pk_fma_f32 v[22:23], v[58:59], v[164:165], v[22:23] neg_lo:[1,0,0] neg_hi:[1,0,0]
	v_pk_fma_f32 v[30:31], v[60:61], v[166:167], v[30:31] neg_lo:[1,0,0] neg_hi:[1,0,0]
	ds_read_b128 v[58:61], v33 offset:30656
	v_cmp_eq_u32_e32 vcc, 51, v152
	v_add_f32_e32 v82, v22, v23
	v_add_f32_e32 v83, v30, v31
	v_add_f32_e32 v166, v82, v83
	v_cvt_pk_bf16_f32 v25, v166, v166
	ds_write_b16 v84, v25 offset:7200
	v_cndmask_b32_e64 v22, 0, 1.0, vcc
	v_mov_b32_e32 v23, 0
	s_waitcnt lgkmcnt(13)
	v_pk_fma_f32 v[22:23], v[0:1], v[98:99], v[22:23] neg_lo:[1,0,0] neg_hi:[1,0,0]
	v_pk_fma_f32 v[30:31], v[2:3], v[100:101], 0 neg_lo:[1,0,0] neg_hi:[1,0,0]
	ds_read_b128 v[0:3], v33 offset:30720
	s_waitcnt lgkmcnt(13)
	v_pk_fma_f32 v[22:23], v[4:5], v[102:103], v[22:23] neg_lo:[1,0,0] neg_hi:[1,0,0]
	v_pk_fma_f32 v[30:31], v[6:7], v[104:105], v[30:31] neg_lo:[1,0,0] neg_hi:[1,0,0]
	ds_read_b128 v[4:7], v33 offset:30736
	s_waitcnt lgkmcnt(13)
	v_pk_fma_f32 v[22:23], v[8:9], v[106:107], v[22:23] neg_lo:[1,0,0] neg_hi:[1,0,0]
	v_pk_fma_f32 v[30:31], v[10:11], v[108:109], v[30:31] neg_lo:[1,0,0] neg_hi:[1,0,0]
	ds_read_b128 v[8:11], v33 offset:30752
	s_waitcnt lgkmcnt(13)
	v_pk_fma_f32 v[22:23], v[12:13], v[110:111], v[22:23] neg_lo:[1,0,0] neg_hi:[1,0,0]
	v_pk_fma_f32 v[30:31], v[14:15], v[112:113], v[30:31] neg_lo:[1,0,0] neg_hi:[1,0,0]
	ds_read_b128 v[12:15], v33 offset:30768
	s_waitcnt lgkmcnt(13)
	v_pk_fma_f32 v[22:23], v[16:17], v[114:115], v[22:23] neg_lo:[1,0,0] neg_hi:[1,0,0]
	v_pk_fma_f32 v[30:31], v[18:19], v[116:117], v[30:31] neg_lo:[1,0,0] neg_hi:[1,0,0]
	ds_read_b128 v[16:19], v33 offset:30784
	s_waitcnt lgkmcnt(13)
	v_pk_fma_f32 v[22:23], v[26:27], v[118:119], v[22:23] neg_lo:[1,0,0] neg_hi:[1,0,0]
	v_pk_fma_f32 v[30:31], v[28:29], v[120:121], v[30:31] neg_lo:[1,0,0] neg_hi:[1,0,0]
	ds_read_b128 v[26:29], v33 offset:30800
	s_waitcnt lgkmcnt(13)
	v_pk_fma_f32 v[22:23], v[34:35], v[122:123], v[22:23] neg_lo:[1,0,0] neg_hi:[1,0,0]
	v_pk_fma_f32 v[30:31], v[36:37], v[124:125], v[30:31] neg_lo:[1,0,0] neg_hi:[1,0,0]
	ds_read_b128 v[34:37], v33 offset:30816
	s_waitcnt lgkmcnt(13)
	v_pk_fma_f32 v[22:23], v[38:39], v[126:127], v[22:23] neg_lo:[1,0,0] neg_hi:[1,0,0]
	v_pk_fma_f32 v[30:31], v[40:41], v[128:129], v[30:31] neg_lo:[1,0,0] neg_hi:[1,0,0]
	ds_read_b128 v[38:41], v33 offset:30832
	s_waitcnt lgkmcnt(13)
	v_pk_fma_f32 v[22:23], v[42:43], v[130:131], v[22:23] neg_lo:[1,0,0] neg_hi:[1,0,0]
	v_pk_fma_f32 v[30:31], v[44:45], v[132:133], v[30:31] neg_lo:[1,0,0] neg_hi:[1,0,0]
	ds_read_b128 v[42:45], v33 offset:30848
	s_waitcnt lgkmcnt(13)
	v_pk_fma_f32 v[22:23], v[46:47], v[134:135], v[22:23] neg_lo:[1,0,0] neg_hi:[1,0,0]
	v_pk_fma_f32 v[30:31], v[48:49], v[136:137], v[30:31] neg_lo:[1,0,0] neg_hi:[1,0,0]
	ds_read_b128 v[46:49], v33 offset:30864
	s_waitcnt lgkmcnt(13)
	v_pk_fma_f32 v[22:23], v[50:51], v[138:139], v[22:23] neg_lo:[1,0,0] neg_hi:[1,0,0]
	v_pk_fma_f32 v[30:31], v[52:53], v[140:141], v[30:31] neg_lo:[1,0,0] neg_hi:[1,0,0]
	ds_read_b128 v[50:53], v33 offset:30880
	s_waitcnt lgkmcnt(13)
	v_pk_fma_f32 v[22:23], v[54:55], v[142:143], v[22:23] neg_lo:[1,0,0] neg_hi:[1,0,0]
	v_pk_fma_f32 v[30:31], v[56:57], v[162:163], v[30:31] neg_lo:[1,0,0] neg_hi:[1,0,0]
	ds_read_b128 v[54:57], v33 offset:30896
	s_waitcnt lgkmcnt(13)
	v_pk_fma_f32 v[22:23], v[58:59], v[164:165], v[22:23] neg_lo:[1,0,0] neg_hi:[1,0,0]
	v_pk_fma_f32 v[30:31], v[60:61], v[166:167], v[30:31] neg_lo:[1,0,0] neg_hi:[1,0,0]
	ds_read_b128 v[58:61], v33 offset:30912
	v_cmp_eq_u32_e32 vcc, 52, v152
	v_add_f32_e32 v82, v22, v23
	v_add_f32_e32 v83, v30, v31
	v_add_f32_e32 v167, v82, v83
	v_cvt_pk_bf16_f32 v25, v167, v167
	ds_write_b16 v84, v25 offset:7344
	v_cndmask_b32_e64 v22, 0, 1.0, vcc
	v_mov_b32_e32 v23, 0
	ds_read_b128 v[62:65], v33 offset:31184
	s_waitcnt lgkmcnt(14)
	v_pk_fma_f32 v[22:23], v[0:1], v[98:99], v[22:23] neg_lo:[1,0,0] neg_hi:[1,0,0]
	v_pk_fma_f32 v[30:31], v[2:3], v[100:101], 0 neg_lo:[1,0,0] neg_hi:[1,0,0]
	ds_read_b128 v[0:3], v33 offset:30976
	s_waitcnt lgkmcnt(14)
	v_pk_fma_f32 v[22:23], v[4:5], v[102:103], v[22:23] neg_lo:[1,0,0] neg_hi:[1,0,0]
	v_pk_fma_f32 v[30:31], v[6:7], v[104:105], v[30:31] neg_lo:[1,0,0] neg_hi:[1,0,0]
	ds_read_b128 v[4:7], v33 offset:30992
	s_waitcnt lgkmcnt(14)
	v_pk_fma_f32 v[22:23], v[8:9], v[106:107], v[22:23] neg_lo:[1,0,0] neg_hi:[1,0,0]
	v_pk_fma_f32 v[30:31], v[10:11], v[108:109], v[30:31] neg_lo:[1,0,0] neg_hi:[1,0,0]
	ds_read_b128 v[8:11], v33 offset:31008
	s_waitcnt lgkmcnt(14)
	v_pk_fma_f32 v[22:23], v[12:13], v[110:111], v[22:23] neg_lo:[1,0,0] neg_hi:[1,0,0]
	v_pk_fma_f32 v[30:31], v[14:15], v[112:113], v[30:31] neg_lo:[1,0,0] neg_hi:[1,0,0]
	ds_read_b128 v[12:15], v33 offset:31024
	s_waitcnt lgkmcnt(14)
	v_pk_fma_f32 v[22:23], v[16:17], v[114:115], v[22:23] neg_lo:[1,0,0] neg_hi:[1,0,0]
	v_pk_fma_f32 v[30:31], v[18:19], v[116:117], v[30:31] neg_lo:[1,0,0] neg_hi:[1,0,0]
	ds_read_b128 v[16:19], v33 offset:31040
	s_waitcnt lgkmcnt(14)
	v_pk_fma_f32 v[22:23], v[26:27], v[118:119], v[22:23] neg_lo:[1,0,0] neg_hi:[1,0,0]
	v_pk_fma_f32 v[30:31], v[28:29], v[120:121], v[30:31] neg_lo:[1,0,0] neg_hi:[1,0,0]
	ds_read_b128 v[26:29], v33 offset:31056
	s_waitcnt lgkmcnt(14)
	v_pk_fma_f32 v[22:23], v[34:35], v[122:123], v[22:23] neg_lo:[1,0,0] neg_hi:[1,0,0]
	v_pk_fma_f32 v[30:31], v[36:37], v[124:125], v[30:31] neg_lo:[1,0,0] neg_hi:[1,0,0]
	ds_read_b128 v[34:37], v33 offset:31072
	s_waitcnt lgkmcnt(14)
	v_pk_fma_f32 v[22:23], v[38:39], v[126:127], v[22:23] neg_lo:[1,0,0] neg_hi:[1,0,0]
	v_pk_fma_f32 v[30:31], v[40:41], v[128:129], v[30:31] neg_lo:[1,0,0] neg_hi:[1,0,0]
	ds_read_b128 v[38:41], v33 offset:31088
	s_waitcnt lgkmcnt(14)
	v_pk_fma_f32 v[22:23], v[42:43], v[130:131], v[22:23] neg_lo:[1,0,0] neg_hi:[1,0,0]
	v_pk_fma_f32 v[30:31], v[44:45], v[132:133], v[30:31] neg_lo:[1,0,0] neg_hi:[1,0,0]
	ds_read_b128 v[42:45], v33 offset:31104
	s_waitcnt lgkmcnt(14)
	v_pk_fma_f32 v[22:23], v[46:47], v[134:135], v[22:23] neg_lo:[1,0,0] neg_hi:[1,0,0]
	v_pk_fma_f32 v[30:31], v[48:49], v[136:137], v[30:31] neg_lo:[1,0,0] neg_hi:[1,0,0]
	ds_read_b128 v[46:49], v33 offset:31120
	s_waitcnt lgkmcnt(14)
	v_pk_fma_f32 v[22:23], v[50:51], v[138:139], v[22:23] neg_lo:[1,0,0] neg_hi:[1,0,0]
	v_pk_fma_f32 v[30:31], v[52:53], v[140:141], v[30:31] neg_lo:[1,0,0] neg_hi:[1,0,0]
	ds_read_b128 v[50:53], v33 offset:31136
	s_waitcnt lgkmcnt(14)
	v_pk_fma_f32 v[22:23], v[54:55], v[142:143], v[22:23] neg_lo:[1,0,0] neg_hi:[1,0,0]
	v_pk_fma_f32 v[30:31], v[56:57], v[162:163], v[30:31] neg_lo:[1,0,0] neg_hi:[1,0,0]
	ds_read_b128 v[54:57], v33 offset:31152
	s_waitcnt lgkmcnt(14)
	v_pk_fma_f32 v[22:23], v[58:59], v[164:165], v[22:23] neg_lo:[1,0,0] neg_hi:[1,0,0]
	v_pk_fma_f32 v[30:31], v[60:61], v[166:167], v[30:31] neg_lo:[1,0,0] neg_hi:[1,0,0]
	ds_read_b128 v[58:61], v33 offset:31168
	v_cmp_eq_u32_e32 vcc, 53, v152
	v_add_f32_e32 v82, v22, v23
	v_add_f32_e32 v83, v30, v31
	v_add_f32_e32 v168, v82, v83
	v_cvt_pk_bf16_f32 v25, v168, v168
	ds_write_b16 v84, v25 offset:7488
	v_cndmask_b32_e64 v22, 0, 1.0, vcc
	v_mov_b32_e32 v23, 0
	s_waitcnt lgkmcnt(13)
	v_pk_fma_f32 v[22:23], v[0:1], v[98:99], v[22:23] neg_lo:[1,0,0] neg_hi:[1,0,0]
	v_pk_fma_f32 v[30:31], v[2:3], v[100:101], 0 neg_lo:[1,0,0] neg_hi:[1,0,0]
	ds_read_b128 v[0:3], v33 offset:31232
	s_waitcnt lgkmcnt(13)
	v_pk_fma_f32 v[22:23], v[4:5], v[102:103], v[22:23] neg_lo:[1,0,0] neg_hi:[1,0,0]
	v_pk_fma_f32 v[30:31], v[6:7], v[104:105], v[30:31] neg_lo:[1,0,0] neg_hi:[1,0,0]
	ds_read_b128 v[4:7], v33 offset:31248
	s_waitcnt lgkmcnt(13)
	v_pk_fma_f32 v[22:23], v[8:9], v[106:107], v[22:23] neg_lo:[1,0,0] neg_hi:[1,0,0]
	v_pk_fma_f32 v[30:31], v[10:11], v[108:109], v[30:31] neg_lo:[1,0,0] neg_hi:[1,0,0]
	ds_read_b128 v[8:11], v33 offset:31264
	s_waitcnt lgkmcnt(13)
	v_pk_fma_f32 v[22:23], v[12:13], v[110:111], v[22:23] neg_lo:[1,0,0] neg_hi:[1,0,0]
	v_pk_fma_f32 v[30:31], v[14:15], v[112:113], v[30:31] neg_lo:[1,0,0] neg_hi:[1,0,0]
	ds_read_b128 v[12:15], v33 offset:31280
	s_waitcnt lgkmcnt(13)
	v_pk_fma_f32 v[22:23], v[16:17], v[114:115], v[22:23] neg_lo:[1,0,0] neg_hi:[1,0,0]
	v_pk_fma_f32 v[30:31], v[18:19], v[116:117], v[30:31] neg_lo:[1,0,0] neg_hi:[1,0,0]
	ds_read_b128 v[16:19], v33 offset:31296
	s_waitcnt lgkmcnt(13)
	v_pk_fma_f32 v[22:23], v[26:27], v[118:119], v[22:23] neg_lo:[1,0,0] neg_hi:[1,0,0]
	v_pk_fma_f32 v[30:31], v[28:29], v[120:121], v[30:31] neg_lo:[1,0,0] neg_hi:[1,0,0]
	ds_read_b128 v[26:29], v33 offset:31312
	s_waitcnt lgkmcnt(13)
	v_pk_fma_f32 v[22:23], v[34:35], v[122:123], v[22:23] neg_lo:[1,0,0] neg_hi:[1,0,0]
	v_pk_fma_f32 v[30:31], v[36:37], v[124:125], v[30:31] neg_lo:[1,0,0] neg_hi:[1,0,0]
	ds_read_b128 v[34:37], v33 offset:31328
	s_waitcnt lgkmcnt(13)
	v_pk_fma_f32 v[22:23], v[38:39], v[126:127], v[22:23] neg_lo:[1,0,0] neg_hi:[1,0,0]
	v_pk_fma_f32 v[30:31], v[40:41], v[128:129], v[30:31] neg_lo:[1,0,0] neg_hi:[1,0,0]
	ds_read_b128 v[38:41], v33 offset:31344
	s_waitcnt lgkmcnt(13)
	v_pk_fma_f32 v[22:23], v[42:43], v[130:131], v[22:23] neg_lo:[1,0,0] neg_hi:[1,0,0]
	v_pk_fma_f32 v[30:31], v[44:45], v[132:133], v[30:31] neg_lo:[1,0,0] neg_hi:[1,0,0]
	ds_read_b128 v[42:45], v33 offset:31360
	s_waitcnt lgkmcnt(13)
	v_pk_fma_f32 v[22:23], v[46:47], v[134:135], v[22:23] neg_lo:[1,0,0] neg_hi:[1,0,0]
	v_pk_fma_f32 v[30:31], v[48:49], v[136:137], v[30:31] neg_lo:[1,0,0] neg_hi:[1,0,0]
	ds_read_b128 v[46:49], v33 offset:31376
	s_waitcnt lgkmcnt(13)
	v_pk_fma_f32 v[22:23], v[50:51], v[138:139], v[22:23] neg_lo:[1,0,0] neg_hi:[1,0,0]
	v_pk_fma_f32 v[30:31], v[52:53], v[140:141], v[30:31] neg_lo:[1,0,0] neg_hi:[1,0,0]
	ds_read_b128 v[50:53], v33 offset:31392
	s_waitcnt lgkmcnt(13)
	v_pk_fma_f32 v[22:23], v[54:55], v[142:143], v[22:23] neg_lo:[1,0,0] neg_hi:[1,0,0]
	v_pk_fma_f32 v[30:31], v[56:57], v[162:163], v[30:31] neg_lo:[1,0,0] neg_hi:[1,0,0]
	ds_read_b128 v[54:57], v33 offset:31408
	s_waitcnt lgkmcnt(13)
	v_pk_fma_f32 v[22:23], v[58:59], v[164:165], v[22:23] neg_lo:[1,0,0] neg_hi:[1,0,0]
	v_pk_fma_f32 v[30:31], v[60:61], v[166:167], v[30:31] neg_lo:[1,0,0] neg_hi:[1,0,0]
	ds_read_b128 v[58:61], v33 offset:31424
	s_waitcnt lgkmcnt(15)
	v_pk_fma_f32 v[22:23], v[62:63], v[168:169], v[22:23] neg_lo:[1,0,0] neg_hi:[1,0,0]
	v_pk_fma_f32 v[30:31], v[64:65], v[170:171], v[30:31] neg_lo:[1,0,0] neg_hi:[1,0,0]
	ds_read_b128 v[62:65], v33 offset:31440
	v_cmp_eq_u32_e32 vcc, 54, v152
	v_add_f32_e32 v82, v22, v23
	v_add_f32_e32 v83, v30, v31
	v_add_f32_e32 v169, v82, v83
	v_cvt_pk_bf16_f32 v25, v169, v169
	ds_write_b16 v84, v25 offset:7632
	v_cndmask_b32_e64 v22, 0, 1.0, vcc
	v_mov_b32_e32 v23, 0
	s_waitcnt lgkmcnt(14)
	v_pk_fma_f32 v[22:23], v[0:1], v[98:99], v[22:23] neg_lo:[1,0,0] neg_hi:[1,0,0]
	v_pk_fma_f32 v[30:31], v[2:3], v[100:101], 0 neg_lo:[1,0,0] neg_hi:[1,0,0]
	ds_read_b128 v[0:3], v33 offset:31488
	s_waitcnt lgkmcnt(14)
	v_pk_fma_f32 v[22:23], v[4:5], v[102:103], v[22:23] neg_lo:[1,0,0] neg_hi:[1,0,0]
	v_pk_fma_f32 v[30:31], v[6:7], v[104:105], v[30:31] neg_lo:[1,0,0] neg_hi:[1,0,0]
	ds_read_b128 v[4:7], v33 offset:31504
	s_waitcnt lgkmcnt(14)
	v_pk_fma_f32 v[22:23], v[8:9], v[106:107], v[22:23] neg_lo:[1,0,0] neg_hi:[1,0,0]
	v_pk_fma_f32 v[30:31], v[10:11], v[108:109], v[30:31] neg_lo:[1,0,0] neg_hi:[1,0,0]
	ds_read_b128 v[8:11], v33 offset:31520
	s_waitcnt lgkmcnt(14)
	v_pk_fma_f32 v[22:23], v[12:13], v[110:111], v[22:23] neg_lo:[1,0,0] neg_hi:[1,0,0]
	v_pk_fma_f32 v[30:31], v[14:15], v[112:113], v[30:31] neg_lo:[1,0,0] neg_hi:[1,0,0]
	ds_read_b128 v[12:15], v33 offset:31536
	s_waitcnt lgkmcnt(14)
	v_pk_fma_f32 v[22:23], v[16:17], v[114:115], v[22:23] neg_lo:[1,0,0] neg_hi:[1,0,0]
	v_pk_fma_f32 v[30:31], v[18:19], v[116:117], v[30:31] neg_lo:[1,0,0] neg_hi:[1,0,0]
	ds_read_b128 v[16:19], v33 offset:31552
	s_waitcnt lgkmcnt(14)
	v_pk_fma_f32 v[22:23], v[26:27], v[118:119], v[22:23] neg_lo:[1,0,0] neg_hi:[1,0,0]
	v_pk_fma_f32 v[30:31], v[28:29], v[120:121], v[30:31] neg_lo:[1,0,0] neg_hi:[1,0,0]
	ds_read_b128 v[26:29], v33 offset:31568
	s_waitcnt lgkmcnt(14)
	v_pk_fma_f32 v[22:23], v[34:35], v[122:123], v[22:23] neg_lo:[1,0,0] neg_hi:[1,0,0]
	v_pk_fma_f32 v[30:31], v[36:37], v[124:125], v[30:31] neg_lo:[1,0,0] neg_hi:[1,0,0]
	ds_read_b128 v[34:37], v33 offset:31584
	s_waitcnt lgkmcnt(14)
	v_pk_fma_f32 v[22:23], v[38:39], v[126:127], v[22:23] neg_lo:[1,0,0] neg_hi:[1,0,0]
	v_pk_fma_f32 v[30:31], v[40:41], v[128:129], v[30:31] neg_lo:[1,0,0] neg_hi:[1,0,0]
	ds_read_b128 v[38:41], v33 offset:31600
	s_waitcnt lgkmcnt(14)
	v_pk_fma_f32 v[22:23], v[42:43], v[130:131], v[22:23] neg_lo:[1,0,0] neg_hi:[1,0,0]
	v_pk_fma_f32 v[30:31], v[44:45], v[132:133], v[30:31] neg_lo:[1,0,0] neg_hi:[1,0,0]
	ds_read_b128 v[42:45], v33 offset:31616
	s_waitcnt lgkmcnt(14)
	v_pk_fma_f32 v[22:23], v[46:47], v[134:135], v[22:23] neg_lo:[1,0,0] neg_hi:[1,0,0]
	v_pk_fma_f32 v[30:31], v[48:49], v[136:137], v[30:31] neg_lo:[1,0,0] neg_hi:[1,0,0]
	ds_read_b128 v[46:49], v33 offset:31632
	s_waitcnt lgkmcnt(14)
	v_pk_fma_f32 v[22:23], v[50:51], v[138:139], v[22:23] neg_lo:[1,0,0] neg_hi:[1,0,0]
	v_pk_fma_f32 v[30:31], v[52:53], v[140:141], v[30:31] neg_lo:[1,0,0] neg_hi:[1,0,0]
	ds_read_b128 v[50:53], v33 offset:31648
	s_waitcnt lgkmcnt(14)
	v_pk_fma_f32 v[22:23], v[54:55], v[142:143], v[22:23] neg_lo:[1,0,0] neg_hi:[1,0,0]
	v_pk_fma_f32 v[30:31], v[56:57], v[162:163], v[30:31] neg_lo:[1,0,0] neg_hi:[1,0,0]
	ds_read_b128 v[54:57], v33 offset:31664
	s_waitcnt lgkmcnt(14)
	v_pk_fma_f32 v[22:23], v[58:59], v[164:165], v[22:23] neg_lo:[1,0,0] neg_hi:[1,0,0]
	v_pk_fma_f32 v[30:31], v[60:61], v[166:167], v[30:31] neg_lo:[1,0,0] neg_hi:[1,0,0]
	ds_read_b128 v[58:61], v33 offset:31680
	s_waitcnt lgkmcnt(14)
	v_pk_fma_f32 v[22:23], v[62:63], v[168:169], v[22:23] neg_lo:[1,0,0] neg_hi:[1,0,0]
	v_pk_fma_f32 v[30:31], v[64:65], v[170:171], v[30:31] neg_lo:[1,0,0] neg_hi:[1,0,0]
	ds_read_b128 v[62:65], v33 offset:31696
	v_cmp_eq_u32_e32 vcc, 55, v152
	v_add_f32_e32 v82, v22, v23
	v_add_f32_e32 v83, v30, v31
	v_add_f32_e32 v170, v82, v83
	v_cvt_pk_bf16_f32 v25, v170, v170
	ds_write_b16 v84, v25 offset:7776
	v_cndmask_b32_e64 v22, 0, 1.0, vcc
	v_mov_b32_e32 v23, 0
	s_waitcnt lgkmcnt(14)
	v_pk_fma_f32 v[22:23], v[0:1], v[98:99], v[22:23] neg_lo:[1,0,0] neg_hi:[1,0,0]
	v_pk_fma_f32 v[30:31], v[2:3], v[100:101], 0 neg_lo:[1,0,0] neg_hi:[1,0,0]
	ds_read_b128 v[0:3], v33 offset:31744
	s_waitcnt lgkmcnt(14)
	v_pk_fma_f32 v[22:23], v[4:5], v[102:103], v[22:23] neg_lo:[1,0,0] neg_hi:[1,0,0]
	v_pk_fma_f32 v[30:31], v[6:7], v[104:105], v[30:31] neg_lo:[1,0,0] neg_hi:[1,0,0]
	ds_read_b128 v[4:7], v33 offset:31760
	s_waitcnt lgkmcnt(14)
	v_pk_fma_f32 v[22:23], v[8:9], v[106:107], v[22:23] neg_lo:[1,0,0] neg_hi:[1,0,0]
	v_pk_fma_f32 v[30:31], v[10:11], v[108:109], v[30:31] neg_lo:[1,0,0] neg_hi:[1,0,0]
	ds_read_b128 v[8:11], v33 offset:31776
	s_waitcnt lgkmcnt(14)
	v_pk_fma_f32 v[22:23], v[12:13], v[110:111], v[22:23] neg_lo:[1,0,0] neg_hi:[1,0,0]
	v_pk_fma_f32 v[30:31], v[14:15], v[112:113], v[30:31] neg_lo:[1,0,0] neg_hi:[1,0,0]
	ds_read_b128 v[12:15], v33 offset:31792
	s_waitcnt lgkmcnt(14)
	v_pk_fma_f32 v[22:23], v[16:17], v[114:115], v[22:23] neg_lo:[1,0,0] neg_hi:[1,0,0]
	v_pk_fma_f32 v[30:31], v[18:19], v[116:117], v[30:31] neg_lo:[1,0,0] neg_hi:[1,0,0]
	ds_read_b128 v[16:19], v33 offset:31808
	s_waitcnt lgkmcnt(14)
	v_pk_fma_f32 v[22:23], v[26:27], v[118:119], v[22:23] neg_lo:[1,0,0] neg_hi:[1,0,0]
	v_pk_fma_f32 v[30:31], v[28:29], v[120:121], v[30:31] neg_lo:[1,0,0] neg_hi:[1,0,0]
	ds_read_b128 v[26:29], v33 offset:31824
	s_waitcnt lgkmcnt(14)
	v_pk_fma_f32 v[22:23], v[34:35], v[122:123], v[22:23] neg_lo:[1,0,0] neg_hi:[1,0,0]
	v_pk_fma_f32 v[30:31], v[36:37], v[124:125], v[30:31] neg_lo:[1,0,0] neg_hi:[1,0,0]
	ds_read_b128 v[34:37], v33 offset:31840
	s_waitcnt lgkmcnt(14)
	v_pk_fma_f32 v[22:23], v[38:39], v[126:127], v[22:23] neg_lo:[1,0,0] neg_hi:[1,0,0]
	v_pk_fma_f32 v[30:31], v[40:41], v[128:129], v[30:31] neg_lo:[1,0,0] neg_hi:[1,0,0]
	ds_read_b128 v[38:41], v33 offset:31856
	s_waitcnt lgkmcnt(14)
	v_pk_fma_f32 v[22:23], v[42:43], v[130:131], v[22:23] neg_lo:[1,0,0] neg_hi:[1,0,0]
	v_pk_fma_f32 v[30:31], v[44:45], v[132:133], v[30:31] neg_lo:[1,0,0] neg_hi:[1,0,0]
	ds_read_b128 v[42:45], v33 offset:31872
	s_waitcnt lgkmcnt(14)
	v_pk_fma_f32 v[22:23], v[46:47], v[134:135], v[22:23] neg_lo:[1,0,0] neg_hi:[1,0,0]
	v_pk_fma_f32 v[30:31], v[48:49], v[136:137], v[30:31] neg_lo:[1,0,0] neg_hi:[1,0,0]
	ds_read_b128 v[46:49], v33 offset:31888
	s_waitcnt lgkmcnt(14)
	v_pk_fma_f32 v[22:23], v[50:51], v[138:139], v[22:23] neg_lo:[1,0,0] neg_hi:[1,0,0]
	v_pk_fma_f32 v[30:31], v[52:53], v[140:141], v[30:31] neg_lo:[1,0,0] neg_hi:[1,0,0]
	ds_read_b128 v[50:53], v33 offset:31904
	s_waitcnt lgkmcnt(14)
	v_pk_fma_f32 v[22:23], v[54:55], v[142:143], v[22:23] neg_lo:[1,0,0] neg_hi:[1,0,0]
	v_pk_fma_f32 v[30:31], v[56:57], v[162:163], v[30:31] neg_lo:[1,0,0] neg_hi:[1,0,0]
	ds_read_b128 v[54:57], v33 offset:31920
	s_waitcnt lgkmcnt(14)
	v_pk_fma_f32 v[22:23], v[58:59], v[164:165], v[22:23] neg_lo:[1,0,0] neg_hi:[1,0,0]
	v_pk_fma_f32 v[30:31], v[60:61], v[166:167], v[30:31] neg_lo:[1,0,0] neg_hi:[1,0,0]
	ds_read_b128 v[58:61], v33 offset:31936
	s_waitcnt lgkmcnt(14)
	v_pk_fma_f32 v[22:23], v[62:63], v[168:169], v[22:23] neg_lo:[1,0,0] neg_hi:[1,0,0]
	v_pk_fma_f32 v[30:31], v[64:65], v[170:171], v[30:31] neg_lo:[1,0,0] neg_hi:[1,0,0]
	ds_read_b128 v[62:65], v33 offset:31952
	v_cmp_eq_u32_e32 vcc, 56, v152
	v_add_f32_e32 v82, v22, v23
	v_add_f32_e32 v83, v30, v31
	v_add_f32_e32 v171, v82, v83
	v_cvt_pk_bf16_f32 v25, v171, v171
	ds_write_b16 v84, v25 offset:7920
	v_cndmask_b32_e64 v22, 0, 1.0, vcc
	v_mov_b32_e32 v23, 0
	ds_read_b128 v[66:69], v33 offset:32224
	s_waitcnt lgkmcnt(15)
	v_pk_fma_f32 v[22:23], v[0:1], v[98:99], v[22:23] neg_lo:[1,0,0] neg_hi:[1,0,0]
	v_pk_fma_f32 v[30:31], v[2:3], v[100:101], 0 neg_lo:[1,0,0] neg_hi:[1,0,0]
	ds_read_b128 v[0:3], v33 offset:32000
	s_waitcnt lgkmcnt(15)
	v_pk_fma_f32 v[22:23], v[4:5], v[102:103], v[22:23] neg_lo:[1,0,0] neg_hi:[1,0,0]
	v_pk_fma_f32 v[30:31], v[6:7], v[104:105], v[30:31] neg_lo:[1,0,0] neg_hi:[1,0,0]
	ds_read_b128 v[4:7], v33 offset:32016
	s_waitcnt lgkmcnt(15)
	v_pk_fma_f32 v[22:23], v[8:9], v[106:107], v[22:23] neg_lo:[1,0,0] neg_hi:[1,0,0]
	v_pk_fma_f32 v[30:31], v[10:11], v[108:109], v[30:31] neg_lo:[1,0,0] neg_hi:[1,0,0]
	ds_read_b128 v[8:11], v33 offset:32032
	s_waitcnt lgkmcnt(15)
	v_pk_fma_f32 v[22:23], v[12:13], v[110:111], v[22:23] neg_lo:[1,0,0] neg_hi:[1,0,0]
	v_pk_fma_f32 v[30:31], v[14:15], v[112:113], v[30:31] neg_lo:[1,0,0] neg_hi:[1,0,0]
	ds_read_b128 v[12:15], v33 offset:32048
	s_waitcnt lgkmcnt(15)
	v_pk_fma_f32 v[22:23], v[16:17], v[114:115], v[22:23] neg_lo:[1,0,0] neg_hi:[1,0,0]
	v_pk_fma_f32 v[30:31], v[18:19], v[116:117], v[30:31] neg_lo:[1,0,0] neg_hi:[1,0,0]
	ds_read_b128 v[16:19], v33 offset:32064
	s_waitcnt lgkmcnt(15)
	v_pk_fma_f32 v[22:23], v[26:27], v[118:119], v[22:23] neg_lo:[1,0,0] neg_hi:[1,0,0]
	v_pk_fma_f32 v[30:31], v[28:29], v[120:121], v[30:31] neg_lo:[1,0,0] neg_hi:[1,0,0]
	ds_read_b128 v[26:29], v33 offset:32080
	s_waitcnt lgkmcnt(15)
	v_pk_fma_f32 v[22:23], v[34:35], v[122:123], v[22:23] neg_lo:[1,0,0] neg_hi:[1,0,0]
	v_pk_fma_f32 v[30:31], v[36:37], v[124:125], v[30:31] neg_lo:[1,0,0] neg_hi:[1,0,0]
	ds_read_b128 v[34:37], v33 offset:32096
	s_waitcnt lgkmcnt(15)
	v_pk_fma_f32 v[22:23], v[38:39], v[126:127], v[22:23] neg_lo:[1,0,0] neg_hi:[1,0,0]
	v_pk_fma_f32 v[30:31], v[40:41], v[128:129], v[30:31] neg_lo:[1,0,0] neg_hi:[1,0,0]
	ds_read_b128 v[38:41], v33 offset:32112
	s_waitcnt lgkmcnt(15)
	v_pk_fma_f32 v[22:23], v[42:43], v[130:131], v[22:23] neg_lo:[1,0,0] neg_hi:[1,0,0]
	v_pk_fma_f32 v[30:31], v[44:45], v[132:133], v[30:31] neg_lo:[1,0,0] neg_hi:[1,0,0]
	ds_read_b128 v[42:45], v33 offset:32128
	s_waitcnt lgkmcnt(15)
	v_pk_fma_f32 v[22:23], v[46:47], v[134:135], v[22:23] neg_lo:[1,0,0] neg_hi:[1,0,0]
	v_pk_fma_f32 v[30:31], v[48:49], v[136:137], v[30:31] neg_lo:[1,0,0] neg_hi:[1,0,0]
	ds_read_b128 v[46:49], v33 offset:32144
	s_waitcnt lgkmcnt(15)
	v_pk_fma_f32 v[22:23], v[50:51], v[138:139], v[22:23] neg_lo:[1,0,0] neg_hi:[1,0,0]
	v_pk_fma_f32 v[30:31], v[52:53], v[140:141], v[30:31] neg_lo:[1,0,0] neg_hi:[1,0,0]
	ds_read_b128 v[50:53], v33 offset:32160
	s_waitcnt lgkmcnt(15)
	v_pk_fma_f32 v[22:23], v[54:55], v[142:143], v[22:23] neg_lo:[1,0,0] neg_hi:[1,0,0]
	v_pk_fma_f32 v[30:31], v[56:57], v[162:163], v[30:31] neg_lo:[1,0,0] neg_hi:[1,0,0]
	ds_read_b128 v[54:57], v33 offset:32176
	s_waitcnt lgkmcnt(15)
	v_pk_fma_f32 v[22:23], v[58:59], v[164:165], v[22:23] neg_lo:[1,0,0] neg_hi:[1,0,0]
	v_pk_fma_f32 v[30:31], v[60:61], v[166:167], v[30:31] neg_lo:[1,0,0] neg_hi:[1,0,0]
	ds_read_b128 v[58:61], v33 offset:32192
	s_waitcnt lgkmcnt(15)
	v_pk_fma_f32 v[22:23], v[62:63], v[168:169], v[22:23] neg_lo:[1,0,0] neg_hi:[1,0,0]
	v_pk_fma_f32 v[30:31], v[64:65], v[170:171], v[30:31] neg_lo:[1,0,0] neg_hi:[1,0,0]
	ds_read_b128 v[62:65], v33 offset:32208
	v_cmp_eq_u32_e32 vcc, 57, v152
	v_add_f32_e32 v82, v22, v23
	v_add_f32_e32 v83, v30, v31
	v_add_f32_e32 v172, v82, v83
	v_cvt_pk_bf16_f32 v25, v172, v172
	ds_write_b16 v84, v25 offset:8064
	v_cndmask_b32_e64 v22, 0, 1.0, vcc
	v_mov_b32_e32 v23, 0
	s_waitcnt lgkmcnt(14)
	v_pk_fma_f32 v[22:23], v[0:1], v[98:99], v[22:23] neg_lo:[1,0,0] neg_hi:[1,0,0]
	v_pk_fma_f32 v[30:31], v[2:3], v[100:101], 0 neg_lo:[1,0,0] neg_hi:[1,0,0]
	ds_read_b128 v[0:3], v33 offset:32256
	s_waitcnt lgkmcnt(14)
	v_pk_fma_f32 v[22:23], v[4:5], v[102:103], v[22:23] neg_lo:[1,0,0] neg_hi:[1,0,0]
	v_pk_fma_f32 v[30:31], v[6:7], v[104:105], v[30:31] neg_lo:[1,0,0] neg_hi:[1,0,0]
	ds_read_b128 v[4:7], v33 offset:32272
	s_waitcnt lgkmcnt(14)
	v_pk_fma_f32 v[22:23], v[8:9], v[106:107], v[22:23] neg_lo:[1,0,0] neg_hi:[1,0,0]
	v_pk_fma_f32 v[30:31], v[10:11], v[108:109], v[30:31] neg_lo:[1,0,0] neg_hi:[1,0,0]
	ds_read_b128 v[8:11], v33 offset:32288
	s_waitcnt lgkmcnt(14)
	v_pk_fma_f32 v[22:23], v[12:13], v[110:111], v[22:23] neg_lo:[1,0,0] neg_hi:[1,0,0]
	v_pk_fma_f32 v[30:31], v[14:15], v[112:113], v[30:31] neg_lo:[1,0,0] neg_hi:[1,0,0]
	ds_read_b128 v[12:15], v33 offset:32304
	s_waitcnt lgkmcnt(14)
	v_pk_fma_f32 v[22:23], v[16:17], v[114:115], v[22:23] neg_lo:[1,0,0] neg_hi:[1,0,0]
	v_pk_fma_f32 v[30:31], v[18:19], v[116:117], v[30:31] neg_lo:[1,0,0] neg_hi:[1,0,0]
	ds_read_b128 v[16:19], v33 offset:32320
	s_waitcnt lgkmcnt(14)
	v_pk_fma_f32 v[22:23], v[26:27], v[118:119], v[22:23] neg_lo:[1,0,0] neg_hi:[1,0,0]
	v_pk_fma_f32 v[30:31], v[28:29], v[120:121], v[30:31] neg_lo:[1,0,0] neg_hi:[1,0,0]
	ds_read_b128 v[26:29], v33 offset:32336
	s_waitcnt lgkmcnt(14)
	v_pk_fma_f32 v[22:23], v[34:35], v[122:123], v[22:23] neg_lo:[1,0,0] neg_hi:[1,0,0]
	v_pk_fma_f32 v[30:31], v[36:37], v[124:125], v[30:31] neg_lo:[1,0,0] neg_hi:[1,0,0]
	ds_read_b128 v[34:37], v33 offset:32352
	s_waitcnt lgkmcnt(14)
	v_pk_fma_f32 v[22:23], v[38:39], v[126:127], v[22:23] neg_lo:[1,0,0] neg_hi:[1,0,0]
	v_pk_fma_f32 v[30:31], v[40:41], v[128:129], v[30:31] neg_lo:[1,0,0] neg_hi:[1,0,0]
	ds_read_b128 v[38:41], v33 offset:32368
	s_waitcnt lgkmcnt(14)
	v_pk_fma_f32 v[22:23], v[42:43], v[130:131], v[22:23] neg_lo:[1,0,0] neg_hi:[1,0,0]
	v_pk_fma_f32 v[30:31], v[44:45], v[132:133], v[30:31] neg_lo:[1,0,0] neg_hi:[1,0,0]
	ds_read_b128 v[42:45], v33 offset:32384
	s_waitcnt lgkmcnt(14)
	v_pk_fma_f32 v[22:23], v[46:47], v[134:135], v[22:23] neg_lo:[1,0,0] neg_hi:[1,0,0]
	v_pk_fma_f32 v[30:31], v[48:49], v[136:137], v[30:31] neg_lo:[1,0,0] neg_hi:[1,0,0]
	ds_read_b128 v[46:49], v33 offset:32400
	s_waitcnt lgkmcnt(14)
	v_pk_fma_f32 v[22:23], v[50:51], v[138:139], v[22:23] neg_lo:[1,0,0] neg_hi:[1,0,0]
	v_pk_fma_f32 v[30:31], v[52:53], v[140:141], v[30:31] neg_lo:[1,0,0] neg_hi:[1,0,0]
	ds_read_b128 v[50:53], v33 offset:32416
	s_waitcnt lgkmcnt(14)
	v_pk_fma_f32 v[22:23], v[54:55], v[142:143], v[22:23] neg_lo:[1,0,0] neg_hi:[1,0,0]
	v_pk_fma_f32 v[30:31], v[56:57], v[162:163], v[30:31] neg_lo:[1,0,0] neg_hi:[1,0,0]
	ds_read_b128 v[54:57], v33 offset:32432
	s_waitcnt lgkmcnt(14)
	v_pk_fma_f32 v[22:23], v[58:59], v[164:165], v[22:23] neg_lo:[1,0,0] neg_hi:[1,0,0]
	v_pk_fma_f32 v[30:31], v[60:61], v[166:167], v[30:31] neg_lo:[1,0,0] neg_hi:[1,0,0]
	ds_read_b128 v[58:61], v33 offset:32448
	s_waitcnt lgkmcnt(14)
	v_pk_fma_f32 v[22:23], v[62:63], v[168:169], v[22:23] neg_lo:[1,0,0] neg_hi:[1,0,0]
	v_pk_fma_f32 v[30:31], v[64:65], v[170:171], v[30:31] neg_lo:[1,0,0] neg_hi:[1,0,0]
	ds_read_b128 v[62:65], v33 offset:32464
	s_waitcnt lgkmcnt(15)
	v_pk_fma_f32 v[22:23], v[66:67], v[172:173], v[22:23] neg_lo:[1,0,0] neg_hi:[1,0,0]
	v_pk_fma_f32 v[30:31], v[68:69], v[174:175], v[30:31] neg_lo:[1,0,0] neg_hi:[1,0,0]
	ds_read_b128 v[66:69], v33 offset:32480
	v_cmp_eq_u32_e32 vcc, 58, v152
	v_add_f32_e32 v82, v22, v23
	v_add_f32_e32 v83, v30, v31
	v_add_f32_e32 v173, v82, v83
	v_cvt_pk_bf16_f32 v25, v173, v173
	ds_write_b16 v84, v25 offset:8208
	v_cndmask_b32_e64 v22, 0, 1.0, vcc
	v_mov_b32_e32 v23, 0
	s_waitcnt lgkmcnt(15)
	v_pk_fma_f32 v[22:23], v[0:1], v[98:99], v[22:23] neg_lo:[1,0,0] neg_hi:[1,0,0]
	v_pk_fma_f32 v[30:31], v[2:3], v[100:101], 0 neg_lo:[1,0,0] neg_hi:[1,0,0]
	ds_read_b128 v[0:3], v33 offset:32512
	s_waitcnt lgkmcnt(15)
	v_pk_fma_f32 v[22:23], v[4:5], v[102:103], v[22:23] neg_lo:[1,0,0] neg_hi:[1,0,0]
	v_pk_fma_f32 v[30:31], v[6:7], v[104:105], v[30:31] neg_lo:[1,0,0] neg_hi:[1,0,0]
	ds_read_b128 v[4:7], v33 offset:32528
	s_waitcnt lgkmcnt(15)
	v_pk_fma_f32 v[22:23], v[8:9], v[106:107], v[22:23] neg_lo:[1,0,0] neg_hi:[1,0,0]
	v_pk_fma_f32 v[30:31], v[10:11], v[108:109], v[30:31] neg_lo:[1,0,0] neg_hi:[1,0,0]
	ds_read_b128 v[8:11], v33 offset:32544
	s_waitcnt lgkmcnt(15)
	v_pk_fma_f32 v[22:23], v[12:13], v[110:111], v[22:23] neg_lo:[1,0,0] neg_hi:[1,0,0]
	v_pk_fma_f32 v[30:31], v[14:15], v[112:113], v[30:31] neg_lo:[1,0,0] neg_hi:[1,0,0]
	ds_read_b128 v[12:15], v33 offset:32560
	s_waitcnt lgkmcnt(15)
	v_pk_fma_f32 v[22:23], v[16:17], v[114:115], v[22:23] neg_lo:[1,0,0] neg_hi:[1,0,0]
	v_pk_fma_f32 v[30:31], v[18:19], v[116:117], v[30:31] neg_lo:[1,0,0] neg_hi:[1,0,0]
	ds_read_b128 v[16:19], v33 offset:32576
	s_waitcnt lgkmcnt(15)
	v_pk_fma_f32 v[22:23], v[26:27], v[118:119], v[22:23] neg_lo:[1,0,0] neg_hi:[1,0,0]
	v_pk_fma_f32 v[30:31], v[28:29], v[120:121], v[30:31] neg_lo:[1,0,0] neg_hi:[1,0,0]
	ds_read_b128 v[26:29], v33 offset:32592
	s_waitcnt lgkmcnt(15)
	v_pk_fma_f32 v[22:23], v[34:35], v[122:123], v[22:23] neg_lo:[1,0,0] neg_hi:[1,0,0]
	v_pk_fma_f32 v[30:31], v[36:37], v[124:125], v[30:31] neg_lo:[1,0,0] neg_hi:[1,0,0]
	ds_read_b128 v[34:37], v33 offset:32608
	s_waitcnt lgkmcnt(15)
	v_pk_fma_f32 v[22:23], v[38:39], v[126:127], v[22:23] neg_lo:[1,0,0] neg_hi:[1,0,0]
	v_pk_fma_f32 v[30:31], v[40:41], v[128:129], v[30:31] neg_lo:[1,0,0] neg_hi:[1,0,0]
	ds_read_b128 v[38:41], v33 offset:32624
	s_waitcnt lgkmcnt(15)
	v_pk_fma_f32 v[22:23], v[42:43], v[130:131], v[22:23] neg_lo:[1,0,0] neg_hi:[1,0,0]
	v_pk_fma_f32 v[30:31], v[44:45], v[132:133], v[30:31] neg_lo:[1,0,0] neg_hi:[1,0,0]
	ds_read_b128 v[42:45], v33 offset:32640
	s_waitcnt lgkmcnt(15)
	v_pk_fma_f32 v[22:23], v[46:47], v[134:135], v[22:23] neg_lo:[1,0,0] neg_hi:[1,0,0]
	v_pk_fma_f32 v[30:31], v[48:49], v[136:137], v[30:31] neg_lo:[1,0,0] neg_hi:[1,0,0]
	ds_read_b128 v[46:49], v33 offset:32656
	s_waitcnt lgkmcnt(15)
	v_pk_fma_f32 v[22:23], v[50:51], v[138:139], v[22:23] neg_lo:[1,0,0] neg_hi:[1,0,0]
	v_pk_fma_f32 v[30:31], v[52:53], v[140:141], v[30:31] neg_lo:[1,0,0] neg_hi:[1,0,0]
	ds_read_b128 v[50:53], v33 offset:32672
	s_waitcnt lgkmcnt(15)
	v_pk_fma_f32 v[22:23], v[54:55], v[142:143], v[22:23] neg_lo:[1,0,0] neg_hi:[1,0,0]
	v_pk_fma_f32 v[30:31], v[56:57], v[162:163], v[30:31] neg_lo:[1,0,0] neg_hi:[1,0,0]
	ds_read_b128 v[54:57], v33 offset:32688
	s_waitcnt lgkmcnt(15)
	v_pk_fma_f32 v[22:23], v[58:59], v[164:165], v[22:23] neg_lo:[1,0,0] neg_hi:[1,0,0]
	v_pk_fma_f32 v[30:31], v[60:61], v[166:167], v[30:31] neg_lo:[1,0,0] neg_hi:[1,0,0]
	ds_read_b128 v[58:61], v33 offset:32704
	s_waitcnt lgkmcnt(15)
	v_pk_fma_f32 v[22:23], v[62:63], v[168:169], v[22:23] neg_lo:[1,0,0] neg_hi:[1,0,0]
	v_pk_fma_f32 v[30:31], v[64:65], v[170:171], v[30:31] neg_lo:[1,0,0] neg_hi:[1,0,0]
	ds_read_b128 v[62:65], v33 offset:32720
	s_waitcnt lgkmcnt(15)
	v_pk_fma_f32 v[22:23], v[66:67], v[172:173], v[22:23] neg_lo:[1,0,0] neg_hi:[1,0,0]
	v_pk_fma_f32 v[30:31], v[68:69], v[174:175], v[30:31] neg_lo:[1,0,0] neg_hi:[1,0,0]
	ds_read_b128 v[66:69], v33 offset:32736
	v_cmp_eq_u32_e32 vcc, 59, v152
	v_add_f32_e32 v82, v22, v23
	v_add_f32_e32 v83, v30, v31
	v_add_f32_e32 v174, v82, v83
	v_cvt_pk_bf16_f32 v25, v174, v174
	ds_write_b16 v84, v25 offset:8352
	v_cndmask_b32_e64 v22, 0, 1.0, vcc
	v_mov_b32_e32 v23, 0
	s_waitcnt lgkmcnt(15)
	v_pk_fma_f32 v[22:23], v[0:1], v[98:99], v[22:23] neg_lo:[1,0,0] neg_hi:[1,0,0]
	v_pk_fma_f32 v[30:31], v[2:3], v[100:101], 0 neg_lo:[1,0,0] neg_hi:[1,0,0]
	ds_read_b128 v[0:3], v33 offset:32768
	s_waitcnt lgkmcnt(15)
	v_pk_fma_f32 v[22:23], v[4:5], v[102:103], v[22:23] neg_lo:[1,0,0] neg_hi:[1,0,0]
	v_pk_fma_f32 v[30:31], v[6:7], v[104:105], v[30:31] neg_lo:[1,0,0] neg_hi:[1,0,0]
	ds_read_b128 v[4:7], v33 offset:32784
	s_waitcnt lgkmcnt(15)
	v_pk_fma_f32 v[22:23], v[8:9], v[106:107], v[22:23] neg_lo:[1,0,0] neg_hi:[1,0,0]
	v_pk_fma_f32 v[30:31], v[10:11], v[108:109], v[30:31] neg_lo:[1,0,0] neg_hi:[1,0,0]
	ds_read_b128 v[8:11], v33 offset:32800
	s_waitcnt lgkmcnt(15)
	v_pk_fma_f32 v[22:23], v[12:13], v[110:111], v[22:23] neg_lo:[1,0,0] neg_hi:[1,0,0]
	v_pk_fma_f32 v[30:31], v[14:15], v[112:113], v[30:31] neg_lo:[1,0,0] neg_hi:[1,0,0]
	ds_read_b128 v[12:15], v33 offset:32816
	s_waitcnt lgkmcnt(15)
	v_pk_fma_f32 v[22:23], v[16:17], v[114:115], v[22:23] neg_lo:[1,0,0] neg_hi:[1,0,0]
	v_pk_fma_f32 v[30:31], v[18:19], v[116:117], v[30:31] neg_lo:[1,0,0] neg_hi:[1,0,0]
	ds_read_b128 v[16:19], v33 offset:32832
	s_waitcnt lgkmcnt(15)
	v_pk_fma_f32 v[22:23], v[26:27], v[118:119], v[22:23] neg_lo:[1,0,0] neg_hi:[1,0,0]
	v_pk_fma_f32 v[30:31], v[28:29], v[120:121], v[30:31] neg_lo:[1,0,0] neg_hi:[1,0,0]
	ds_read_b128 v[26:29], v33 offset:32848
	s_waitcnt lgkmcnt(15)
	v_pk_fma_f32 v[22:23], v[34:35], v[122:123], v[22:23] neg_lo:[1,0,0] neg_hi:[1,0,0]
	v_pk_fma_f32 v[30:31], v[36:37], v[124:125], v[30:31] neg_lo:[1,0,0] neg_hi:[1,0,0]
	ds_read_b128 v[34:37], v33 offset:32864
	s_waitcnt lgkmcnt(15)
	v_pk_fma_f32 v[22:23], v[38:39], v[126:127], v[22:23] neg_lo:[1,0,0] neg_hi:[1,0,0]
	v_pk_fma_f32 v[30:31], v[40:41], v[128:129], v[30:31] neg_lo:[1,0,0] neg_hi:[1,0,0]
	ds_read_b128 v[38:41], v33 offset:32880
	s_waitcnt lgkmcnt(15)
	v_pk_fma_f32 v[22:23], v[42:43], v[130:131], v[22:23] neg_lo:[1,0,0] neg_hi:[1,0,0]
	v_pk_fma_f32 v[30:31], v[44:45], v[132:133], v[30:31] neg_lo:[1,0,0] neg_hi:[1,0,0]
	ds_read_b128 v[42:45], v33 offset:32896
	s_waitcnt lgkmcnt(15)
	v_pk_fma_f32 v[22:23], v[46:47], v[134:135], v[22:23] neg_lo:[1,0,0] neg_hi:[1,0,0]
	v_pk_fma_f32 v[30:31], v[48:49], v[136:137], v[30:31] neg_lo:[1,0,0] neg_hi:[1,0,0]
	ds_read_b128 v[46:49], v33 offset:32912
	s_waitcnt lgkmcnt(15)
	v_pk_fma_f32 v[22:23], v[50:51], v[138:139], v[22:23] neg_lo:[1,0,0] neg_hi:[1,0,0]
	v_pk_fma_f32 v[30:31], v[52:53], v[140:141], v[30:31] neg_lo:[1,0,0] neg_hi:[1,0,0]
	ds_read_b128 v[50:53], v33 offset:32928
	s_waitcnt lgkmcnt(15)
	v_pk_fma_f32 v[22:23], v[54:55], v[142:143], v[22:23] neg_lo:[1,0,0] neg_hi:[1,0,0]
	v_pk_fma_f32 v[30:31], v[56:57], v[162:163], v[30:31] neg_lo:[1,0,0] neg_hi:[1,0,0]
	ds_read_b128 v[54:57], v33 offset:32944
	s_waitcnt lgkmcnt(15)
	v_pk_fma_f32 v[22:23], v[58:59], v[164:165], v[22:23] neg_lo:[1,0,0] neg_hi:[1,0,0]
	v_pk_fma_f32 v[30:31], v[60:61], v[166:167], v[30:31] neg_lo:[1,0,0] neg_hi:[1,0,0]
	ds_read_b128 v[58:61], v33 offset:32960
	s_waitcnt lgkmcnt(15)
	v_pk_fma_f32 v[22:23], v[62:63], v[168:169], v[22:23] neg_lo:[1,0,0] neg_hi:[1,0,0]
	v_pk_fma_f32 v[30:31], v[64:65], v[170:171], v[30:31] neg_lo:[1,0,0] neg_hi:[1,0,0]
	ds_read_b128 v[62:65], v33 offset:32976
	s_waitcnt lgkmcnt(15)
	v_pk_fma_f32 v[22:23], v[66:67], v[172:173], v[22:23] neg_lo:[1,0,0] neg_hi:[1,0,0]
	v_pk_fma_f32 v[30:31], v[68:69], v[174:175], v[30:31] neg_lo:[1,0,0] neg_hi:[1,0,0]
	ds_read_b128 v[66:69], v33 offset:32992
	v_cmp_eq_u32_e32 vcc, 60, v152
	v_add_f32_e32 v82, v22, v23
	v_add_f32_e32 v83, v30, v31
	v_add_f32_e32 v175, v82, v83
	v_cvt_pk_bf16_f32 v25, v175, v175
	ds_write_b16 v84, v25 offset:8496
	v_cndmask_b32_e64 v22, 0, 1.0, vcc
	v_mov_b32_e32 v23, 0
	ds_read_b128 v[70:73], v33 offset:33264
	s_waitcnt lgkmcnt(15)
	v_pk_fma_f32 v[22:23], v[0:1], v[98:99], v[22:23] neg_lo:[1,0,0] neg_hi:[1,0,0]
	v_pk_fma_f32 v[30:31], v[2:3], v[100:101], 0 neg_lo:[1,0,0] neg_hi:[1,0,0]
	ds_read_b128 v[0:3], v33 offset:33024
	s_waitcnt lgkmcnt(15)
	v_pk_fma_f32 v[22:23], v[4:5], v[102:103], v[22:23] neg_lo:[1,0,0] neg_hi:[1,0,0]
	v_pk_fma_f32 v[30:31], v[6:7], v[104:105], v[30:31] neg_lo:[1,0,0] neg_hi:[1,0,0]
	ds_read_b128 v[4:7], v33 offset:33040
	s_waitcnt lgkmcnt(15)
	v_pk_fma_f32 v[22:23], v[8:9], v[106:107], v[22:23] neg_lo:[1,0,0] neg_hi:[1,0,0]
	v_pk_fma_f32 v[30:31], v[10:11], v[108:109], v[30:31] neg_lo:[1,0,0] neg_hi:[1,0,0]
	ds_read_b128 v[8:11], v33 offset:33056
	s_waitcnt lgkmcnt(15)
	v_pk_fma_f32 v[22:23], v[12:13], v[110:111], v[22:23] neg_lo:[1,0,0] neg_hi:[1,0,0]
	v_pk_fma_f32 v[30:31], v[14:15], v[112:113], v[30:31] neg_lo:[1,0,0] neg_hi:[1,0,0]
	ds_read_b128 v[12:15], v33 offset:33072
	s_waitcnt lgkmcnt(15)
	v_pk_fma_f32 v[22:23], v[16:17], v[114:115], v[22:23] neg_lo:[1,0,0] neg_hi:[1,0,0]
	v_pk_fma_f32 v[30:31], v[18:19], v[116:117], v[30:31] neg_lo:[1,0,0] neg_hi:[1,0,0]
	ds_read_b128 v[16:19], v33 offset:33088
	s_waitcnt lgkmcnt(15)
	v_pk_fma_f32 v[22:23], v[26:27], v[118:119], v[22:23] neg_lo:[1,0,0] neg_hi:[1,0,0]
	v_pk_fma_f32 v[30:31], v[28:29], v[120:121], v[30:31] neg_lo:[1,0,0] neg_hi:[1,0,0]
	ds_read_b128 v[26:29], v33 offset:33104
	s_waitcnt lgkmcnt(15)
	v_pk_fma_f32 v[22:23], v[34:35], v[122:123], v[22:23] neg_lo:[1,0,0] neg_hi:[1,0,0]
	v_pk_fma_f32 v[30:31], v[36:37], v[124:125], v[30:31] neg_lo:[1,0,0] neg_hi:[1,0,0]
	ds_read_b128 v[34:37], v33 offset:33120
	s_waitcnt lgkmcnt(15)
	v_pk_fma_f32 v[22:23], v[38:39], v[126:127], v[22:23] neg_lo:[1,0,0] neg_hi:[1,0,0]
	v_pk_fma_f32 v[30:31], v[40:41], v[128:129], v[30:31] neg_lo:[1,0,0] neg_hi:[1,0,0]
	ds_read_b128 v[38:41], v33 offset:33136
	s_waitcnt lgkmcnt(15)
	v_pk_fma_f32 v[22:23], v[42:43], v[130:131], v[22:23] neg_lo:[1,0,0] neg_hi:[1,0,0]
	v_pk_fma_f32 v[30:31], v[44:45], v[132:133], v[30:31] neg_lo:[1,0,0] neg_hi:[1,0,0]
	ds_read_b128 v[42:45], v33 offset:33152
	s_waitcnt lgkmcnt(15)
	v_pk_fma_f32 v[22:23], v[46:47], v[134:135], v[22:23] neg_lo:[1,0,0] neg_hi:[1,0,0]
	v_pk_fma_f32 v[30:31], v[48:49], v[136:137], v[30:31] neg_lo:[1,0,0] neg_hi:[1,0,0]
	ds_read_b128 v[46:49], v33 offset:33168
	s_waitcnt lgkmcnt(15)
	v_pk_fma_f32 v[22:23], v[50:51], v[138:139], v[22:23] neg_lo:[1,0,0] neg_hi:[1,0,0]
	v_pk_fma_f32 v[30:31], v[52:53], v[140:141], v[30:31] neg_lo:[1,0,0] neg_hi:[1,0,0]
	ds_read_b128 v[50:53], v33 offset:33184
	s_waitcnt lgkmcnt(15)
	v_pk_fma_f32 v[22:23], v[54:55], v[142:143], v[22:23] neg_lo:[1,0,0] neg_hi:[1,0,0]
	v_pk_fma_f32 v[30:31], v[56:57], v[162:163], v[30:31] neg_lo:[1,0,0] neg_hi:[1,0,0]
	ds_read_b128 v[54:57], v33 offset:33200
	s_waitcnt lgkmcnt(15)
	v_pk_fma_f32 v[22:23], v[58:59], v[164:165], v[22:23] neg_lo:[1,0,0] neg_hi:[1,0,0]
	v_pk_fma_f32 v[30:31], v[60:61], v[166:167], v[30:31] neg_lo:[1,0,0] neg_hi:[1,0,0]
	ds_read_b128 v[58:61], v33 offset:33216
	s_waitcnt lgkmcnt(15)
	v_pk_fma_f32 v[22:23], v[62:63], v[168:169], v[22:23] neg_lo:[1,0,0] neg_hi:[1,0,0]
	v_pk_fma_f32 v[30:31], v[64:65], v[170:171], v[30:31] neg_lo:[1,0,0] neg_hi:[1,0,0]
	ds_read_b128 v[62:65], v33 offset:33232
	s_waitcnt lgkmcnt(15)
	v_pk_fma_f32 v[22:23], v[66:67], v[172:173], v[22:23] neg_lo:[1,0,0] neg_hi:[1,0,0]
	v_pk_fma_f32 v[30:31], v[68:69], v[174:175], v[30:31] neg_lo:[1,0,0] neg_hi:[1,0,0]
	ds_read_b128 v[66:69], v33 offset:33248
	v_cmp_eq_u32_e32 vcc, 61, v152
	v_add_f32_e32 v82, v22, v23
	v_add_f32_e32 v83, v30, v31
	v_add_f32_e32 v176, v82, v83
	v_cvt_pk_bf16_f32 v25, v176, v176
	ds_write_b16 v84, v25 offset:8640
	v_cndmask_b32_e64 v22, 0, 1.0, vcc
	v_mov_b32_e32 v23, 0
	s_waitcnt lgkmcnt(15)
	v_pk_fma_f32 v[22:23], v[0:1], v[98:99], v[22:23] neg_lo:[1,0,0] neg_hi:[1,0,0]
	v_pk_fma_f32 v[30:31], v[2:3], v[100:101], 0 neg_lo:[1,0,0] neg_hi:[1,0,0]
	ds_read_b128 v[0:3], v33 offset:33280
	s_waitcnt lgkmcnt(15)
	v_pk_fma_f32 v[22:23], v[4:5], v[102:103], v[22:23] neg_lo:[1,0,0] neg_hi:[1,0,0]
	v_pk_fma_f32 v[30:31], v[6:7], v[104:105], v[30:31] neg_lo:[1,0,0] neg_hi:[1,0,0]
	ds_read_b128 v[4:7], v33 offset:33296
	s_waitcnt lgkmcnt(15)
	v_pk_fma_f32 v[22:23], v[8:9], v[106:107], v[22:23] neg_lo:[1,0,0] neg_hi:[1,0,0]
	v_pk_fma_f32 v[30:31], v[10:11], v[108:109], v[30:31] neg_lo:[1,0,0] neg_hi:[1,0,0]
	ds_read_b128 v[8:11], v33 offset:33312
	s_waitcnt lgkmcnt(15)
	v_pk_fma_f32 v[22:23], v[12:13], v[110:111], v[22:23] neg_lo:[1,0,0] neg_hi:[1,0,0]
	v_pk_fma_f32 v[30:31], v[14:15], v[112:113], v[30:31] neg_lo:[1,0,0] neg_hi:[1,0,0]
	ds_read_b128 v[12:15], v33 offset:33328
	s_waitcnt lgkmcnt(15)
	v_pk_fma_f32 v[22:23], v[16:17], v[114:115], v[22:23] neg_lo:[1,0,0] neg_hi:[1,0,0]
	v_pk_fma_f32 v[30:31], v[18:19], v[116:117], v[30:31] neg_lo:[1,0,0] neg_hi:[1,0,0]
	ds_read_b128 v[16:19], v33 offset:33344
	s_waitcnt lgkmcnt(15)
	v_pk_fma_f32 v[22:23], v[26:27], v[118:119], v[22:23] neg_lo:[1,0,0] neg_hi:[1,0,0]
	v_pk_fma_f32 v[30:31], v[28:29], v[120:121], v[30:31] neg_lo:[1,0,0] neg_hi:[1,0,0]
	ds_read_b128 v[26:29], v33 offset:33360
	s_waitcnt lgkmcnt(15)
	v_pk_fma_f32 v[22:23], v[34:35], v[122:123], v[22:23] neg_lo:[1,0,0] neg_hi:[1,0,0]
	v_pk_fma_f32 v[30:31], v[36:37], v[124:125], v[30:31] neg_lo:[1,0,0] neg_hi:[1,0,0]
	ds_read_b128 v[34:37], v33 offset:33376
	s_waitcnt lgkmcnt(15)
	v_pk_fma_f32 v[22:23], v[38:39], v[126:127], v[22:23] neg_lo:[1,0,0] neg_hi:[1,0,0]
	v_pk_fma_f32 v[30:31], v[40:41], v[128:129], v[30:31] neg_lo:[1,0,0] neg_hi:[1,0,0]
	ds_read_b128 v[38:41], v33 offset:33392
	s_waitcnt lgkmcnt(15)
	v_pk_fma_f32 v[22:23], v[42:43], v[130:131], v[22:23] neg_lo:[1,0,0] neg_hi:[1,0,0]
	v_pk_fma_f32 v[30:31], v[44:45], v[132:133], v[30:31] neg_lo:[1,0,0] neg_hi:[1,0,0]
	ds_read_b128 v[42:45], v33 offset:33408
	s_waitcnt lgkmcnt(15)
	v_pk_fma_f32 v[22:23], v[46:47], v[134:135], v[22:23] neg_lo:[1,0,0] neg_hi:[1,0,0]
	v_pk_fma_f32 v[30:31], v[48:49], v[136:137], v[30:31] neg_lo:[1,0,0] neg_hi:[1,0,0]
	ds_read_b128 v[46:49], v33 offset:33424
	s_waitcnt lgkmcnt(15)
	v_pk_fma_f32 v[22:23], v[50:51], v[138:139], v[22:23] neg_lo:[1,0,0] neg_hi:[1,0,0]
	v_pk_fma_f32 v[30:31], v[52:53], v[140:141], v[30:31] neg_lo:[1,0,0] neg_hi:[1,0,0]
	ds_read_b128 v[50:53], v33 offset:33440
	s_waitcnt lgkmcnt(15)
	v_pk_fma_f32 v[22:23], v[54:55], v[142:143], v[22:23] neg_lo:[1,0,0] neg_hi:[1,0,0]
	v_pk_fma_f32 v[30:31], v[56:57], v[162:163], v[30:31] neg_lo:[1,0,0] neg_hi:[1,0,0]
	ds_read_b128 v[54:57], v33 offset:33456
	s_waitcnt lgkmcnt(15)
	v_pk_fma_f32 v[22:23], v[58:59], v[164:165], v[22:23] neg_lo:[1,0,0] neg_hi:[1,0,0]
	v_pk_fma_f32 v[30:31], v[60:61], v[166:167], v[30:31] neg_lo:[1,0,0] neg_hi:[1,0,0]
	ds_read_b128 v[58:61], v33 offset:33472
	s_waitcnt lgkmcnt(15)
	v_pk_fma_f32 v[22:23], v[62:63], v[168:169], v[22:23] neg_lo:[1,0,0] neg_hi:[1,0,0]
	v_pk_fma_f32 v[30:31], v[64:65], v[170:171], v[30:31] neg_lo:[1,0,0] neg_hi:[1,0,0]
	ds_read_b128 v[62:65], v33 offset:33488
	s_waitcnt lgkmcnt(15)
	v_pk_fma_f32 v[22:23], v[66:67], v[172:173], v[22:23] neg_lo:[1,0,0] neg_hi:[1,0,0]
	v_pk_fma_f32 v[30:31], v[68:69], v[174:175], v[30:31] neg_lo:[1,0,0] neg_hi:[1,0,0]
	ds_read_b128 v[66:69], v33 offset:33504
	s_waitcnt lgkmcnt(15)
	v_pk_fma_f32 v[22:23], v[70:71], v[176:177], v[22:23] neg_lo:[1,0,0] neg_hi:[1,0,0]
	v_pk_fma_f32 v[30:31], v[72:73], v[178:179], v[30:31] neg_lo:[1,0,0] neg_hi:[1,0,0]
	ds_read_b128 v[70:73], v33 offset:33520
	v_cmp_eq_u32_e32 vcc, 62, v152
	v_add_f32_e32 v82, v22, v23
	v_add_f32_e32 v83, v30, v31
	v_add_f32_e32 v177, v82, v83
	v_cvt_pk_bf16_f32 v25, v177, v177
	ds_write_b16 v84, v25 offset:8784
	v_cndmask_b32_e64 v22, 0, 1.0, vcc
	v_mov_b32_e32 v23, 0
	s_waitcnt lgkmcnt(15)
	v_pk_fma_f32 v[22:23], v[0:1], v[98:99], v[22:23] neg_lo:[1,0,0] neg_hi:[1,0,0]
	v_pk_fma_f32 v[30:31], v[2:3], v[100:101], 0 neg_lo:[1,0,0] neg_hi:[1,0,0]
	ds_read_b128 v[0:3], v33 offset:33536
	s_waitcnt lgkmcnt(15)
	v_pk_fma_f32 v[22:23], v[4:5], v[102:103], v[22:23] neg_lo:[1,0,0] neg_hi:[1,0,0]
	v_pk_fma_f32 v[30:31], v[6:7], v[104:105], v[30:31] neg_lo:[1,0,0] neg_hi:[1,0,0]
	ds_read_b128 v[4:7], v33 offset:33552
	s_waitcnt lgkmcnt(15)
	v_pk_fma_f32 v[22:23], v[8:9], v[106:107], v[22:23] neg_lo:[1,0,0] neg_hi:[1,0,0]
	v_pk_fma_f32 v[30:31], v[10:11], v[108:109], v[30:31] neg_lo:[1,0,0] neg_hi:[1,0,0]
	ds_read_b128 v[8:11], v33 offset:33568
	s_waitcnt lgkmcnt(15)
	v_pk_fma_f32 v[22:23], v[12:13], v[110:111], v[22:23] neg_lo:[1,0,0] neg_hi:[1,0,0]
	v_pk_fma_f32 v[30:31], v[14:15], v[112:113], v[30:31] neg_lo:[1,0,0] neg_hi:[1,0,0]
	ds_read_b128 v[12:15], v33 offset:33584
	s_waitcnt lgkmcnt(15)
	v_pk_fma_f32 v[22:23], v[16:17], v[114:115], v[22:23] neg_lo:[1,0,0] neg_hi:[1,0,0]
	v_pk_fma_f32 v[30:31], v[18:19], v[116:117], v[30:31] neg_lo:[1,0,0] neg_hi:[1,0,0]
	ds_read_b128 v[16:19], v33 offset:33600
	s_waitcnt lgkmcnt(15)
	v_pk_fma_f32 v[22:23], v[26:27], v[118:119], v[22:23] neg_lo:[1,0,0] neg_hi:[1,0,0]
	v_pk_fma_f32 v[30:31], v[28:29], v[120:121], v[30:31] neg_lo:[1,0,0] neg_hi:[1,0,0]
	ds_read_b128 v[26:29], v33 offset:33616
	s_waitcnt lgkmcnt(15)
	v_pk_fma_f32 v[22:23], v[34:35], v[122:123], v[22:23] neg_lo:[1,0,0] neg_hi:[1,0,0]
	v_pk_fma_f32 v[30:31], v[36:37], v[124:125], v[30:31] neg_lo:[1,0,0] neg_hi:[1,0,0]
	ds_read_b128 v[34:37], v33 offset:33632
	s_waitcnt lgkmcnt(15)
	v_pk_fma_f32 v[22:23], v[38:39], v[126:127], v[22:23] neg_lo:[1,0,0] neg_hi:[1,0,0]
	v_pk_fma_f32 v[30:31], v[40:41], v[128:129], v[30:31] neg_lo:[1,0,0] neg_hi:[1,0,0]
	ds_read_b128 v[38:41], v33 offset:33648
	s_waitcnt lgkmcnt(15)
	v_pk_fma_f32 v[22:23], v[42:43], v[130:131], v[22:23] neg_lo:[1,0,0] neg_hi:[1,0,0]
	v_pk_fma_f32 v[30:31], v[44:45], v[132:133], v[30:31] neg_lo:[1,0,0] neg_hi:[1,0,0]
	ds_read_b128 v[42:45], v33 offset:33664
	s_waitcnt lgkmcnt(15)
	v_pk_fma_f32 v[22:23], v[46:47], v[134:135], v[22:23] neg_lo:[1,0,0] neg_hi:[1,0,0]
	v_pk_fma_f32 v[30:31], v[48:49], v[136:137], v[30:31] neg_lo:[1,0,0] neg_hi:[1,0,0]
	ds_read_b128 v[46:49], v33 offset:33680
	s_waitcnt lgkmcnt(15)
	v_pk_fma_f32 v[22:23], v[50:51], v[138:139], v[22:23] neg_lo:[1,0,0] neg_hi:[1,0,0]
	v_pk_fma_f32 v[30:31], v[52:53], v[140:141], v[30:31] neg_lo:[1,0,0] neg_hi:[1,0,0]
	ds_read_b128 v[50:53], v33 offset:33696
	s_waitcnt lgkmcnt(15)
	v_pk_fma_f32 v[22:23], v[54:55], v[142:143], v[22:23] neg_lo:[1,0,0] neg_hi:[1,0,0]
	v_pk_fma_f32 v[30:31], v[56:57], v[162:163], v[30:31] neg_lo:[1,0,0] neg_hi:[1,0,0]
	ds_read_b128 v[54:57], v33 offset:33712
	s_waitcnt lgkmcnt(15)
	v_pk_fma_f32 v[22:23], v[58:59], v[164:165], v[22:23] neg_lo:[1,0,0] neg_hi:[1,0,0]
	v_pk_fma_f32 v[30:31], v[60:61], v[166:167], v[30:31] neg_lo:[1,0,0] neg_hi:[1,0,0]
	ds_read_b128 v[58:61], v33 offset:33728
	s_waitcnt lgkmcnt(15)
	v_pk_fma_f32 v[22:23], v[62:63], v[168:169], v[22:23] neg_lo:[1,0,0] neg_hi:[1,0,0]
	v_pk_fma_f32 v[30:31], v[64:65], v[170:171], v[30:31] neg_lo:[1,0,0] neg_hi:[1,0,0]
	ds_read_b128 v[62:65], v33 offset:33744
	s_waitcnt lgkmcnt(15)
	v_pk_fma_f32 v[22:23], v[66:67], v[172:173], v[22:23] neg_lo:[1,0,0] neg_hi:[1,0,0]
	v_pk_fma_f32 v[30:31], v[68:69], v[174:175], v[30:31] neg_lo:[1,0,0] neg_hi:[1,0,0]
	ds_read_b128 v[66:69], v33 offset:33760
	s_waitcnt lgkmcnt(15)
	v_pk_fma_f32 v[22:23], v[70:71], v[176:177], v[22:23] neg_lo:[1,0,0] neg_hi:[1,0,0]
	v_pk_fma_f32 v[30:31], v[72:73], v[178:179], v[30:31] neg_lo:[1,0,0] neg_hi:[1,0,0]
	ds_read_b128 v[70:73], v33 offset:33776
	v_cmp_eq_u32_e32 vcc, 63, v152
	v_add_f32_e32 v82, v22, v23
	v_add_f32_e32 v83, v30, v31
	v_add_f32_e32 v178, v82, v83
	v_cvt_pk_bf16_f32 v25, v178, v178
	ds_write_b16 v84, v25 offset:8928
	v_cndmask_b32_e64 v22, 0, 1.0, vcc
	v_mov_b32_e32 v23, 0
	s_waitcnt lgkmcnt(15)
	v_pk_fma_f32 v[22:23], v[0:1], v[98:99], v[22:23] neg_lo:[1,0,0] neg_hi:[1,0,0]
	v_pk_fma_f32 v[30:31], v[2:3], v[100:101], 0 neg_lo:[1,0,0] neg_hi:[1,0,0]
	s_waitcnt lgkmcnt(15)
	v_pk_fma_f32 v[22:23], v[4:5], v[102:103], v[22:23] neg_lo:[1,0,0] neg_hi:[1,0,0]
	v_pk_fma_f32 v[30:31], v[6:7], v[104:105], v[30:31] neg_lo:[1,0,0] neg_hi:[1,0,0]
	s_waitcnt lgkmcnt(14)
	v_pk_fma_f32 v[22:23], v[8:9], v[106:107], v[22:23] neg_lo:[1,0,0] neg_hi:[1,0,0]
	v_pk_fma_f32 v[30:31], v[10:11], v[108:109], v[30:31] neg_lo:[1,0,0] neg_hi:[1,0,0]
	s_waitcnt lgkmcnt(13)
	v_pk_fma_f32 v[22:23], v[12:13], v[110:111], v[22:23] neg_lo:[1,0,0] neg_hi:[1,0,0]
	v_pk_fma_f32 v[30:31], v[14:15], v[112:113], v[30:31] neg_lo:[1,0,0] neg_hi:[1,0,0]
	s_waitcnt lgkmcnt(12)
	v_pk_fma_f32 v[22:23], v[16:17], v[114:115], v[22:23] neg_lo:[1,0,0] neg_hi:[1,0,0]
	v_pk_fma_f32 v[30:31], v[18:19], v[116:117], v[30:31] neg_lo:[1,0,0] neg_hi:[1,0,0]
	s_waitcnt lgkmcnt(11)
	v_pk_fma_f32 v[22:23], v[26:27], v[118:119], v[22:23] neg_lo:[1,0,0] neg_hi:[1,0,0]
	v_pk_fma_f32 v[30:31], v[28:29], v[120:121], v[30:31] neg_lo:[1,0,0] neg_hi:[1,0,0]
	s_waitcnt lgkmcnt(10)
	v_pk_fma_f32 v[22:23], v[34:35], v[122:123], v[22:23] neg_lo:[1,0,0] neg_hi:[1,0,0]
	v_pk_fma_f32 v[30:31], v[36:37], v[124:125], v[30:31] neg_lo:[1,0,0] neg_hi:[1,0,0]
	s_waitcnt lgkmcnt(9)
	v_pk_fma_f32 v[22:23], v[38:39], v[126:127], v[22:23] neg_lo:[1,0,0] neg_hi:[1,0,0]
	v_pk_fma_f32 v[30:31], v[40:41], v[128:129], v[30:31] neg_lo:[1,0,0] neg_hi:[1,0,0]
	s_waitcnt lgkmcnt(8)
	v_pk_fma_f32 v[22:23], v[42:43], v[130:131], v[22:23] neg_lo:[1,0,0] neg_hi:[1,0,0]
	v_pk_fma_f32 v[30:31], v[44:45], v[132:133], v[30:31] neg_lo:[1,0,0] neg_hi:[1,0,0]
	s_waitcnt lgkmcnt(7)
	v_pk_fma_f32 v[22:23], v[46:47], v[134:135], v[22:23] neg_lo:[1,0,0] neg_hi:[1,0,0]
	v_pk_fma_f32 v[30:31], v[48:49], v[136:137], v[30:31] neg_lo:[1,0,0] neg_hi:[1,0,0]
	s_waitcnt lgkmcnt(6)
	v_pk_fma_f32 v[22:23], v[50:51], v[138:139], v[22:23] neg_lo:[1,0,0] neg_hi:[1,0,0]
	v_pk_fma_f32 v[30:31], v[52:53], v[140:141], v[30:31] neg_lo:[1,0,0] neg_hi:[1,0,0]
	s_waitcnt lgkmcnt(5)
	v_pk_fma_f32 v[22:23], v[54:55], v[142:143], v[22:23] neg_lo:[1,0,0] neg_hi:[1,0,0]
	v_pk_fma_f32 v[30:31], v[56:57], v[162:163], v[30:31] neg_lo:[1,0,0] neg_hi:[1,0,0]
	s_waitcnt lgkmcnt(4)
	v_pk_fma_f32 v[22:23], v[58:59], v[164:165], v[22:23] neg_lo:[1,0,0] neg_hi:[1,0,0]
	v_pk_fma_f32 v[30:31], v[60:61], v[166:167], v[30:31] neg_lo:[1,0,0] neg_hi:[1,0,0]
	s_waitcnt lgkmcnt(3)
	v_pk_fma_f32 v[22:23], v[62:63], v[168:169], v[22:23] neg_lo:[1,0,0] neg_hi:[1,0,0]
	v_pk_fma_f32 v[30:31], v[64:65], v[170:171], v[30:31] neg_lo:[1,0,0] neg_hi:[1,0,0]
	s_waitcnt lgkmcnt(2)
	v_pk_fma_f32 v[22:23], v[66:67], v[172:173], v[22:23] neg_lo:[1,0,0] neg_hi:[1,0,0]
	v_pk_fma_f32 v[30:31], v[68:69], v[174:175], v[30:31] neg_lo:[1,0,0] neg_hi:[1,0,0]
	s_waitcnt lgkmcnt(1)
	v_pk_fma_f32 v[22:23], v[70:71], v[176:177], v[22:23] neg_lo:[1,0,0] neg_hi:[1,0,0]
	v_pk_fma_f32 v[30:31], v[72:73], v[178:179], v[30:31] neg_lo:[1,0,0] neg_hi:[1,0,0]
	v_add_f32_e32 v82, v22, v23
	v_add_f32_e32 v83, v30, v31
	v_add_f32_e32 v179, v82, v83
	v_cvt_pk_bf16_f32 v25, v179, v179
	ds_write_b16 v84, v25 offset:9072
	s_branch .LBB0_227
